# speedup vs baseline: 1.0153x; 1.0153x over previous
;     ...
;   for (int kt = 0; kt < nk; ++kt) {
;     const int kn = (kt + 1 < nk) ? kt + 1 : kt;
;     GW_LOAD2(kn * 64, kn * bkstep)
;     __builtin_amdgcn_sched_barrier(0);
;     __builtin_amdgcn_s_setprio(1);
; #pragma unroll
;     for (int st = 0; st < 4; ++st) {
;       bf16x8 a0 = *(const bf16x8*)(Ab + st * 32);
;       bf16x8 a1 = *(const bf16x8*)(Ab + 32 * LSTR + st * 32);
;       bf16x8 b0 = *(const bf16x8*)(Bb + st * 32);
;       bf16x8 b1 = *(const bf16x8*)(Bb + 32 * LSTR + st * 32);
;       bf16x8 b2 = *(const bf16x8*)(Bb + 64 * LSTR + st * 32);
;       bf16x8 b3 = *(const bf16x8*)(Bb + 96 * LSTR + st * 32);
;       acc[0][0] = mfma32(a0, b0, acc[0][0]);
;       acc[0][1] = mfma32(a0, b1, acc[0][1]);
;       acc[0][2] = mfma32(a0, b2, acc[0][2]);
;       acc[0][3] = mfma32(a0, b3, acc[0][3]);
;       acc[1][0] = mfma32(a1, b0, acc[1][0]);
;       acc[1][1] = mfma32(a1, b1, acc[1][1]);
;       acc[1][2] = mfma32(a1, b2, acc[1][2]);
;       acc[1][3] = mfma32(a1, b3, acc[1][3]);
;     }
;     __builtin_amdgcn_s_setprio(0);
;     __builtin_amdgcn_sched_barrier(0);
;     __syncthreads();
;     GW_STORE()
;     __syncthreads();
.LBB0_238:
	s_setprio 1
	ds_read_b128 v[202:205], v131 offset:0
	ds_read_b128 v[214:217], v136 offset:18432
	ds_read_b128 v[218:221], v136 offset:23040
	ds_read_b128 v[224:227], v136 offset:27648
	ds_read_b128 v[228:231], v136 offset:32256
	ds_read_b128 v[210:213], v131 offset:4608
	s_waitcnt lgkmcnt(4)
	v_mfma_f32_32x32x16_bf16 v[114:129], v[202:205], v[214:217], v[114:129]
	ds_read_b128 v[206:209], v131 offset:32
	ds_read_b128 v[232:235], v136 offset:18464
	s_waitcnt lgkmcnt(5)
	v_mfma_f32_32x32x16_bf16 v[98:113], v[202:205], v[218:221], v[98:113]
	ds_read_b128 v[236:239], v136 offset:23072
	s_waitcnt lgkmcnt(5)
	v_mfma_f32_32x32x16_bf16 v[82:97], v[202:205], v[224:227], v[82:97]
	ds_read_b128 v[240:243], v136 offset:27680
	s_waitcnt lgkmcnt(5)
	v_mfma_f32_32x32x16_bf16 v[66:81], v[202:205], v[228:231], v[66:81]
	ds_read_b128 v[244:247], v136 offset:32288
	s_waitcnt lgkmcnt(5)
	v_mfma_f32_32x32x16_bf16 v[50:65], v[210:213], v[214:217], v[50:65]
	v_mfma_f32_32x32x16_bf16 v[34:49], v[210:213], v[218:221], v[34:49]
	v_mfma_f32_32x32x16_bf16 v[18:33], v[210:213], v[224:227], v[18:33]
	v_mfma_f32_32x32x16_bf16 v[2:17], v[210:213], v[228:231], v[2:17]
	ds_read_b128 v[210:213], v131 offset:4640
	s_waitcnt lgkmcnt(4)
	v_mfma_f32_32x32x16_bf16 v[114:129], v[206:209], v[232:235], v[114:129]
	ds_read_b128 v[202:205], v131 offset:64
	ds_read_b128 v[214:217], v136 offset:18496
	s_waitcnt lgkmcnt(5)
	v_mfma_f32_32x32x16_bf16 v[98:113], v[206:209], v[236:239], v[98:113]
	ds_read_b128 v[218:221], v136 offset:23104
	s_waitcnt lgkmcnt(5)
	v_mfma_f32_32x32x16_bf16 v[82:97], v[206:209], v[240:243], v[82:97]
	ds_read_b128 v[224:227], v136 offset:27712
	s_waitcnt lgkmcnt(5)
	v_mfma_f32_32x32x16_bf16 v[66:81], v[206:209], v[244:247], v[66:81]
	ds_read_b128 v[228:231], v136 offset:32320
	s_waitcnt lgkmcnt(5)
	v_mfma_f32_32x32x16_bf16 v[50:65], v[210:213], v[232:235], v[50:65]
	v_mfma_f32_32x32x16_bf16 v[34:49], v[210:213], v[236:239], v[34:49]
	v_mfma_f32_32x32x16_bf16 v[18:33], v[210:213], v[240:243], v[18:33]
	v_mfma_f32_32x32x16_bf16 v[2:17], v[210:213], v[244:247], v[2:17]
	ds_read_b128 v[210:213], v131 offset:4672
	s_waitcnt lgkmcnt(4)
	v_mfma_f32_32x32x16_bf16 v[114:129], v[202:205], v[214:217], v[114:129]
	ds_read_b128 v[206:209], v131 offset:96
	ds_read_b128 v[232:235], v136 offset:18528
	s_waitcnt lgkmcnt(5)
	v_mfma_f32_32x32x16_bf16 v[98:113], v[202:205], v[218:221], v[98:113]
	ds_read_b128 v[236:239], v136 offset:23136
	s_waitcnt lgkmcnt(5)
	v_mfma_f32_32x32x16_bf16 v[82:97], v[202:205], v[224:227], v[82:97]
	ds_read_b128 v[240:243], v136 offset:27744
	s_waitcnt lgkmcnt(5)
	v_mfma_f32_32x32x16_bf16 v[66:81], v[202:205], v[228:231], v[66:81]
	ds_read_b128 v[244:247], v136 offset:32352
	s_waitcnt lgkmcnt(5)
	v_mfma_f32_32x32x16_bf16 v[50:65], v[210:213], v[214:217], v[50:65]
	v_mfma_f32_32x32x16_bf16 v[34:49], v[210:213], v[218:221], v[34:49]
	v_mfma_f32_32x32x16_bf16 v[18:33], v[210:213], v[224:227], v[18:33]
	v_mfma_f32_32x32x16_bf16 v[2:17], v[210:213], v[228:231], v[2:17]
	ds_read_b128 v[210:213], v131 offset:4704
	s_waitcnt lgkmcnt(4)
	v_mfma_f32_32x32x16_bf16 v[114:129], v[206:209], v[232:235], v[114:129]
	s_waitcnt lgkmcnt(3)
	v_mfma_f32_32x32x16_bf16 v[98:113], v[206:209], v[236:239], v[98:113]
	s_waitcnt lgkmcnt(2)
	v_mfma_f32_32x32x16_bf16 v[82:97], v[206:209], v[240:243], v[82:97]
	s_waitcnt lgkmcnt(1)
	v_mfma_f32_32x32x16_bf16 v[66:81], v[206:209], v[244:247], v[66:81]
	s_waitcnt lgkmcnt(0)
	v_mfma_f32_32x32x16_bf16 v[50:65], v[210:213], v[232:235], v[50:65]
	v_mfma_f32_32x32x16_bf16 v[34:49], v[210:213], v[236:239], v[34:49]
	v_mfma_f32_32x32x16_bf16 v[18:33], v[210:213], v[240:243], v[18:33]
	v_mfma_f32_32x32x16_bf16 v[2:17], v[210:213], v[244:247], v[2:17]
	s_setprio 0
	s_add_u32 s10, s10, 0x80
	s_addc_u32 s11, s11, 0
	s_cmpk_lg_i32 s10, 0x700
	s_barrier
	s_waitcnt vmcnt(11)
	ds_write_b128 v130, v[150:153]
	v_lshl_add_u64 v[150:151], v[148:149], 0, s[10:11]
	v_add_co_u32_e32 v150, vcc, 0x12c31000, v150
	s_nop 1
	v_addc_co_u32_e32 v151, vcc, 0, v151, vcc
	global_load_dwordx4 v[150:153], v[150:151], off offset:384
	s_waitcnt vmcnt(11)
	ds_write_b128 v130, v[154:157] offset:4608
	v_lshl_add_u64 v[154:155], v[148:149], 0, s[10:11]
	v_add_co_u32_e32 v154, vcc, 0x12c41000, v154
	s_nop 1
	v_addc_co_u32_e32 v155, vcc, 0, v155, vcc
	global_load_dwordx4 v[154:157], v[154:155], off offset:384
	s_waitcnt vmcnt(11)
	ds_write_b128 v130, v[158:161] offset:9216
	v_lshl_add_u64 v[158:159], v[148:149], 0, s[10:11]
	v_add_co_u32_e32 v158, vcc, 0x12c51000, v158
	s_nop 1
	v_addc_co_u32_e32 v159, vcc, 0, v159, vcc
	global_load_dwordx4 v[158:161], v[158:159], off offset:384
	s_waitcnt vmcnt(11)
	ds_write_b128 v130, v[162:165] offset:13824
	v_lshl_add_u64 v[162:163], v[148:149], 0, s[10:11]
	v_add_co_u32_e32 v162, vcc, 0x12c61000, v162
	s_nop 1
	v_addc_co_u32_e32 v163, vcc, 0, v163, vcc
	global_load_dwordx4 v[162:165], v[162:163], off offset:384
	s_waitcnt vmcnt(11)
	ds_write_b128 v130, v[166:169] offset:18432
	v_lshl_add_u64 v[166:167], v[132:133], 0, s[10:11]
	global_load_dwordx4 v[166:169], v[166:167], off offset:128
	s_waitcnt vmcnt(11)
	ds_write_b128 v130, v[170:173] offset:23040
	v_lshl_add_u64 v[170:171], v[132:133], 0, s[10:11]
	v_add_co_u32_e32 v170, vcc, s37, v170
	s_nop 1
	v_addc_co_u32_e32 v171, vcc, 0, v171, vcc
	global_load_dwordx4 v[170:173], v[170:171], off offset:128
	s_waitcnt vmcnt(11)
	ds_write_b128 v130, v[174:177] offset:27648
	v_lshl_add_u64 v[174:175], v[132:133], 0, s[10:11]
	v_add_co_u32_e32 v174, vcc, s38, v174
	s_nop 1
	v_addc_co_u32_e32 v175, vcc, 0, v175, vcc
	global_load_dwordx4 v[174:177], v[174:175], off offset:128
	s_waitcnt vmcnt(11)
	ds_write_b128 v130, v[178:181] offset:32256
	v_lshl_add_u64 v[178:179], v[132:133], 0, s[10:11]
	v_add_co_u32_e32 v178, vcc, s39, v178
	s_nop 1
	v_addc_co_u32_e32 v179, vcc, 0, v179, vcc
	global_load_dwordx4 v[178:181], v[178:179], off offset:128
	s_waitcnt vmcnt(11)
	ds_write_b128 v130, v[186:189] offset:36864
	v_lshl_add_u64 v[186:187], v[132:133], 0, s[10:11]
	v_add_co_u32_e32 v186, vcc, s40, v186
	s_nop 1
	v_addc_co_u32_e32 v187, vcc, 0, v187, vcc
	global_load_dwordx4 v[186:189], v[186:187], off offset:128
	s_waitcnt vmcnt(11)
	ds_write_b128 v130, v[190:193] offset:41472
	v_lshl_add_u64 v[190:191], v[132:133], 0, s[10:11]
	v_add_co_u32_e32 v190, vcc, s41, v190
	s_nop 1
	v_addc_co_u32_e32 v191, vcc, 0, v191, vcc
	global_load_dwordx4 v[190:193], v[190:191], off offset:128
	s_waitcnt vmcnt(11)
	ds_write_b128 v130, v[194:197] offset:46080
	v_lshl_add_u64 v[194:195], v[132:133], 0, s[10:11]
	v_add_co_u32_e32 v194, vcc, s42, v194
	s_nop 1
	v_addc_co_u32_e32 v195, vcc, 0, v195, vcc
	global_load_dwordx4 v[194:197], v[194:195], off offset:128
	s_waitcnt vmcnt(11)
	ds_write_b128 v130, v[198:201] offset:50688
	v_lshl_add_u64 v[198:199], v[132:133], 0, s[10:11]
	v_add_co_u32_e32 v198, vcc, s43, v198
	s_nop 1
	v_addc_co_u32_e32 v199, vcc, 0, v199, vcc
	global_load_dwordx4 v[198:201], v[198:199], off offset:128
	s_waitcnt lgkmcnt(0)
	s_barrier
;     ...
; #pragma unroll
;     for (int st = 0; st < 4; ++st) {
;       bf16x8 a0 = *(const bf16x8*)(Ab + st * 32);
;       bf16x8 a1 = *(const bf16x8*)(Ab + 32 * LSTR + st * 32);
;       bf16x8 b0 = *(const bf16x8*)(Bb + st * 32);
;       bf16x8 b1 = *(const bf16x8*)(Bb + 32 * LSTR + st * 32);
;       bf16x8 b2 = *(const bf16x8*)(Bb + 64 * LSTR + st * 32);
;       bf16x8 b3 = *(const bf16x8*)(Bb + 96 * LSTR + st * 32);
;       acc[0][0] = mfma32(a0, b0, acc[0][0]);
;       acc[0][1] = mfma32(a0, b1, acc[0][1]);
;       acc[0][2] = mfma32(a0, b2, acc[0][2]);
;       acc[0][3] = mfma32(a0, b3, acc[0][3]);
;       acc[1][0] = mfma32(a1, b0, acc[1][0]);
;       acc[1][1] = mfma32(a1, b1, acc[1][1]);
;       acc[1][2] = mfma32(a1, b2, acc[1][2]);
;       acc[1][3] = mfma32(a1, b3, acc[1][3]);
;     }
;     __builtin_amdgcn_s_setprio(0);
;     __builtin_amdgcn_sched_barrier(0);
;     __syncthreads();
;     GW_STORE()
;     __syncthreads();
	s_cbranch_scc1 .LBB0_238
	s_setprio 1
	ds_read_b128 v[202:205], v131 offset:0
	ds_read_b128 v[214:217], v136 offset:18432
	ds_read_b128 v[218:221], v136 offset:23040
	ds_read_b128 v[224:227], v136 offset:27648
	ds_read_b128 v[228:231], v136 offset:32256
	ds_read_b128 v[210:213], v131 offset:4608
	s_waitcnt lgkmcnt(4)
	v_mfma_f32_32x32x16_bf16 v[114:129], v[202:205], v[214:217], v[114:129]
	ds_read_b128 v[206:209], v131 offset:32
	ds_read_b128 v[232:235], v136 offset:18464
	s_waitcnt lgkmcnt(5)
	v_mfma_f32_32x32x16_bf16 v[98:113], v[202:205], v[218:221], v[98:113]
	ds_read_b128 v[236:239], v136 offset:23072
	s_waitcnt lgkmcnt(5)
	v_mfma_f32_32x32x16_bf16 v[82:97], v[202:205], v[224:227], v[82:97]
	ds_read_b128 v[240:243], v136 offset:27680
	s_waitcnt lgkmcnt(5)
	v_mfma_f32_32x32x16_bf16 v[66:81], v[202:205], v[228:231], v[66:81]
	ds_read_b128 v[244:247], v136 offset:32288
	s_waitcnt lgkmcnt(5)
	v_mfma_f32_32x32x16_bf16 v[50:65], v[210:213], v[214:217], v[50:65]
	v_mfma_f32_32x32x16_bf16 v[34:49], v[210:213], v[218:221], v[34:49]
	v_mfma_f32_32x32x16_bf16 v[18:33], v[210:213], v[224:227], v[18:33]
	v_mfma_f32_32x32x16_bf16 v[2:17], v[210:213], v[228:231], v[2:17]
	ds_read_b128 v[210:213], v131 offset:4640
	s_waitcnt lgkmcnt(4)
	v_mfma_f32_32x32x16_bf16 v[114:129], v[206:209], v[232:235], v[114:129]
	ds_read_b128 v[202:205], v131 offset:64
	ds_read_b128 v[214:217], v136 offset:18496
	s_waitcnt lgkmcnt(5)
	v_mfma_f32_32x32x16_bf16 v[98:113], v[206:209], v[236:239], v[98:113]
	ds_read_b128 v[218:221], v136 offset:23104
	s_waitcnt lgkmcnt(5)
	v_mfma_f32_32x32x16_bf16 v[82:97], v[206:209], v[240:243], v[82:97]
	ds_read_b128 v[224:227], v136 offset:27712
	s_waitcnt lgkmcnt(5)
	v_mfma_f32_32x32x16_bf16 v[66:81], v[206:209], v[244:247], v[66:81]
	ds_read_b128 v[228:231], v136 offset:32320
	s_waitcnt lgkmcnt(5)
	v_mfma_f32_32x32x16_bf16 v[50:65], v[210:213], v[232:235], v[50:65]
	v_mfma_f32_32x32x16_bf16 v[34:49], v[210:213], v[236:239], v[34:49]
	v_mfma_f32_32x32x16_bf16 v[18:33], v[210:213], v[240:243], v[18:33]
	v_mfma_f32_32x32x16_bf16 v[2:17], v[210:213], v[244:247], v[2:17]
	ds_read_b128 v[210:213], v131 offset:4672
	s_waitcnt lgkmcnt(4)
	v_mfma_f32_32x32x16_bf16 v[114:129], v[202:205], v[214:217], v[114:129]
	ds_read_b128 v[206:209], v131 offset:96
	ds_read_b128 v[232:235], v136 offset:18528
	s_waitcnt lgkmcnt(5)
	v_mfma_f32_32x32x16_bf16 v[98:113], v[202:205], v[218:221], v[98:113]
	ds_read_b128 v[236:239], v136 offset:23136
	s_waitcnt lgkmcnt(5)
	v_mfma_f32_32x32x16_bf16 v[82:97], v[202:205], v[224:227], v[82:97]
	ds_read_b128 v[240:243], v136 offset:27744
	s_waitcnt lgkmcnt(5)
	v_mfma_f32_32x32x16_bf16 v[66:81], v[202:205], v[228:231], v[66:81]
	ds_read_b128 v[244:247], v136 offset:32352
	s_waitcnt lgkmcnt(5)
	v_mfma_f32_32x32x16_bf16 v[50:65], v[210:213], v[214:217], v[50:65]
	v_mfma_f32_32x32x16_bf16 v[34:49], v[210:213], v[218:221], v[34:49]
	v_mfma_f32_32x32x16_bf16 v[18:33], v[210:213], v[224:227], v[18:33]
	v_mfma_f32_32x32x16_bf16 v[2:17], v[210:213], v[228:231], v[2:17]
	ds_read_b128 v[210:213], v131 offset:4704
	s_waitcnt lgkmcnt(4)
	v_mfma_f32_32x32x16_bf16 v[114:129], v[206:209], v[232:235], v[114:129]
	s_waitcnt lgkmcnt(3)
	v_mfma_f32_32x32x16_bf16 v[98:113], v[206:209], v[236:239], v[98:113]
	s_waitcnt lgkmcnt(2)
	v_mfma_f32_32x32x16_bf16 v[82:97], v[206:209], v[240:243], v[82:97]
	s_waitcnt lgkmcnt(1)
	v_mfma_f32_32x32x16_bf16 v[66:81], v[206:209], v[244:247], v[66:81]
	s_waitcnt lgkmcnt(0)
	v_mfma_f32_32x32x16_bf16 v[50:65], v[210:213], v[232:235], v[50:65]
	v_mfma_f32_32x32x16_bf16 v[34:49], v[210:213], v[236:239], v[34:49]
	v_mfma_f32_32x32x16_bf16 v[18:33], v[210:213], v[240:243], v[18:33]
	v_mfma_f32_32x32x16_bf16 v[2:17], v[210:213], v[244:247], v[2:17]
	s_setprio 0
	s_add_u32 s10, s10, 0x80
	s_addc_u32 s11, s11, 0
	s_barrier
	s_waitcnt vmcnt(11)
	ds_write_b128 v130, v[150:153]
	s_waitcnt vmcnt(10)
	ds_write_b128 v130, v[154:157] offset:4608
	s_waitcnt vmcnt(9)
	ds_write_b128 v130, v[158:161] offset:9216
	s_waitcnt vmcnt(8)
	ds_write_b128 v130, v[162:165] offset:13824
	s_waitcnt vmcnt(7)
	ds_write_b128 v130, v[166:169] offset:18432
	s_waitcnt vmcnt(6)
	ds_write_b128 v130, v[170:173] offset:23040
	s_waitcnt vmcnt(5)
	ds_write_b128 v130, v[174:177] offset:27648
	s_waitcnt vmcnt(4)
	ds_write_b128 v130, v[178:181] offset:32256
	s_waitcnt vmcnt(3)
	ds_write_b128 v130, v[186:189] offset:36864
	s_waitcnt vmcnt(2)
	ds_write_b128 v130, v[190:193] offset:41472
	s_waitcnt vmcnt(1)
	ds_write_b128 v130, v[194:197] offset:46080
	s_waitcnt vmcnt(0)
	ds_write_b128 v130, v[198:201] offset:50688
	s_waitcnt lgkmcnt(0)
	s_barrier
;     ...
; #pragma unroll
;     for (int st = 0; st < 4; ++st) {
;       bf16x8 a0 = *(const bf16x8*)(Ab + st * 32);
;       bf16x8 a1 = *(const bf16x8*)(Ab + 32 * LSTR + st * 32);
;       bf16x8 b0 = *(const bf16x8*)(Bb + st * 32);
;       bf16x8 b1 = *(const bf16x8*)(Bb + 32 * LSTR + st * 32);
;       bf16x8 b2 = *(const bf16x8*)(Bb + 64 * LSTR + st * 32);
;       bf16x8 b3 = *(const bf16x8*)(Bb + 96 * LSTR + st * 32);
;       acc[0][0] = mfma32(a0, b0, acc[0][0]);
;       acc[0][1] = mfma32(a0, b1, acc[0][1]);
;       acc[0][2] = mfma32(a0, b2, acc[0][2]);
;       acc[0][3] = mfma32(a0, b3, acc[0][3]);
;       acc[1][0] = mfma32(a1, b0, acc[1][0]);
;       acc[1][1] = mfma32(a1, b1, acc[1][1]);
;       acc[1][2] = mfma32(a1, b2, acc[1][2]);
;       acc[1][3] = mfma32(a1, b3, acc[1][3]);
;     }
;     __builtin_amdgcn_s_setprio(0);
; __device__ __forceinline__ void inproj_tile(const Params& P, int l, int mt, int ntw, char* smem) {
;     ...
;   float* cs = (float*)smem;
;   const int row0 = mt * 128;
;   const bool isctx = row0 >= NLAT;
;   const int b = isctx ? ((row0 - NLAT) >> 8) : (row0 >> 12);
;   const int pos0 = isctx ? ((row0 - NLAT) & 255) : (row0 & 4095);
;   const int tk0 = isctx ? (SEQ + pos0) : pos0;
	v_add_co_u32_e32 v160, vcc, 0x10000, v132
	s_nop 0
	s_nop 0
	s_nop 0
	v_addc_co_u32_e32 v161, vcc, 0, v133, vcc
	v_add_co_u32_e32 v164, vcc, 0x20000, v132
	s_nop 0
	v_addc_co_u32_e32 v165, vcc, 0, v133, vcc
	v_add_co_u32_e32 v168, vcc, 0x30000, v132
	s_mov_b32 s52, 0
	s_nop 0
	v_addc_co_u32_e32 v169, vcc, 0, v133, vcc
	v_add_co_u32_e32 v172, vcc, 0x40000, v132
	s_nop 0
	v_addc_co_u32_e32 v173, vcc, 0, v133, vcc
	v_add_co_u32_e32 v176, vcc, 0x50000, v132
	s_nop 1
	v_addc_co_u32_e32 v177, vcc, 0, v133, vcc
	v_add_co_u32_e32 v180, vcc, 0x60000, v132
	s_nop 0
	v_addc_co_u32_e32 v181, vcc, 0, v133, vcc
	v_add_co_u32_e32 v132, vcc, 0x70000, v132
	s_nop 1
	v_addc_co_u32_e32 v133, vcc, 0, v133, vcc
	s_setprio 1
	ds_read_b128 v[194:197], v131 offset:0
	ds_read_b128 v[206:209], v136 offset:18432
	ds_read_b128 v[210:213], v136 offset:23040
	ds_read_b128 v[214:217], v136 offset:27648
	ds_read_b128 v[218:221], v136 offset:32256
	ds_read_b128 v[202:205], v131 offset:4608
	s_waitcnt lgkmcnt(4)
	v_mfma_f32_32x32x16_bf16 v[114:129], v[194:197], v[206:209], v[114:129]
	ds_read_b128 v[198:201], v131 offset:32
	ds_read_b128 v[224:227], v136 offset:18464
	s_waitcnt lgkmcnt(5)
	v_mfma_f32_32x32x16_bf16 v[98:113], v[194:197], v[210:213], v[98:113]
	ds_read_b128 v[228:231], v136 offset:23072
	s_waitcnt lgkmcnt(5)
	v_mfma_f32_32x32x16_bf16 v[82:97], v[194:197], v[214:217], v[82:97]
	ds_read_b128 v[232:235], v136 offset:27680
	s_waitcnt lgkmcnt(5)
	v_mfma_f32_32x32x16_bf16 v[66:81], v[194:197], v[218:221], v[66:81]
	ds_read_b128 v[236:239], v136 offset:32288
	s_waitcnt lgkmcnt(5)
	v_mfma_f32_32x32x16_bf16 v[50:65], v[202:205], v[206:209], v[50:65]
	v_mfma_f32_32x32x16_bf16 v[34:49], v[202:205], v[210:213], v[34:49]
	v_mfma_f32_32x32x16_bf16 v[18:33], v[202:205], v[214:217], v[18:33]
	v_mfma_f32_32x32x16_bf16 v[2:17], v[202:205], v[218:221], v[2:17]
	ds_read_b128 v[202:205], v131 offset:4640
	s_waitcnt lgkmcnt(4)
	v_mfma_f32_32x32x16_bf16 v[114:129], v[198:201], v[224:227], v[114:129]
	ds_read_b128 v[194:197], v131 offset:64
	ds_read_b128 v[206:209], v136 offset:18496
	s_waitcnt lgkmcnt(5)
	v_mfma_f32_32x32x16_bf16 v[98:113], v[198:201], v[228:231], v[98:113]
	ds_read_b128 v[210:213], v136 offset:23104
	s_waitcnt lgkmcnt(5)
	v_mfma_f32_32x32x16_bf16 v[82:97], v[198:201], v[232:235], v[82:97]
	ds_read_b128 v[214:217], v136 offset:27712
	s_waitcnt lgkmcnt(5)
	v_mfma_f32_32x32x16_bf16 v[66:81], v[198:201], v[236:239], v[66:81]
	ds_read_b128 v[218:221], v136 offset:32320
	s_waitcnt lgkmcnt(5)
	v_mfma_f32_32x32x16_bf16 v[50:65], v[202:205], v[224:227], v[50:65]
	v_mfma_f32_32x32x16_bf16 v[34:49], v[202:205], v[228:231], v[34:49]
	v_mfma_f32_32x32x16_bf16 v[18:33], v[202:205], v[232:235], v[18:33]
	v_mfma_f32_32x32x16_bf16 v[2:17], v[202:205], v[236:239], v[2:17]
	ds_read_b128 v[202:205], v131 offset:4672
	s_waitcnt lgkmcnt(4)
	v_mfma_f32_32x32x16_bf16 v[114:129], v[194:197], v[206:209], v[114:129]
	ds_read_b128 v[198:201], v131 offset:96
	ds_read_b128 v[224:227], v136 offset:18528
	s_waitcnt lgkmcnt(5)
	v_mfma_f32_32x32x16_bf16 v[98:113], v[194:197], v[210:213], v[98:113]
	ds_read_b128 v[228:231], v136 offset:23136
	s_waitcnt lgkmcnt(5)
	v_mfma_f32_32x32x16_bf16 v[82:97], v[194:197], v[214:217], v[82:97]
	ds_read_b128 v[232:235], v136 offset:27744
	s_waitcnt lgkmcnt(5)
	v_mfma_f32_32x32x16_bf16 v[66:81], v[194:197], v[218:221], v[66:81]
	ds_read_b128 v[236:239], v136 offset:32352
	s_waitcnt lgkmcnt(5)
	v_mfma_f32_32x32x16_bf16 v[50:65], v[202:205], v[206:209], v[50:65]
	v_mfma_f32_32x32x16_bf16 v[34:49], v[202:205], v[210:213], v[34:49]
	v_mfma_f32_32x32x16_bf16 v[18:33], v[202:205], v[214:217], v[18:33]
	v_mfma_f32_32x32x16_bf16 v[2:17], v[202:205], v[218:221], v[2:17]
	ds_read_b128 v[202:205], v131 offset:4704
	s_waitcnt lgkmcnt(4)
	v_mfma_f32_32x32x16_bf16 v[114:129], v[198:201], v[224:227], v[114:129]
	s_waitcnt lgkmcnt(3)
	v_mfma_f32_32x32x16_bf16 v[98:113], v[198:201], v[228:231], v[98:113]
	s_waitcnt lgkmcnt(2)
	v_mfma_f32_32x32x16_bf16 v[82:97], v[198:201], v[232:235], v[82:97]
	s_waitcnt lgkmcnt(1)
	v_mfma_f32_32x32x16_bf16 v[66:81], v[198:201], v[236:239], v[66:81]
	s_waitcnt lgkmcnt(0)
	v_mfma_f32_32x32x16_bf16 v[50:65], v[202:205], v[224:227], v[50:65]
	v_mfma_f32_32x32x16_bf16 v[34:49], v[202:205], v[228:231], v[34:49]
	v_mfma_f32_32x32x16_bf16 v[18:33], v[202:205], v[232:235], v[18:33]
	v_mfma_f32_32x32x16_bf16 v[2:17], v[202:205], v[236:239], v[2:17]
	s_setprio 0
	s_lshl_b32 s20, s12, 7
	s_cmpk_lt_i32 s12, 0x100
	s_cselect_b64 s[10:11], -1, 0
	s_add_i32 s8, s20, 0xffff8000
	s_and_b32 s51, s20, 0x80
	s_lshr_b32 s8, s8, 8
	s_ashr_i32 s22, s18, 2
	s_and_b32 s53, s20, 0xf80
	s_or_b32 s13, s51, 0x1000
	s_barrier
; __device__ __forceinline__ void inproj_tile(const Params& P, int l, int mt, int ntw, char* smem) {
;     ...
;   const int row0 = mt * 128;
;   const bool isctx = row0 >= NLAT;
;   const int b = isctx ? ((row0 - NLAT) >> 8) : (row0 >> 12);
;   const int pos0 = isctx ? ((row0 - NLAT) & 255) : (row0 & 4095);
;   const int tk0 = isctx ? (SEQ + pos0) : pos0;
;   int tid_ = threadIdx.x;
;   asm volatile("" : "+v"(tid_));
;   const int lane = tid_ & 63, wave = tid_ >> 6;
;   const int r = 32 * wave + (lane & 31), half = lane >> 5;
;   const size_t grow = (size_t)row0 + r;
;   const float* crow = cs + r * CSTR + half * 64;
; #pragma unroll 1
;   for (int hsel = 0; hsel < 2; ++hsel) {
;     const int nt = ntw * 2 + hsel;
;     wide_acc_to_lds(acc, cs, hsel);
;     if (nt < 4) {
;       const int part = nt >> 1, cb = (nt & 1) * 128;
;       if (!isctx) {
;         u16* base = WSP(u16, OFF_FTT) + (size_t)b * 256 * 8192 + part * 4096 + pos0;
;         epi_transposed(cs, [&](int ch) { return base + (size_t)(cb + ch) * 8192; });
;       } else {
;         u16* base = WSP(u16, OFF_FTTC) + (size_t)b * 256 * 512 + part * 256 + pos0;
;         epi_transposed(cs, [&](int ch) { return base + (size_t)(cb + ch) * 512; });
;       }
;     } else if (nt < 7 || (nt >= 10 && nt < 13)) {
;       const bool isq = nt < 7;
;       const int head = (isq ? (nt - 4) : (nt - 10)) * 2 + half;
;       const float* g = (isq ? P.na_qn_g : P.na_kn_g) + l * 64;
;       float ss = 0.f;
; #pragma unroll
;       for (int q = 0; q < 16; ++q) {
;         float4 a = *(const float4*)(crow + q * 4);
;         ss += a.x * a.x + a.y * a.y + a.z * a.z + a.w * a.w;
;       }
;       const float rinv = rsqrtf(ss * (1.f / 64.f) + EPS) * (isq ? (0.125f * LOG2E) : 1.f);
;       u16* dst = WSP(u16, isq ? OFF_QN : OFF_KN) + grow * 384 + head * 64;
; #pragma unroll 1
;       for (int q = 0; q < 8; ++q) {
;         float4 a = *(const float4*)(crow + q * 8), c = *(const float4*)(crow + q * 8 + 4);
;         float4 ga = *(const float4*)(g + q * 8), gc = *(const float4*)(g + q * 8 + 4);
;         *(uint4*)(dst + q * 8) = pack8(a.x * rinv * ga.x, a.y * rinv * ga.y, a.z * rinv * ga.z, a.w * rinv * ga.w,
;                                        c.x * rinv * gc.x, c.y * rinv * gc.y, c.z * rinv * gc.z, c.w * rinv * gc.w);
;       }
;     } else if ((nt >= 7 && nt < 10) || (nt >= 16 && nt < 19)) {
;       const bool isq = nt < 10;
	s_cmpk_gt_i32 s12, 0xff
	v_mov_b32_e32 v152, v134
	s_waitcnt lgkmcnt(0)
	s_cselect_b32 s54, s13, s53
	s_movk_i32 s13, 0xffe0
	v_ashrrev_i32_e32 v153, 1, v152
	v_bfi_b32 v130, s13, v153, v152
	s_cselect_b32 s12, s8, s22
	s_cselect_b32 s15, s51, s53
	s_ashr_i32 s21, s20, 31
	v_ashrrev_i32_e32 v131, 31, v130
	s_ashr_i32 s23, s22, 31
	v_lshl_add_u64 v[132:133], v[130:131], 0, s[20:21]
	s_lshl_b64 s[20:21], s[22:23], 22
	s_lshl_b32 s22, s14, 12
	s_movk_i32 s13, 0x210
	s_lshl_b32 s33, s14, 1
	s_ashr_i32 s23, s22, 31
	s_lshl_b64 s[24:25], s[8:9], 18
	v_mul_lo_u32 v136, v130, s13
	v_lshlrev_b32_e32 v139, 1, v152
	s_mul_i32 s13, s12, 6
	s_cmp_gt_u32 s33, 9
	v_and_b32_e32 v185, 64, v139
	s_mul_i32 s55, s12, 0x330000
	s_mul_hi_i32 s56, s13, 0x88000
	s_cselect_b64 s[12:13], -1, 0
	s_cmp_gt_u32 s33, 21
	v_lshl_add_u32 v186, v185, 2, v136
	v_add_u32_e32 v136, s15, v153
	s_cselect_b64 s[14:15], -1, 0
	s_cmp_lt_u32 s33, 16
	s_cselect_b64 s[26:27], -1, 0
	s_and_b64 s[26:27], s[26:27], exec
	s_mov_b32 s8, 0x1fffff3
	s_cselect_b32 s50, s8, 0x1ffffed
	s_mov_b32 s8, 0x32a31100
	s_cselect_b32 s8, s8, 0x343b1100
	v_mov_b64_e32 v[144:145], s[90:91]
	v_mad_u64_u32 v[144:145], s[26:27], v132, s44, v[144:145]
	s_add_u32 s8, s90, s8
	s_addc_u32 s26, s91, 0
	s_add_u32 s8, s8, s55
	s_addc_u32 s27, s26, s56
	s_lshl_b32 s26, s54, 1
	s_add_u32 s26, s8, s26
	s_addc_u32 s27, s27, 0
	v_mov_b32_e32 v139, v137
	s_add_u32 s8, s30, s20
	v_lshl_add_u64 v[146:147], s[26:27], 0, v[138:139]
	s_addc_u32 s26, s31, s21
	s_lshl_b64 s[20:21], s[22:23], 1
	s_add_u32 s8, s8, s20
	s_addc_u32 s21, s26, s21
	s_lshl_b32 s20, s53, 1
	s_add_u32 s20, s8, s20
	s_addc_u32 s21, s21, 0
	s_add_u32 s8, s34, s24
	v_lshl_add_u64 v[148:149], s[20:21], 0, v[138:139]
	s_addc_u32 s22, s35, s25
	s_lshl_b64 s[20:21], s[16:17], 1
	s_add_u32 s8, s8, s20
	s_addc_u32 s17, s22, s21
	s_lshl_b32 s20, s51, 1
	v_ashrrev_i32_e32 v136, 2, v136
	s_add_u32 s20, s8, s20
	v_and_b32_e32 v140, -16, v136
	v_lshlrev_b32_e32 v136, 4, v130
	s_addc_u32 s21, s17, 0
	s_lshl_b32 s8, s18, 10
	s_lshl_b32 s17, s19, 7
	v_and_b32_e32 v136, 0x3f0, v136
	s_or_b32 s18, s8, s17
	v_and_b32_e32 v154, 31, v152
	v_mov_b64_e32 v[142:143], v[136:137]
	v_lshrrev_b32_e32 v132, 5, v153
	v_bfe_u32 v136, v152, 5, 1
	s_ashr_i32 s19, s18, 31
	v_mad_i32_i24 v145, v133, s44, v145
	v_lshl_add_u64 v[150:151], s[20:21], 0, v[138:139]
	v_mul_lo_u32 v132, v132, s45
	v_mul_u32_u24_e32 v133, 0x210, v154
	v_lshlrev_b32_e32 v139, 8, v136
	v_lshl_add_u64 v[130:131], s[18:19], 0, v[130:131]
	v_add3_u32 v139, v132, v133, v139
	v_mad_u64_u32 v[132:133], s[18:19], v130, s46, 0
	v_mad_i32_i24 v133, v131, s46, v133
	v_lshl_or_b32 v132, v136, 7, v132
	v_lshl_add_u64 v[152:153], s[4:5], 0, v[132:133]
	v_mov_b64_e32 v[132:133], s[6:7]
	s_add_i32 s51, s16, 0xfffff500
	v_mad_u64_u32 v[154:155], s[16:17], v130, s44, v[132:133]
	v_ashrrev_i32_e32 v141, 31, v140
	v_mad_i32_i24 v155, v131, s44, v155
	s_mov_b64 s[16:17], -1
	s_branch .LBB0_241

;     ...
;   for (int kt = 0; kt < nk; ++kt) {
;     const int kn = (kt + 1 < nk) ? kt + 1 : kt;
;     GW_LOAD2(kn * 64, kn * bkstep)
;     __builtin_amdgcn_sched_barrier(0);
;     __builtin_amdgcn_s_setprio(1);
; #pragma unroll
;     for (int st = 0; st < 4; ++st) {
;       bf16x8 a0 = *(const bf16x8*)(Ab + st * 32);
;       bf16x8 a1 = *(const bf16x8*)(Ab + 32 * LSTR + st * 32);
;       bf16x8 b0 = *(const bf16x8*)(Bb + st * 32);
;       bf16x8 b1 = *(const bf16x8*)(Bb + 32 * LSTR + st * 32);
;       bf16x8 b2 = *(const bf16x8*)(Bb + 64 * LSTR + st * 32);
;       bf16x8 b3 = *(const bf16x8*)(Bb + 96 * LSTR + st * 32);
;       acc[0][0] = mfma32(a0, b0, acc[0][0]);
;       acc[0][1] = mfma32(a0, b1, acc[0][1]);
;       acc[0][2] = mfma32(a0, b2, acc[0][2]);
;       acc[0][3] = mfma32(a0, b3, acc[0][3]);
;       acc[1][0] = mfma32(a1, b0, acc[1][0]);
;       acc[1][1] = mfma32(a1, b1, acc[1][1]);
;       acc[1][2] = mfma32(a1, b2, acc[1][2]);
;       acc[1][3] = mfma32(a1, b3, acc[1][3]);
;     }
;     __builtin_amdgcn_s_setprio(0);
;     __builtin_amdgcn_sched_barrier(0);
;     __syncthreads();
;     GW_STORE()
;     __syncthreads();
.LBB0_707:
	s_setprio 1
	ds_read_b128 v[200:203], v130 offset:0
	ds_read_b128 v[212:215], v133 offset:18432
	ds_read_b128 v[216:219], v133 offset:23040
	ds_read_b128 v[224:227], v133 offset:27648
	ds_read_b128 v[228:231], v133 offset:32256
	ds_read_b128 v[208:211], v130 offset:4608
	s_waitcnt lgkmcnt(4)
	v_mfma_f32_32x32x16_bf16 v[114:129], v[200:203], v[212:215], v[114:129]
	ds_read_b128 v[204:207], v130 offset:32
	ds_read_b128 v[232:235], v133 offset:18464
	s_waitcnt lgkmcnt(5)
	v_mfma_f32_32x32x16_bf16 v[98:113], v[200:203], v[216:219], v[98:113]
	ds_read_b128 v[236:239], v133 offset:23072
	s_waitcnt lgkmcnt(5)
	v_mfma_f32_32x32x16_bf16 v[82:97], v[200:203], v[224:227], v[82:97]
	ds_read_b128 v[240:243], v133 offset:27680
	s_waitcnt lgkmcnt(5)
	v_mfma_f32_32x32x16_bf16 v[66:81], v[200:203], v[228:231], v[66:81]
	ds_read_b128 v[244:247], v133 offset:32288
	s_waitcnt lgkmcnt(5)
	v_mfma_f32_32x32x16_bf16 v[50:65], v[208:211], v[212:215], v[50:65]
	v_mfma_f32_32x32x16_bf16 v[34:49], v[208:211], v[216:219], v[34:49]
	v_mfma_f32_32x32x16_bf16 v[18:33], v[208:211], v[224:227], v[18:33]
	v_mfma_f32_32x32x16_bf16 v[2:17], v[208:211], v[228:231], v[2:17]
	ds_read_b128 v[208:211], v130 offset:4640
	s_waitcnt lgkmcnt(4)
	v_mfma_f32_32x32x16_bf16 v[114:129], v[204:207], v[232:235], v[114:129]
	ds_read_b128 v[200:203], v130 offset:64
	ds_read_b128 v[212:215], v133 offset:18496
	s_waitcnt lgkmcnt(5)
	v_mfma_f32_32x32x16_bf16 v[98:113], v[204:207], v[236:239], v[98:113]
	ds_read_b128 v[216:219], v133 offset:23104
	s_waitcnt lgkmcnt(5)
	v_mfma_f32_32x32x16_bf16 v[82:97], v[204:207], v[240:243], v[82:97]
	ds_read_b128 v[224:227], v133 offset:27712
	s_waitcnt lgkmcnt(5)
	v_mfma_f32_32x32x16_bf16 v[66:81], v[204:207], v[244:247], v[66:81]
	ds_read_b128 v[228:231], v133 offset:32320
	s_waitcnt lgkmcnt(5)
	v_mfma_f32_32x32x16_bf16 v[50:65], v[208:211], v[232:235], v[50:65]
	v_mfma_f32_32x32x16_bf16 v[34:49], v[208:211], v[236:239], v[34:49]
	v_mfma_f32_32x32x16_bf16 v[18:33], v[208:211], v[240:243], v[18:33]
	v_mfma_f32_32x32x16_bf16 v[2:17], v[208:211], v[244:247], v[2:17]
	ds_read_b128 v[208:211], v130 offset:4672
	s_waitcnt lgkmcnt(4)
	v_mfma_f32_32x32x16_bf16 v[114:129], v[200:203], v[212:215], v[114:129]
	ds_read_b128 v[204:207], v130 offset:96
	ds_read_b128 v[232:235], v133 offset:18528
	s_waitcnt lgkmcnt(5)
	v_mfma_f32_32x32x16_bf16 v[98:113], v[200:203], v[216:219], v[98:113]
	ds_read_b128 v[236:239], v133 offset:23136
	s_waitcnt lgkmcnt(5)
	v_mfma_f32_32x32x16_bf16 v[82:97], v[200:203], v[224:227], v[82:97]
	ds_read_b128 v[240:243], v133 offset:27744
	s_waitcnt lgkmcnt(5)
	v_mfma_f32_32x32x16_bf16 v[66:81], v[200:203], v[228:231], v[66:81]
	ds_read_b128 v[244:247], v133 offset:32352
	s_waitcnt lgkmcnt(5)
	v_mfma_f32_32x32x16_bf16 v[50:65], v[208:211], v[212:215], v[50:65]
	v_mfma_f32_32x32x16_bf16 v[34:49], v[208:211], v[216:219], v[34:49]
	v_mfma_f32_32x32x16_bf16 v[18:33], v[208:211], v[224:227], v[18:33]
	v_mfma_f32_32x32x16_bf16 v[2:17], v[208:211], v[228:231], v[2:17]
	ds_read_b128 v[208:211], v130 offset:4704
	s_waitcnt lgkmcnt(4)
	v_mfma_f32_32x32x16_bf16 v[114:129], v[204:207], v[232:235], v[114:129]
	s_waitcnt lgkmcnt(3)
	v_mfma_f32_32x32x16_bf16 v[98:113], v[204:207], v[236:239], v[98:113]
	s_waitcnt lgkmcnt(2)
	v_mfma_f32_32x32x16_bf16 v[82:97], v[204:207], v[240:243], v[82:97]
	s_waitcnt lgkmcnt(1)
	v_mfma_f32_32x32x16_bf16 v[66:81], v[204:207], v[244:247], v[66:81]
	s_waitcnt lgkmcnt(0)
	v_mfma_f32_32x32x16_bf16 v[50:65], v[208:211], v[232:235], v[50:65]
	v_mfma_f32_32x32x16_bf16 v[34:49], v[208:211], v[236:239], v[34:49]
	v_mfma_f32_32x32x16_bf16 v[18:33], v[208:211], v[240:243], v[18:33]
	v_mfma_f32_32x32x16_bf16 v[2:17], v[208:211], v[244:247], v[2:17]
	s_setprio 0
	s_add_u32 s18, s18, 0x80
	s_addc_u32 s19, s19, 0
	s_cmpk_lg_i32 s18, 0x700
	s_barrier
	s_waitcnt vmcnt(11)
	ds_write_b128 v132, v[152:155]
	v_lshl_add_u64 v[152:153], v[146:147], 0, s[18:19]
	v_add_co_u32_e32 v152, vcc, s39, v152
	s_nop 1
	v_addc_co_u32_e32 v153, vcc, 0, v153, vcc
	global_load_dwordx4 v[152:155], v[152:153], off offset:384
	s_waitcnt vmcnt(11)
	ds_write_b128 v132, v[156:159] offset:4608
	v_lshl_add_u64 v[156:157], v[146:147], 0, s[18:19]
	v_add_co_u32_e32 v156, vcc, s40, v156
	s_nop 1
	v_addc_co_u32_e32 v157, vcc, 0, v157, vcc
	global_load_dwordx4 v[156:159], v[156:157], off offset:384
	s_waitcnt vmcnt(11)
	ds_write_b128 v132, v[160:163] offset:9216
	v_lshl_add_u64 v[160:161], v[146:147], 0, s[18:19]
	v_add_co_u32_e32 v160, vcc, s41, v160
	s_nop 1
	v_addc_co_u32_e32 v161, vcc, 0, v161, vcc
	global_load_dwordx4 v[160:163], v[160:161], off offset:384
	s_waitcnt vmcnt(11)
	ds_write_b128 v132, v[164:167] offset:13824
	v_lshl_add_u64 v[164:165], v[146:147], 0, s[18:19]
	v_add_co_u32_e32 v164, vcc, s42, v164
	s_nop 1
	v_addc_co_u32_e32 v165, vcc, 0, v165, vcc
	global_load_dwordx4 v[164:167], v[164:165], off offset:384
	s_waitcnt vmcnt(11)
	ds_write_b128 v132, v[168:171] offset:18432
	v_lshl_add_u64 v[168:169], v[148:149], 0, s[18:19]
	v_add_co_u32_e32 v168, vcc, s43, v168
	s_nop 1
	v_addc_co_u32_e32 v169, vcc, 0, v169, vcc
	global_load_dwordx4 v[168:171], v[168:169], off offset:128
	s_waitcnt vmcnt(11)
	ds_write_b128 v132, v[172:175] offset:23040
	v_lshl_add_u64 v[172:173], v[148:149], 0, s[18:19]
	v_add_co_u32_e32 v172, vcc, s44, v172
	s_nop 1
	v_addc_co_u32_e32 v173, vcc, 0, v173, vcc
	global_load_dwordx4 v[172:175], v[172:173], off offset:128
	s_waitcnt vmcnt(11)
	ds_write_b128 v132, v[176:179] offset:27648
	v_lshl_add_u64 v[176:177], v[148:149], 0, s[18:19]
	v_add_co_u32_e32 v176, vcc, s45, v176
	s_nop 1
	v_addc_co_u32_e32 v177, vcc, 0, v177, vcc
	global_load_dwordx4 v[176:179], v[176:177], off offset:128
	s_waitcnt vmcnt(11)
;     ...
;     GW_LOAD2(kn * 64, kn * bkstep)
;     __builtin_amdgcn_sched_barrier(0);
;     __builtin_amdgcn_s_setprio(1);
; #pragma unroll
;     for (int st = 0; st < 4; ++st) {
;       bf16x8 a0 = *(const bf16x8*)(Ab + st * 32);
;       bf16x8 a1 = *(const bf16x8*)(Ab + 32 * LSTR + st * 32);
;       bf16x8 b0 = *(const bf16x8*)(Bb + st * 32);
;       bf16x8 b1 = *(const bf16x8*)(Bb + 32 * LSTR + st * 32);
;       bf16x8 b2 = *(const bf16x8*)(Bb + 64 * LSTR + st * 32);
;       bf16x8 b3 = *(const bf16x8*)(Bb + 96 * LSTR + st * 32);
;       acc[0][0] = mfma32(a0, b0, acc[0][0]);
;       acc[0][1] = mfma32(a0, b1, acc[0][1]);
;       acc[0][2] = mfma32(a0, b2, acc[0][2]);
;       acc[0][3] = mfma32(a0, b3, acc[0][3]);
;       acc[1][0] = mfma32(a1, b0, acc[1][0]);
;       acc[1][1] = mfma32(a1, b1, acc[1][1]);
;       acc[1][2] = mfma32(a1, b2, acc[1][2]);
;       acc[1][3] = mfma32(a1, b3, acc[1][3]);
;     }
;     __builtin_amdgcn_s_setprio(0);
;     __builtin_amdgcn_sched_barrier(0);
;     __syncthreads();
;     GW_STORE()
	ds_write_b128 v132, v[180:183] offset:32256
	v_lshl_add_u64 v[180:181], v[148:149], 0, s[18:19]
	v_add_co_u32_e32 v180, vcc, s46, v180
	s_nop 1
	v_addc_co_u32_e32 v181, vcc, 0, v181, vcc
	global_load_dwordx4 v[180:183], v[180:181], off offset:128
	s_waitcnt vmcnt(11)
	ds_write_b128 v132, v[184:187] offset:36864
	v_lshl_add_u64 v[184:185], v[148:149], 0, s[18:19]
	v_add_co_u32_e32 v184, vcc, s47, v184
	s_nop 1
	v_addc_co_u32_e32 v185, vcc, 0, v185, vcc
	global_load_dwordx4 v[184:187], v[184:185], off offset:128
	s_waitcnt vmcnt(11)
	ds_write_b128 v132, v[188:191] offset:41472
	v_lshl_add_u64 v[188:189], v[148:149], 0, s[18:19]
	v_add_co_u32_e32 v188, vcc, s48, v188
	s_nop 1
	v_addc_co_u32_e32 v189, vcc, 0, v189, vcc
	global_load_dwordx4 v[188:191], v[188:189], off offset:128
	s_waitcnt vmcnt(11)
	ds_write_b128 v132, v[192:195] offset:46080
	v_lshl_add_u64 v[192:193], v[148:149], 0, s[18:19]
	v_add_co_u32_e32 v192, vcc, s49, v192
	s_nop 1
	v_addc_co_u32_e32 v193, vcc, 0, v193, vcc
	global_load_dwordx4 v[192:195], v[192:193], off offset:128
	s_waitcnt vmcnt(11)
	ds_write_b128 v132, v[196:199] offset:50688
	v_lshl_add_u64 v[196:197], v[148:149], 0, s[18:19]
	v_add_co_u32_e32 v196, vcc, s50, v196
	s_nop 1
	v_addc_co_u32_e32 v197, vcc, 0, v197, vcc
	global_load_dwordx4 v[196:199], v[196:197], off offset:128
	s_waitcnt lgkmcnt(0)
	s_barrier
	s_cbranch_scc1 .LBB0_707
	s_setprio 1
	ds_read_b128 v[200:203], v130 offset:0
	ds_read_b128 v[212:215], v133 offset:18432
	ds_read_b128 v[216:219], v133 offset:23040
	ds_read_b128 v[224:227], v133 offset:27648
	ds_read_b128 v[228:231], v133 offset:32256
	ds_read_b128 v[208:211], v130 offset:4608
	s_waitcnt lgkmcnt(4)
	v_mfma_f32_32x32x16_bf16 v[114:129], v[200:203], v[212:215], v[114:129]
	ds_read_b128 v[204:207], v130 offset:32
	ds_read_b128 v[232:235], v133 offset:18464
	s_waitcnt lgkmcnt(5)
	v_mfma_f32_32x32x16_bf16 v[98:113], v[200:203], v[216:219], v[98:113]
	ds_read_b128 v[236:239], v133 offset:23072
	s_waitcnt lgkmcnt(5)
	v_mfma_f32_32x32x16_bf16 v[82:97], v[200:203], v[224:227], v[82:97]
	ds_read_b128 v[240:243], v133 offset:27680
	s_waitcnt lgkmcnt(5)
	v_mfma_f32_32x32x16_bf16 v[66:81], v[200:203], v[228:231], v[66:81]
	ds_read_b128 v[244:247], v133 offset:32288
	s_waitcnt lgkmcnt(5)
	v_mfma_f32_32x32x16_bf16 v[50:65], v[208:211], v[212:215], v[50:65]
	v_mfma_f32_32x32x16_bf16 v[34:49], v[208:211], v[216:219], v[34:49]
	v_mfma_f32_32x32x16_bf16 v[18:33], v[208:211], v[224:227], v[18:33]
	v_mfma_f32_32x32x16_bf16 v[2:17], v[208:211], v[228:231], v[2:17]
	ds_read_b128 v[208:211], v130 offset:4640
	s_waitcnt lgkmcnt(4)
	v_mfma_f32_32x32x16_bf16 v[114:129], v[204:207], v[232:235], v[114:129]
	ds_read_b128 v[200:203], v130 offset:64
	ds_read_b128 v[212:215], v133 offset:18496
	s_waitcnt lgkmcnt(5)
	v_mfma_f32_32x32x16_bf16 v[98:113], v[204:207], v[236:239], v[98:113]
	ds_read_b128 v[216:219], v133 offset:23104
	s_waitcnt lgkmcnt(5)
	v_mfma_f32_32x32x16_bf16 v[82:97], v[204:207], v[240:243], v[82:97]
	ds_read_b128 v[224:227], v133 offset:27712
	s_waitcnt lgkmcnt(5)
	v_mfma_f32_32x32x16_bf16 v[66:81], v[204:207], v[244:247], v[66:81]
	ds_read_b128 v[228:231], v133 offset:32320
	s_waitcnt lgkmcnt(5)
	v_mfma_f32_32x32x16_bf16 v[50:65], v[208:211], v[232:235], v[50:65]
	v_mfma_f32_32x32x16_bf16 v[34:49], v[208:211], v[236:239], v[34:49]
	v_mfma_f32_32x32x16_bf16 v[18:33], v[208:211], v[240:243], v[18:33]
	v_mfma_f32_32x32x16_bf16 v[2:17], v[208:211], v[244:247], v[2:17]
	ds_read_b128 v[208:211], v130 offset:4672
	s_waitcnt lgkmcnt(4)
	v_mfma_f32_32x32x16_bf16 v[114:129], v[200:203], v[212:215], v[114:129]
	ds_read_b128 v[204:207], v130 offset:96
	ds_read_b128 v[232:235], v133 offset:18528
	s_waitcnt lgkmcnt(5)
	v_mfma_f32_32x32x16_bf16 v[98:113], v[200:203], v[216:219], v[98:113]
	ds_read_b128 v[236:239], v133 offset:23136
	s_waitcnt lgkmcnt(5)
	v_mfma_f32_32x32x16_bf16 v[82:97], v[200:203], v[224:227], v[82:97]
	ds_read_b128 v[240:243], v133 offset:27744
	s_waitcnt lgkmcnt(5)
	v_mfma_f32_32x32x16_bf16 v[66:81], v[200:203], v[228:231], v[66:81]
	ds_read_b128 v[244:247], v133 offset:32352
	s_waitcnt lgkmcnt(5)
	v_mfma_f32_32x32x16_bf16 v[50:65], v[208:211], v[212:215], v[50:65]
	v_mfma_f32_32x32x16_bf16 v[34:49], v[208:211], v[216:219], v[34:49]
	v_mfma_f32_32x32x16_bf16 v[18:33], v[208:211], v[224:227], v[18:33]
	v_mfma_f32_32x32x16_bf16 v[2:17], v[208:211], v[228:231], v[2:17]
	ds_read_b128 v[208:211], v130 offset:4704
	s_waitcnt lgkmcnt(4)
	v_mfma_f32_32x32x16_bf16 v[114:129], v[204:207], v[232:235], v[114:129]
	s_waitcnt lgkmcnt(3)
	v_mfma_f32_32x32x16_bf16 v[98:113], v[204:207], v[236:239], v[98:113]
	s_waitcnt lgkmcnt(2)
	v_mfma_f32_32x32x16_bf16 v[82:97], v[204:207], v[240:243], v[82:97]
	s_waitcnt lgkmcnt(1)
	v_mfma_f32_32x32x16_bf16 v[66:81], v[204:207], v[244:247], v[66:81]
	s_waitcnt lgkmcnt(0)
	v_mfma_f32_32x32x16_bf16 v[50:65], v[208:211], v[232:235], v[50:65]
	v_mfma_f32_32x32x16_bf16 v[34:49], v[208:211], v[236:239], v[34:49]
	v_mfma_f32_32x32x16_bf16 v[18:33], v[208:211], v[240:243], v[18:33]
	v_mfma_f32_32x32x16_bf16 v[2:17], v[208:211], v[244:247], v[2:17]
	s_setprio 0
	s_add_u32 s18, s18, 0x80
	s_addc_u32 s19, s19, 0
	s_barrier
;     ...
; #pragma unroll
;     for (int st = 0; st < 4; ++st) {
;       bf16x8 a0 = *(const bf16x8*)(Ab + st * 32);
;       bf16x8 a1 = *(const bf16x8*)(Ab + 32 * LSTR + st * 32);
;       bf16x8 b0 = *(const bf16x8*)(Bb + st * 32);
;       bf16x8 b1 = *(const bf16x8*)(Bb + 32 * LSTR + st * 32);
;       bf16x8 b2 = *(const bf16x8*)(Bb + 64 * LSTR + st * 32);
;       bf16x8 b3 = *(const bf16x8*)(Bb + 96 * LSTR + st * 32);
;       acc[0][0] = mfma32(a0, b0, acc[0][0]);
;       acc[0][1] = mfma32(a0, b1, acc[0][1]);
;       acc[0][2] = mfma32(a0, b2, acc[0][2]);
;       acc[0][3] = mfma32(a0, b3, acc[0][3]);
;       acc[1][0] = mfma32(a1, b0, acc[1][0]);
;       acc[1][1] = mfma32(a1, b1, acc[1][1]);
;       acc[1][2] = mfma32(a1, b2, acc[1][2]);
;       acc[1][3] = mfma32(a1, b3, acc[1][3]);
;     }
;     __builtin_amdgcn_s_setprio(0);
;     ...
;     __syncthreads();
;     GW_STORE()
;     __syncthreads();
	s_waitcnt vmcnt(11)
	ds_write_b128 v132, v[152:155]
	s_waitcnt vmcnt(10)
	ds_write_b128 v132, v[156:159] offset:4608
	s_waitcnt vmcnt(9)
	ds_write_b128 v132, v[160:163] offset:9216
	s_waitcnt vmcnt(8)
	ds_write_b128 v132, v[164:167] offset:13824
	s_waitcnt vmcnt(7)
	ds_write_b128 v132, v[168:171] offset:18432
	s_waitcnt vmcnt(6)
	ds_write_b128 v132, v[172:175] offset:23040
	s_waitcnt vmcnt(5)
	ds_write_b128 v132, v[176:179] offset:27648
	s_waitcnt vmcnt(4)
	ds_write_b128 v132, v[180:183] offset:32256
	s_waitcnt vmcnt(3)
	ds_write_b128 v132, v[184:187] offset:36864
	s_waitcnt vmcnt(2)
	ds_write_b128 v132, v[188:191] offset:41472
	s_waitcnt vmcnt(1)
	ds_write_b128 v132, v[192:195] offset:46080
	s_waitcnt vmcnt(0)
	ds_write_b128 v132, v[196:199] offset:50688
	s_waitcnt lgkmcnt(0)
	s_barrier
	v_add_co_u32_e32 v160, vcc, 0x10000, v136
	s_nop 0
	s_nop 0
	s_nop 0
	v_addc_co_u32_e32 v161, vcc, 0, v137, vcc
	v_add_co_u32_e32 v164, vcc, 0x20000, v136
	s_nop 0
	v_addc_co_u32_e32 v165, vcc, 0, v137, vcc
	v_add_co_u32_e32 v168, vcc, 0x30000, v136
	s_lshl_b64 s[16:17], s[16:17], 7
	s_nop 0
	v_addc_co_u32_e32 v169, vcc, 0, v137, vcc
	v_add_co_u32_e32 v172, vcc, 0x40000, v136
	s_nop 0
	v_addc_co_u32_e32 v173, vcc, 0, v137, vcc
	v_add_co_u32_e32 v176, vcc, 0x50000, v136
	s_mov_b32 s15, 0
	s_nop 0
	v_addc_co_u32_e32 v177, vcc, 0, v137, vcc
	v_add_co_u32_e32 v180, vcc, 0x60000, v136
	s_nop 0
	v_addc_co_u32_e32 v181, vcc, 0, v137, vcc
	v_add_co_u32_e32 v136, vcc, 0x70000, v136
	s_nop 1
	v_addc_co_u32_e32 v137, vcc, 0, v137, vcc
	s_nop 0
	s_setprio 1
	ds_read_b128 v[188:191], v130 offset:0
	ds_read_b128 v[200:203], v133 offset:18432
	ds_read_b128 v[204:207], v133 offset:23040
	ds_read_b128 v[208:211], v133 offset:27648
	ds_read_b128 v[212:215], v133 offset:32256
	ds_read_b128 v[196:199], v130 offset:4608
	s_waitcnt lgkmcnt(4)
	v_mfma_f32_32x32x16_bf16 v[114:129], v[188:191], v[200:203], v[114:129]
	ds_read_b128 v[192:195], v130 offset:32
	ds_read_b128 v[216:219], v133 offset:18464
	s_waitcnt lgkmcnt(5)
	v_mfma_f32_32x32x16_bf16 v[98:113], v[188:191], v[204:207], v[98:113]
	ds_read_b128 v[224:227], v133 offset:23072
	s_waitcnt lgkmcnt(5)
	v_mfma_f32_32x32x16_bf16 v[82:97], v[188:191], v[208:211], v[82:97]
	ds_read_b128 v[228:231], v133 offset:27680
	s_waitcnt lgkmcnt(5)
	v_mfma_f32_32x32x16_bf16 v[66:81], v[188:191], v[212:215], v[66:81]
	ds_read_b128 v[232:235], v133 offset:32288
	s_waitcnt lgkmcnt(5)
	v_mfma_f32_32x32x16_bf16 v[50:65], v[196:199], v[200:203], v[50:65]
	v_mfma_f32_32x32x16_bf16 v[34:49], v[196:199], v[204:207], v[34:49]
	v_mfma_f32_32x32x16_bf16 v[18:33], v[196:199], v[208:211], v[18:33]
	v_mfma_f32_32x32x16_bf16 v[2:17], v[196:199], v[212:215], v[2:17]
	ds_read_b128 v[196:199], v130 offset:4640
	s_waitcnt lgkmcnt(4)
	v_mfma_f32_32x32x16_bf16 v[114:129], v[192:195], v[216:219], v[114:129]
	ds_read_b128 v[188:191], v130 offset:64
	ds_read_b128 v[200:203], v133 offset:18496
	s_waitcnt lgkmcnt(5)
	v_mfma_f32_32x32x16_bf16 v[98:113], v[192:195], v[224:227], v[98:113]
	ds_read_b128 v[204:207], v133 offset:23104
	s_waitcnt lgkmcnt(5)
	v_mfma_f32_32x32x16_bf16 v[82:97], v[192:195], v[228:231], v[82:97]
	ds_read_b128 v[208:211], v133 offset:27712
	s_waitcnt lgkmcnt(5)
	v_mfma_f32_32x32x16_bf16 v[66:81], v[192:195], v[232:235], v[66:81]
	ds_read_b128 v[212:215], v133 offset:32320
	s_waitcnt lgkmcnt(5)
	v_mfma_f32_32x32x16_bf16 v[50:65], v[196:199], v[216:219], v[50:65]
	v_mfma_f32_32x32x16_bf16 v[34:49], v[196:199], v[224:227], v[34:49]
	v_mfma_f32_32x32x16_bf16 v[18:33], v[196:199], v[228:231], v[18:33]
	v_mfma_f32_32x32x16_bf16 v[2:17], v[196:199], v[232:235], v[2:17]
	ds_read_b128 v[196:199], v130 offset:4672
	s_waitcnt lgkmcnt(4)
	v_mfma_f32_32x32x16_bf16 v[114:129], v[188:191], v[200:203], v[114:129]
	ds_read_b128 v[192:195], v130 offset:96
	ds_read_b128 v[216:219], v133 offset:18528
	s_waitcnt lgkmcnt(5)
	v_mfma_f32_32x32x16_bf16 v[98:113], v[188:191], v[204:207], v[98:113]
	ds_read_b128 v[224:227], v133 offset:23136
	s_waitcnt lgkmcnt(5)
	v_mfma_f32_32x32x16_bf16 v[82:97], v[188:191], v[208:211], v[82:97]
	ds_read_b128 v[228:231], v133 offset:27744
	s_waitcnt lgkmcnt(5)
	v_mfma_f32_32x32x16_bf16 v[66:81], v[188:191], v[212:215], v[66:81]
	ds_read_b128 v[232:235], v133 offset:32352
	s_waitcnt lgkmcnt(5)
	v_mfma_f32_32x32x16_bf16 v[50:65], v[196:199], v[200:203], v[50:65]
	v_mfma_f32_32x32x16_bf16 v[34:49], v[196:199], v[204:207], v[34:49]
	v_mfma_f32_32x32x16_bf16 v[18:33], v[196:199], v[208:211], v[18:33]
	v_mfma_f32_32x32x16_bf16 v[2:17], v[196:199], v[212:215], v[2:17]
	ds_read_b128 v[196:199], v130 offset:4704
	s_waitcnt lgkmcnt(4)
	v_mfma_f32_32x32x16_bf16 v[114:129], v[192:195], v[216:219], v[114:129]
	s_waitcnt lgkmcnt(3)
	v_mfma_f32_32x32x16_bf16 v[98:113], v[192:195], v[224:227], v[98:113]
	s_waitcnt lgkmcnt(2)
	v_mfma_f32_32x32x16_bf16 v[82:97], v[192:195], v[228:231], v[82:97]
	s_waitcnt lgkmcnt(1)
	v_mfma_f32_32x32x16_bf16 v[66:81], v[192:195], v[232:235], v[66:81]
	s_waitcnt lgkmcnt(0)
	v_mfma_f32_32x32x16_bf16 v[50:65], v[196:199], v[216:219], v[50:65]
	v_mfma_f32_32x32x16_bf16 v[34:49], v[196:199], v[224:227], v[34:49]
	v_mfma_f32_32x32x16_bf16 v[18:33], v[196:199], v[228:231], v[18:33]
	v_mfma_f32_32x32x16_bf16 v[2:17], v[196:199], v[232:235], v[2:17]
	s_setprio 0
	s_mov_b64 s[18:19], -1
	s_barrier
	s_waitcnt lgkmcnt(0)

;     ...
;   for (int kt = 0; kt < nk; ++kt) {
;     const int kn = (kt + 1 < nk) ? kt + 1 : kt;
;     GW_LOAD2(kn * 64, kn * bkstep)
;     __builtin_amdgcn_sched_barrier(0);
;     __builtin_amdgcn_s_setprio(1);
; #pragma unroll
;     for (int st = 0; st < 4; ++st) {
;       bf16x8 a0 = *(const bf16x8*)(Ab + st * 32);
;       bf16x8 a1 = *(const bf16x8*)(Ab + 32 * LSTR + st * 32);
;       bf16x8 b0 = *(const bf16x8*)(Bb + st * 32);
;       bf16x8 b1 = *(const bf16x8*)(Bb + 32 * LSTR + st * 32);
;       bf16x8 b2 = *(const bf16x8*)(Bb + 64 * LSTR + st * 32);
;       bf16x8 b3 = *(const bf16x8*)(Bb + 96 * LSTR + st * 32);
;       acc[0][0] = mfma32(a0, b0, acc[0][0]);
;       acc[0][1] = mfma32(a0, b1, acc[0][1]);
;       acc[0][2] = mfma32(a0, b2, acc[0][2]);
;       acc[0][3] = mfma32(a0, b3, acc[0][3]);
;       acc[1][0] = mfma32(a1, b0, acc[1][0]);
;       acc[1][1] = mfma32(a1, b1, acc[1][1]);
;       acc[1][2] = mfma32(a1, b2, acc[1][2]);
;       acc[1][3] = mfma32(a1, b3, acc[1][3]);
;     }
;     __builtin_amdgcn_s_setprio(0);
;     __builtin_amdgcn_sched_barrier(0);
;     __syncthreads();
;     GW_STORE()
;     __syncthreads();
.LBB0_1035:
	s_setprio 1
	ds_read_b128 v[206:209], v133 offset:0
	ds_read_b128 v[218:221], v156 offset:18432
	ds_read_b128 v[224:227], v156 offset:23040
	ds_read_b128 v[228:231], v156 offset:27648
	ds_read_b128 v[232:235], v156 offset:32256
	ds_read_b128 v[214:217], v133 offset:4608
	s_waitcnt lgkmcnt(4)
	v_mfma_f32_32x32x16_bf16 v[114:129], v[206:209], v[218:221], v[114:129]
	ds_read_b128 v[210:213], v133 offset:32
	ds_read_b128 v[236:239], v156 offset:18464
	s_waitcnt lgkmcnt(5)
	v_mfma_f32_32x32x16_bf16 v[98:113], v[206:209], v[224:227], v[98:113]
	ds_read_b128 v[240:243], v156 offset:23072
	s_waitcnt lgkmcnt(5)
	v_mfma_f32_32x32x16_bf16 v[82:97], v[206:209], v[228:231], v[82:97]
	ds_read_b128 v[244:247], v156 offset:27680
	s_waitcnt lgkmcnt(5)
	v_mfma_f32_32x32x16_bf16 v[66:81], v[206:209], v[232:235], v[66:81]
	ds_read_b128 v[248:251], v156 offset:32288
	s_waitcnt lgkmcnt(5)
	v_mfma_f32_32x32x16_bf16 v[50:65], v[214:217], v[218:221], v[50:65]
	v_mfma_f32_32x32x16_bf16 v[34:49], v[214:217], v[224:227], v[34:49]
	v_mfma_f32_32x32x16_bf16 v[18:33], v[214:217], v[228:231], v[18:33]
	v_mfma_f32_32x32x16_bf16 v[2:17], v[214:217], v[232:235], v[2:17]
	ds_read_b128 v[214:217], v133 offset:4640
	s_waitcnt lgkmcnt(4)
	v_mfma_f32_32x32x16_bf16 v[114:129], v[210:213], v[236:239], v[114:129]
	ds_read_b128 v[206:209], v133 offset:64
	ds_read_b128 v[218:221], v156 offset:18496
	s_waitcnt lgkmcnt(5)
	v_mfma_f32_32x32x16_bf16 v[98:113], v[210:213], v[240:243], v[98:113]
	ds_read_b128 v[224:227], v156 offset:23104
	s_waitcnt lgkmcnt(5)
	v_mfma_f32_32x32x16_bf16 v[82:97], v[210:213], v[244:247], v[82:97]
	ds_read_b128 v[228:231], v156 offset:27712
	s_waitcnt lgkmcnt(5)
	v_mfma_f32_32x32x16_bf16 v[66:81], v[210:213], v[248:251], v[66:81]
	ds_read_b128 v[232:235], v156 offset:32320
	s_waitcnt lgkmcnt(5)
	v_mfma_f32_32x32x16_bf16 v[50:65], v[214:217], v[236:239], v[50:65]
	v_mfma_f32_32x32x16_bf16 v[34:49], v[214:217], v[240:243], v[34:49]
	v_mfma_f32_32x32x16_bf16 v[18:33], v[214:217], v[244:247], v[18:33]
	v_mfma_f32_32x32x16_bf16 v[2:17], v[214:217], v[248:251], v[2:17]
	ds_read_b128 v[214:217], v133 offset:4672
	s_waitcnt lgkmcnt(4)
	v_mfma_f32_32x32x16_bf16 v[114:129], v[206:209], v[218:221], v[114:129]
	ds_read_b128 v[210:213], v133 offset:96
	ds_read_b128 v[236:239], v156 offset:18528
	s_waitcnt lgkmcnt(5)
	v_mfma_f32_32x32x16_bf16 v[98:113], v[206:209], v[224:227], v[98:113]
	ds_read_b128 v[240:243], v156 offset:23136
	s_waitcnt lgkmcnt(5)
	v_mfma_f32_32x32x16_bf16 v[82:97], v[206:209], v[228:231], v[82:97]
	ds_read_b128 v[244:247], v156 offset:27744
	s_waitcnt lgkmcnt(5)
	v_mfma_f32_32x32x16_bf16 v[66:81], v[206:209], v[232:235], v[66:81]
	ds_read_b128 v[248:251], v156 offset:32352
	s_waitcnt lgkmcnt(5)
	v_mfma_f32_32x32x16_bf16 v[50:65], v[214:217], v[218:221], v[50:65]
	v_mfma_f32_32x32x16_bf16 v[34:49], v[214:217], v[224:227], v[34:49]
	v_mfma_f32_32x32x16_bf16 v[18:33], v[214:217], v[228:231], v[18:33]
	v_mfma_f32_32x32x16_bf16 v[2:17], v[214:217], v[232:235], v[2:17]
	ds_read_b128 v[214:217], v133 offset:4704
	s_waitcnt lgkmcnt(4)
	v_mfma_f32_32x32x16_bf16 v[114:129], v[210:213], v[236:239], v[114:129]
	s_waitcnt lgkmcnt(3)
	v_mfma_f32_32x32x16_bf16 v[98:113], v[210:213], v[240:243], v[98:113]
	s_waitcnt lgkmcnt(2)
	v_mfma_f32_32x32x16_bf16 v[82:97], v[210:213], v[244:247], v[82:97]
	s_waitcnt lgkmcnt(1)
	v_mfma_f32_32x32x16_bf16 v[66:81], v[210:213], v[248:251], v[66:81]
	s_waitcnt lgkmcnt(0)
	v_mfma_f32_32x32x16_bf16 v[50:65], v[214:217], v[236:239], v[50:65]
	v_mfma_f32_32x32x16_bf16 v[34:49], v[214:217], v[240:243], v[34:49]
	v_mfma_f32_32x32x16_bf16 v[18:33], v[214:217], v[244:247], v[18:33]
	v_mfma_f32_32x32x16_bf16 v[2:17], v[214:217], v[248:251], v[2:17]
	s_setprio 0
	s_add_i32 s41, s41, -1
	v_lshl_add_u64 v[146:147], v[146:147], 0, s[8:9]
	v_lshl_add_u64 v[148:149], v[148:149], 0, s[10:11]
	v_lshl_add_u64 v[150:151], v[150:151], 0, s[10:11]
	v_lshl_add_u64 v[152:153], v[152:153], 0, s[10:11]
	s_cmp_lg_u32 s41, 0
	v_lshl_add_u64 v[154:155], v[154:155], 0, s[10:11]
	s_barrier
	s_waitcnt vmcnt(11)
	ds_write_b128 v132, v[158:161]
	v_lshl_add_u64 v[158:159], v[148:149], 0, v[130:131]
	global_load_dwordx4 v[158:161], v[158:159], off
	s_waitcnt vmcnt(11)
	ds_write_b128 v132, v[162:165] offset:4608
	v_lshl_add_u64 v[162:163], v[150:151], 0, v[130:131]
	global_load_dwordx4 v[162:165], v[162:163], off
	s_waitcnt vmcnt(11)
	ds_write_b128 v132, v[166:169] offset:9216
	v_lshl_add_u64 v[166:167], v[152:153], 0, v[130:131]
	global_load_dwordx4 v[166:169], v[166:167], off
	s_waitcnt vmcnt(11)
	ds_write_b128 v132, v[170:173] offset:13824
	v_lshl_add_u64 v[170:171], v[154:155], 0, v[130:131]
	global_load_dwordx4 v[170:173], v[170:171], off
	s_waitcnt vmcnt(11)
	ds_write_b128 v132, v[174:177] offset:18432
	v_lshl_add_u64 v[174:175], v[146:147], 0, v[130:131]
	v_add_co_u32_e32 v174, vcc, s35, v174
	s_nop 1
	v_addc_co_u32_e32 v175, vcc, 0, v175, vcc
	global_load_dwordx4 v[174:177], v[174:175], off offset:-4096
	s_waitcnt vmcnt(11)
	ds_write_b128 v132, v[178:181] offset:23040
	v_lshl_add_u64 v[178:179], v[146:147], 0, v[130:131]
	v_add_co_u32_e32 v178, vcc, s35, v178
	s_nop 1
	v_addc_co_u32_e32 v179, vcc, 0, v179, vcc
	global_load_dwordx4 v[178:181], v[178:179], off
	s_waitcnt vmcnt(11)
	ds_write_b128 v132, v[182:185] offset:27648
	v_lshl_add_u64 v[182:183], v[146:147], 0, v[130:131]
	v_add_co_u32_e32 v182, vcc, s36, v182
	s_nop 1
	v_addc_co_u32_e32 v183, vcc, 0, v183, vcc
	global_load_dwordx4 v[182:185], v[182:183], off offset:-4096
	s_waitcnt vmcnt(11)
	ds_write_b128 v132, v[186:189] offset:32256
	v_lshl_add_u64 v[186:187], v[146:147], 0, v[130:131]
	v_add_co_u32_e32 v186, vcc, s36, v186
	s_nop 1
	v_addc_co_u32_e32 v187, vcc, 0, v187, vcc
	global_load_dwordx4 v[186:189], v[186:187], off
	s_waitcnt vmcnt(11)
	ds_write_b128 v132, v[190:193] offset:36864
	v_lshl_add_u64 v[190:191], v[146:147], 0, v[130:131]
	v_add_co_u32_e32 v190, vcc, s37, v190
	s_nop 1
	v_addc_co_u32_e32 v191, vcc, 0, v191, vcc
	global_load_dwordx4 v[190:193], v[190:191], off offset:-4096
	s_waitcnt vmcnt(11)
	ds_write_b128 v132, v[194:197] offset:41472
	v_lshl_add_u64 v[194:195], v[146:147], 0, v[130:131]
	v_add_co_u32_e32 v194, vcc, s37, v194
	s_nop 1
	v_addc_co_u32_e32 v195, vcc, 0, v195, vcc
	global_load_dwordx4 v[194:197], v[194:195], off
	s_waitcnt vmcnt(11)
	ds_write_b128 v132, v[198:201] offset:46080
	v_lshl_add_u64 v[198:199], v[146:147], 0, v[130:131]
	v_add_co_u32_e32 v198, vcc, s38, v198
	s_nop 1
	v_addc_co_u32_e32 v199, vcc, 0, v199, vcc
	global_load_dwordx4 v[198:201], v[198:199], off offset:-4096
	s_waitcnt vmcnt(11)
	ds_write_b128 v132, v[202:205] offset:50688
	v_lshl_add_u64 v[202:203], v[146:147], 0, v[130:131]
	v_add_co_u32_e32 v202, vcc, s38, v202
	s_nop 1
	v_addc_co_u32_e32 v203, vcc, 0, v203, vcc
	global_load_dwordx4 v[202:205], v[202:203], off
	s_waitcnt lgkmcnt(0)
	s_barrier
;     ...
; #pragma unroll
;     for (int st = 0; st < 4; ++st) {
;       bf16x8 a0 = *(const bf16x8*)(Ab + st * 32);
;       bf16x8 a1 = *(const bf16x8*)(Ab + 32 * LSTR + st * 32);
;       bf16x8 b0 = *(const bf16x8*)(Bb + st * 32);
;       bf16x8 b1 = *(const bf16x8*)(Bb + 32 * LSTR + st * 32);
;       bf16x8 b2 = *(const bf16x8*)(Bb + 64 * LSTR + st * 32);
;       bf16x8 b3 = *(const bf16x8*)(Bb + 96 * LSTR + st * 32);
;       acc[0][0] = mfma32(a0, b0, acc[0][0]);
;       acc[0][1] = mfma32(a0, b1, acc[0][1]);
;       acc[0][2] = mfma32(a0, b2, acc[0][2]);
;       acc[0][3] = mfma32(a0, b3, acc[0][3]);
;       acc[1][0] = mfma32(a1, b0, acc[1][0]);
;       acc[1][1] = mfma32(a1, b1, acc[1][1]);
;       acc[1][2] = mfma32(a1, b2, acc[1][2]);
;       acc[1][3] = mfma32(a1, b3, acc[1][3]);
;     }
;     __builtin_amdgcn_s_setprio(0);
;     __builtin_amdgcn_sched_barrier(0);
;     __syncthreads();
;     GW_STORE()
;     __syncthreads();
	s_cbranch_scc1 .LBB0_1035
	s_setprio 1
	ds_read_b128 v[206:209], v133 offset:0
	ds_read_b128 v[218:221], v156 offset:18432
	ds_read_b128 v[224:227], v156 offset:23040
	ds_read_b128 v[228:231], v156 offset:27648
	ds_read_b128 v[232:235], v156 offset:32256
	ds_read_b128 v[214:217], v133 offset:4608
	s_waitcnt lgkmcnt(4)
	v_mfma_f32_32x32x16_bf16 v[114:129], v[206:209], v[218:221], v[114:129]
	ds_read_b128 v[210:213], v133 offset:32
	ds_read_b128 v[236:239], v156 offset:18464
	s_waitcnt lgkmcnt(5)
	v_mfma_f32_32x32x16_bf16 v[98:113], v[206:209], v[224:227], v[98:113]
	ds_read_b128 v[240:243], v156 offset:23072
	s_waitcnt lgkmcnt(5)
	v_mfma_f32_32x32x16_bf16 v[82:97], v[206:209], v[228:231], v[82:97]
	ds_read_b128 v[244:247], v156 offset:27680
	s_waitcnt lgkmcnt(5)
	v_mfma_f32_32x32x16_bf16 v[66:81], v[206:209], v[232:235], v[66:81]
	ds_read_b128 v[248:251], v156 offset:32288
	s_waitcnt lgkmcnt(5)
	v_mfma_f32_32x32x16_bf16 v[50:65], v[214:217], v[218:221], v[50:65]
	v_mfma_f32_32x32x16_bf16 v[34:49], v[214:217], v[224:227], v[34:49]
	v_mfma_f32_32x32x16_bf16 v[18:33], v[214:217], v[228:231], v[18:33]
	v_mfma_f32_32x32x16_bf16 v[2:17], v[214:217], v[232:235], v[2:17]
	ds_read_b128 v[214:217], v133 offset:4640
	s_waitcnt lgkmcnt(4)
	v_mfma_f32_32x32x16_bf16 v[114:129], v[210:213], v[236:239], v[114:129]
	ds_read_b128 v[206:209], v133 offset:64
	ds_read_b128 v[218:221], v156 offset:18496
	s_waitcnt lgkmcnt(5)
	v_mfma_f32_32x32x16_bf16 v[98:113], v[210:213], v[240:243], v[98:113]
	ds_read_b128 v[224:227], v156 offset:23104
	s_waitcnt lgkmcnt(5)
	v_mfma_f32_32x32x16_bf16 v[82:97], v[210:213], v[244:247], v[82:97]
	ds_read_b128 v[228:231], v156 offset:27712
	s_waitcnt lgkmcnt(5)
	v_mfma_f32_32x32x16_bf16 v[66:81], v[210:213], v[248:251], v[66:81]
	ds_read_b128 v[232:235], v156 offset:32320
	s_waitcnt lgkmcnt(5)
	v_mfma_f32_32x32x16_bf16 v[50:65], v[214:217], v[236:239], v[50:65]
	v_mfma_f32_32x32x16_bf16 v[34:49], v[214:217], v[240:243], v[34:49]
	v_mfma_f32_32x32x16_bf16 v[18:33], v[214:217], v[244:247], v[18:33]
	v_mfma_f32_32x32x16_bf16 v[2:17], v[214:217], v[248:251], v[2:17]
	ds_read_b128 v[214:217], v133 offset:4672
	s_waitcnt lgkmcnt(4)
	v_mfma_f32_32x32x16_bf16 v[114:129], v[206:209], v[218:221], v[114:129]
	ds_read_b128 v[210:213], v133 offset:96
	ds_read_b128 v[236:239], v156 offset:18528
	s_waitcnt lgkmcnt(5)
	v_mfma_f32_32x32x16_bf16 v[98:113], v[206:209], v[224:227], v[98:113]
	ds_read_b128 v[240:243], v156 offset:23136
	s_waitcnt lgkmcnt(5)
	v_mfma_f32_32x32x16_bf16 v[82:97], v[206:209], v[228:231], v[82:97]
	ds_read_b128 v[244:247], v156 offset:27744
	s_waitcnt lgkmcnt(5)
	v_mfma_f32_32x32x16_bf16 v[66:81], v[206:209], v[232:235], v[66:81]
	ds_read_b128 v[248:251], v156 offset:32352
	s_waitcnt lgkmcnt(5)
	v_mfma_f32_32x32x16_bf16 v[50:65], v[214:217], v[218:221], v[50:65]
	v_mfma_f32_32x32x16_bf16 v[34:49], v[214:217], v[224:227], v[34:49]
	v_mfma_f32_32x32x16_bf16 v[18:33], v[214:217], v[228:231], v[18:33]
	v_mfma_f32_32x32x16_bf16 v[2:17], v[214:217], v[232:235], v[2:17]
	ds_read_b128 v[214:217], v133 offset:4704
	s_waitcnt lgkmcnt(4)
	v_mfma_f32_32x32x16_bf16 v[114:129], v[210:213], v[236:239], v[114:129]
	s_waitcnt lgkmcnt(3)
	v_mfma_f32_32x32x16_bf16 v[98:113], v[210:213], v[240:243], v[98:113]
	s_waitcnt lgkmcnt(2)
	v_mfma_f32_32x32x16_bf16 v[82:97], v[210:213], v[244:247], v[82:97]
	s_waitcnt lgkmcnt(1)
	v_mfma_f32_32x32x16_bf16 v[66:81], v[210:213], v[248:251], v[66:81]
	s_waitcnt lgkmcnt(0)
	v_mfma_f32_32x32x16_bf16 v[50:65], v[214:217], v[236:239], v[50:65]
	v_mfma_f32_32x32x16_bf16 v[34:49], v[214:217], v[240:243], v[34:49]
	v_mfma_f32_32x32x16_bf16 v[18:33], v[214:217], v[244:247], v[18:33]
	v_mfma_f32_32x32x16_bf16 v[2:17], v[214:217], v[248:251], v[2:17]
	s_setprio 0
	v_lshl_add_u64 v[146:147], v[146:147], 0, s[8:9]
	v_lshl_add_u64 v[148:149], v[148:149], 0, s[10:11]
	v_lshl_add_u64 v[150:151], v[150:151], 0, s[10:11]
	v_lshl_add_u64 v[152:153], v[152:153], 0, s[10:11]
	v_lshl_add_u64 v[154:155], v[154:155], 0, s[10:11]
	s_barrier
	s_waitcnt vmcnt(11)
	ds_write_b128 v132, v[158:161]
	s_waitcnt vmcnt(10)
	ds_write_b128 v132, v[162:165] offset:4608
	s_waitcnt vmcnt(9)
	ds_write_b128 v132, v[166:169] offset:9216
	s_waitcnt vmcnt(8)
	ds_write_b128 v132, v[170:173] offset:13824
	s_waitcnt vmcnt(7)
	ds_write_b128 v132, v[174:177] offset:18432
	s_waitcnt vmcnt(6)
	ds_write_b128 v132, v[178:181] offset:23040
	s_waitcnt vmcnt(5)
	ds_write_b128 v132, v[182:185] offset:27648
	s_waitcnt vmcnt(4)
	ds_write_b128 v132, v[186:189] offset:32256
	s_waitcnt vmcnt(3)
	ds_write_b128 v132, v[190:193] offset:36864
	s_waitcnt vmcnt(2)
	ds_write_b128 v132, v[194:197] offset:41472
	s_waitcnt vmcnt(1)
	ds_write_b128 v132, v[198:201] offset:46080
	s_waitcnt vmcnt(0)
	ds_write_b128 v132, v[202:205] offset:50688
	s_waitcnt lgkmcnt(0)
	s_barrier
;     ...
; #pragma unroll
;     for (int st = 0; st < 4; ++st) {
;       bf16x8 a0 = *(const bf16x8*)(Ab + st * 32);
;       bf16x8 a1 = *(const bf16x8*)(Ab + 32 * LSTR + st * 32);
;       bf16x8 b0 = *(const bf16x8*)(Bb + st * 32);
;       bf16x8 b1 = *(const bf16x8*)(Bb + 32 * LSTR + st * 32);
;       bf16x8 b2 = *(const bf16x8*)(Bb + 64 * LSTR + st * 32);
;       bf16x8 b3 = *(const bf16x8*)(Bb + 96 * LSTR + st * 32);
;       acc[0][0] = mfma32(a0, b0, acc[0][0]);
;       acc[0][1] = mfma32(a0, b1, acc[0][1]);
;       acc[0][2] = mfma32(a0, b2, acc[0][2]);
;       acc[0][3] = mfma32(a0, b3, acc[0][3]);
;       acc[1][0] = mfma32(a1, b0, acc[1][0]);
;       acc[1][1] = mfma32(a1, b1, acc[1][1]);
;       acc[1][2] = mfma32(a1, b2, acc[1][2]);
;       acc[1][3] = mfma32(a1, b3, acc[1][3]);
;     }
;     __builtin_amdgcn_s_setprio(0);
; __device__ __forceinline__ void expert1_tile(const Params& P, int e, int mt, int ntw, char* smem) {
;     ...
;   float* cs = (float*)smem;
;   int tid_ = threadIdx.x;
;   asm volatile("" : "+v"(tid_));
;   const int lane = tid_ & 63, wave = tid_ >> 6;
;   const int r = 32 * wave + (lane & 31), part = lane >> 5;
; #pragma unroll 1
;   for (int h = 0; h < 2; ++h) {
;     wide_acc_to_lds(acc, cs, h);
;     u16* dst = WSP(u16, OFF_HID) + ((size_t)e * EROWS + mt * 128 + r) * 2048 + (ntw * 2 + h) * 64 + part * 32;
	v_add_co_u32_e32 v154, vcc, 0x780000, v136
	s_nop 0
	s_nop 0
	s_nop 0
	v_addc_co_u32_e32 v155, vcc, 0, v137, vcc
	v_add_co_u32_e32 v162, vcc, 0x781000, v136
	s_mov_b32 s18, 0
	s_nop 0
	v_addc_co_u32_e32 v163, vcc, 0, v137, vcc
	s_nop 0
	v_add_co_u32_e32 v154, vcc, 0x782000, v136
	s_nop 1
	v_addc_co_u32_e32 v155, vcc, 0, v137, vcc
	v_add_co_u32_e32 v170, vcc, 0x783000, v136
	s_nop 1
	v_addc_co_u32_e32 v171, vcc, 0, v137, vcc
	s_nop 0
	v_add_co_u32_e32 v154, vcc, 0x784000, v136
	s_nop 1
	v_addc_co_u32_e32 v155, vcc, 0, v137, vcc
	v_add_co_u32_e32 v178, vcc, 0x785000, v136
	s_nop 1
	v_addc_co_u32_e32 v179, vcc, 0, v137, vcc
	s_nop 0
	v_add_co_u32_e32 v154, vcc, 0x786000, v136
	s_nop 1
	v_addc_co_u32_e32 v155, vcc, 0, v137, vcc
	v_add_co_u32_e32 v136, vcc, 0x787000, v136
	s_nop 1
	v_addc_co_u32_e32 v137, vcc, 0, v137, vcc
	s_setprio 1
	ds_read_b128 v[190:193], v133 offset:0
	ds_read_b128 v[202:205], v156 offset:18432
	ds_read_b128 v[206:209], v156 offset:23040
	ds_read_b128 v[210:213], v156 offset:27648
	ds_read_b128 v[214:217], v156 offset:32256
	ds_read_b128 v[198:201], v133 offset:4608
	s_waitcnt lgkmcnt(4)
	v_mfma_f32_32x32x16_bf16 v[114:129], v[190:193], v[202:205], v[114:129]
	ds_read_b128 v[194:197], v133 offset:32
	ds_read_b128 v[218:221], v156 offset:18464
	s_waitcnt lgkmcnt(5)
	v_mfma_f32_32x32x16_bf16 v[98:113], v[190:193], v[206:209], v[98:113]
	ds_read_b128 v[224:227], v156 offset:23072
	s_waitcnt lgkmcnt(5)
	v_mfma_f32_32x32x16_bf16 v[82:97], v[190:193], v[210:213], v[82:97]
	ds_read_b128 v[228:231], v156 offset:27680
	s_waitcnt lgkmcnt(5)
	v_mfma_f32_32x32x16_bf16 v[66:81], v[190:193], v[214:217], v[66:81]
	ds_read_b128 v[232:235], v156 offset:32288
	s_waitcnt lgkmcnt(5)
	v_mfma_f32_32x32x16_bf16 v[50:65], v[198:201], v[202:205], v[50:65]
	v_mfma_f32_32x32x16_bf16 v[34:49], v[198:201], v[206:209], v[34:49]
	v_mfma_f32_32x32x16_bf16 v[18:33], v[198:201], v[210:213], v[18:33]
	v_mfma_f32_32x32x16_bf16 v[2:17], v[198:201], v[214:217], v[2:17]
	ds_read_b128 v[198:201], v133 offset:4640
	s_waitcnt lgkmcnt(4)
	v_mfma_f32_32x32x16_bf16 v[114:129], v[194:197], v[218:221], v[114:129]
	ds_read_b128 v[190:193], v133 offset:64
	ds_read_b128 v[202:205], v156 offset:18496
	s_waitcnt lgkmcnt(5)
	v_mfma_f32_32x32x16_bf16 v[98:113], v[194:197], v[224:227], v[98:113]
	ds_read_b128 v[206:209], v156 offset:23104
	s_waitcnt lgkmcnt(5)
	v_mfma_f32_32x32x16_bf16 v[82:97], v[194:197], v[228:231], v[82:97]
	ds_read_b128 v[210:213], v156 offset:27712
	s_waitcnt lgkmcnt(5)
	v_mfma_f32_32x32x16_bf16 v[66:81], v[194:197], v[232:235], v[66:81]
	ds_read_b128 v[214:217], v156 offset:32320
	s_waitcnt lgkmcnt(5)
	v_mfma_f32_32x32x16_bf16 v[50:65], v[198:201], v[218:221], v[50:65]
	v_mfma_f32_32x32x16_bf16 v[34:49], v[198:201], v[224:227], v[34:49]
	v_mfma_f32_32x32x16_bf16 v[18:33], v[198:201], v[228:231], v[18:33]
	v_mfma_f32_32x32x16_bf16 v[2:17], v[198:201], v[232:235], v[2:17]
	ds_read_b128 v[198:201], v133 offset:4672
	s_waitcnt lgkmcnt(4)
	v_mfma_f32_32x32x16_bf16 v[114:129], v[190:193], v[202:205], v[114:129]
	ds_read_b128 v[194:197], v133 offset:96
	ds_read_b128 v[218:221], v156 offset:18528
	s_waitcnt lgkmcnt(5)
	v_mfma_f32_32x32x16_bf16 v[98:113], v[190:193], v[206:209], v[98:113]
	ds_read_b128 v[224:227], v156 offset:23136
	s_waitcnt lgkmcnt(5)
	v_mfma_f32_32x32x16_bf16 v[82:97], v[190:193], v[210:213], v[82:97]
	ds_read_b128 v[228:231], v156 offset:27744
	s_waitcnt lgkmcnt(5)
	v_mfma_f32_32x32x16_bf16 v[66:81], v[190:193], v[214:217], v[66:81]
	ds_read_b128 v[232:235], v156 offset:32352
	s_waitcnt lgkmcnt(5)
	v_mfma_f32_32x32x16_bf16 v[50:65], v[198:201], v[202:205], v[50:65]
	v_mfma_f32_32x32x16_bf16 v[34:49], v[198:201], v[206:209], v[34:49]
	v_mfma_f32_32x32x16_bf16 v[18:33], v[198:201], v[210:213], v[18:33]
	v_mfma_f32_32x32x16_bf16 v[2:17], v[198:201], v[214:217], v[2:17]
	ds_read_b128 v[198:201], v133 offset:4704
	s_waitcnt lgkmcnt(4)
	v_mfma_f32_32x32x16_bf16 v[114:129], v[194:197], v[218:221], v[114:129]
	s_waitcnt lgkmcnt(3)
	v_mfma_f32_32x32x16_bf16 v[98:113], v[194:197], v[224:227], v[98:113]
	s_waitcnt lgkmcnt(2)
	v_mfma_f32_32x32x16_bf16 v[82:97], v[194:197], v[228:231], v[82:97]
	s_waitcnt lgkmcnt(1)
	v_mfma_f32_32x32x16_bf16 v[66:81], v[194:197], v[232:235], v[66:81]
	s_waitcnt lgkmcnt(0)
	v_mfma_f32_32x32x16_bf16 v[50:65], v[198:201], v[218:221], v[50:65]
	v_mfma_f32_32x32x16_bf16 v[34:49], v[198:201], v[224:227], v[34:49]
	v_mfma_f32_32x32x16_bf16 v[18:33], v[198:201], v[228:231], v[18:33]
	v_mfma_f32_32x32x16_bf16 v[2:17], v[198:201], v[232:235], v[2:17]
	s_setprio 0
	v_mov_b32_e32 v130, v134
	s_barrier
	s_waitcnt lgkmcnt(0)
	s_mul_hi_i32 s13, s14, 0x1100
	v_ashrrev_i32_e32 v132, 1, v130
	s_mulk_i32 s14, 0x1100
	v_bfi_b32 v132, s39, v132, v130
	s_add_u32 s14, s14, s16
	s_addc_u32 s15, s13, s17
	v_ashrrev_i32_e32 v133, 31, v132
	v_lshl_add_u64 v[136:137], s[14:15], 0, v[132:133]
	v_and_b32_e32 v130, 32, v130
	v_lshlrev_b64 v[136:137], 12, v[136:137]
	v_mul_lo_u32 v132, v132, s22
	v_lshl_add_u32 v138, v130, 2, v132
	v_lshl_add_u64 v[132:133], s[4:5], 0, v[136:137]
	v_lshlrev_b32_e32 v130, 1, v130
	s_lshl_b32 s16, s12, 7
	v_lshl_add_u64 v[132:133], v[132:133], 0, v[130:131]
	s_mov_b64 s[12:13], -1
	s_branch .LBB0_1038

;     ...
;   for (int kt = 0; kt < nk; ++kt) {
;     const int kn = (kt + 1 < nk) ? kt + 1 : kt;
;     GW_LOAD2(kn * 64, kn * bkstep)
;     __builtin_amdgcn_sched_barrier(0);
;     __builtin_amdgcn_s_setprio(1);
; #pragma unroll
;     for (int st = 0; st < 4; ++st) {
;       bf16x8 a0 = *(const bf16x8*)(Ab + st * 32);
;       bf16x8 a1 = *(const bf16x8*)(Ab + 32 * LSTR + st * 32);
;       bf16x8 b0 = *(const bf16x8*)(Bb + st * 32);
;       bf16x8 b1 = *(const bf16x8*)(Bb + 32 * LSTR + st * 32);
;       bf16x8 b2 = *(const bf16x8*)(Bb + 64 * LSTR + st * 32);
;       bf16x8 b3 = *(const bf16x8*)(Bb + 96 * LSTR + st * 32);
;       acc[0][0] = mfma32(a0, b0, acc[0][0]);
;       acc[0][1] = mfma32(a0, b1, acc[0][1]);
;       acc[0][2] = mfma32(a0, b2, acc[0][2]);
;       acc[0][3] = mfma32(a0, b3, acc[0][3]);
;       acc[1][0] = mfma32(a1, b0, acc[1][0]);
;       acc[1][1] = mfma32(a1, b1, acc[1][1]);
;       acc[1][2] = mfma32(a1, b2, acc[1][2]);
;       acc[1][3] = mfma32(a1, b3, acc[1][3]);
;     }
;     __builtin_amdgcn_s_setprio(0);
;     __builtin_amdgcn_sched_barrier(0);
;     __syncthreads();
;     GW_STORE()
;     __syncthreads();
.LBB0_1113:
	s_setprio 1
	ds_read_b128 v[200:203], v133 offset:0
	ds_read_b128 v[212:215], v150 offset:18432
	ds_read_b128 v[216:219], v150 offset:23040
	ds_read_b128 v[224:227], v150 offset:27648
	ds_read_b128 v[228:231], v150 offset:32256
	ds_read_b128 v[208:211], v133 offset:4608
	s_waitcnt lgkmcnt(4)
	v_mfma_f32_32x32x16_bf16 v[114:129], v[200:203], v[212:215], v[114:129]
	ds_read_b128 v[204:207], v133 offset:32
	ds_read_b128 v[232:235], v150 offset:18464
	s_waitcnt lgkmcnt(5)
	v_mfma_f32_32x32x16_bf16 v[98:113], v[200:203], v[216:219], v[98:113]
	ds_read_b128 v[236:239], v150 offset:23072
	s_waitcnt lgkmcnt(5)
	v_mfma_f32_32x32x16_bf16 v[82:97], v[200:203], v[224:227], v[82:97]
	ds_read_b128 v[240:243], v150 offset:27680
	s_waitcnt lgkmcnt(5)
	v_mfma_f32_32x32x16_bf16 v[66:81], v[200:203], v[228:231], v[66:81]
	ds_read_b128 v[244:247], v150 offset:32288
	s_waitcnt lgkmcnt(5)
	v_mfma_f32_32x32x16_bf16 v[50:65], v[208:211], v[212:215], v[50:65]
	v_mfma_f32_32x32x16_bf16 v[34:49], v[208:211], v[216:219], v[34:49]
	v_mfma_f32_32x32x16_bf16 v[18:33], v[208:211], v[224:227], v[18:33]
	v_mfma_f32_32x32x16_bf16 v[2:17], v[208:211], v[228:231], v[2:17]
	ds_read_b128 v[208:211], v133 offset:4640
	s_waitcnt lgkmcnt(4)
	v_mfma_f32_32x32x16_bf16 v[114:129], v[204:207], v[232:235], v[114:129]
	ds_read_b128 v[200:203], v133 offset:64
	ds_read_b128 v[212:215], v150 offset:18496
	s_waitcnt lgkmcnt(5)
	v_mfma_f32_32x32x16_bf16 v[98:113], v[204:207], v[236:239], v[98:113]
	ds_read_b128 v[216:219], v150 offset:23104
	s_waitcnt lgkmcnt(5)
	v_mfma_f32_32x32x16_bf16 v[82:97], v[204:207], v[240:243], v[82:97]
	ds_read_b128 v[224:227], v150 offset:27712
	s_waitcnt lgkmcnt(5)
	v_mfma_f32_32x32x16_bf16 v[66:81], v[204:207], v[244:247], v[66:81]
	ds_read_b128 v[228:231], v150 offset:32320
	s_waitcnt lgkmcnt(5)
	v_mfma_f32_32x32x16_bf16 v[50:65], v[208:211], v[232:235], v[50:65]
	v_mfma_f32_32x32x16_bf16 v[34:49], v[208:211], v[236:239], v[34:49]
	v_mfma_f32_32x32x16_bf16 v[18:33], v[208:211], v[240:243], v[18:33]
	v_mfma_f32_32x32x16_bf16 v[2:17], v[208:211], v[244:247], v[2:17]
	ds_read_b128 v[208:211], v133 offset:4672
	s_waitcnt lgkmcnt(4)
	v_mfma_f32_32x32x16_bf16 v[114:129], v[200:203], v[212:215], v[114:129]
	ds_read_b128 v[204:207], v133 offset:96
	ds_read_b128 v[232:235], v150 offset:18528
	s_waitcnt lgkmcnt(5)
	v_mfma_f32_32x32x16_bf16 v[98:113], v[200:203], v[216:219], v[98:113]
	ds_read_b128 v[236:239], v150 offset:23136
	s_waitcnt lgkmcnt(5)
	v_mfma_f32_32x32x16_bf16 v[82:97], v[200:203], v[224:227], v[82:97]
	ds_read_b128 v[240:243], v150 offset:27744
	s_waitcnt lgkmcnt(5)
	v_mfma_f32_32x32x16_bf16 v[66:81], v[200:203], v[228:231], v[66:81]
	ds_read_b128 v[244:247], v150 offset:32352
	s_waitcnt lgkmcnt(5)
	v_mfma_f32_32x32x16_bf16 v[50:65], v[208:211], v[212:215], v[50:65]
	v_mfma_f32_32x32x16_bf16 v[34:49], v[208:211], v[216:219], v[34:49]
	v_mfma_f32_32x32x16_bf16 v[18:33], v[208:211], v[224:227], v[18:33]
	v_mfma_f32_32x32x16_bf16 v[2:17], v[208:211], v[228:231], v[2:17]
	ds_read_b128 v[208:211], v133 offset:4704
	s_waitcnt lgkmcnt(4)
	v_mfma_f32_32x32x16_bf16 v[114:129], v[204:207], v[232:235], v[114:129]
	s_waitcnt lgkmcnt(3)
	v_mfma_f32_32x32x16_bf16 v[98:113], v[204:207], v[236:239], v[98:113]
	s_waitcnt lgkmcnt(2)
	v_mfma_f32_32x32x16_bf16 v[82:97], v[204:207], v[240:243], v[82:97]
	s_waitcnt lgkmcnt(1)
	v_mfma_f32_32x32x16_bf16 v[66:81], v[204:207], v[244:247], v[66:81]
	s_waitcnt lgkmcnt(0)
	v_mfma_f32_32x32x16_bf16 v[50:65], v[208:211], v[232:235], v[50:65]
	v_mfma_f32_32x32x16_bf16 v[34:49], v[208:211], v[236:239], v[34:49]
	v_mfma_f32_32x32x16_bf16 v[18:33], v[208:211], v[240:243], v[18:33]
	v_mfma_f32_32x32x16_bf16 v[2:17], v[208:211], v[244:247], v[2:17]
	s_setprio 0
	s_add_i32 s15, s15, -1
	v_lshl_add_u64 v[146:147], v[146:147], 0, s[4:5]
	s_cmp_lg_u32 s15, 0
	v_lshl_add_u64 v[148:149], v[148:149], 0, s[10:11]
	s_barrier
	s_waitcnt vmcnt(11)
	ds_write_b128 v132, v[152:155]
	v_lshl_add_u64 v[152:153], v[148:149], 0, v[130:131]
	v_add_co_u32_e32 v152, vcc, s37, v152
	s_nop 1
	v_addc_co_u32_e32 v153, vcc, 0, v153, vcc
	global_load_dwordx4 v[152:155], v[152:153], off offset:384
	s_waitcnt vmcnt(11)
	ds_write_b128 v132, v[156:159] offset:4608
	v_lshl_add_u64 v[156:157], v[148:149], 0, v[130:131]
	v_add_co_u32_e32 v156, vcc, s38, v156
	s_nop 1
	v_addc_co_u32_e32 v157, vcc, 0, v157, vcc
	global_load_dwordx4 v[156:159], v[156:157], off offset:384
	s_waitcnt vmcnt(11)
	ds_write_b128 v132, v[160:163] offset:9216
	v_lshl_add_u64 v[160:161], v[148:149], 0, v[130:131]
	v_add_co_u32_e32 v160, vcc, s39, v160
	s_nop 1
	v_addc_co_u32_e32 v161, vcc, 0, v161, vcc
	global_load_dwordx4 v[160:163], v[160:161], off offset:384
	s_waitcnt vmcnt(11)
	ds_write_b128 v132, v[164:167] offset:13824
	v_lshl_add_u64 v[164:165], v[148:149], 0, v[130:131]
	v_add_co_u32_e32 v164, vcc, s40, v164
	s_nop 1
	v_addc_co_u32_e32 v165, vcc, 0, v165, vcc
	global_load_dwordx4 v[164:167], v[164:165], off offset:384
	s_waitcnt vmcnt(11)
	ds_write_b128 v132, v[168:171] offset:18432
	v_lshl_add_u64 v[168:169], v[146:147], 0, v[130:131]
	v_add_co_u32_e32 v168, vcc, s41, v168
	s_nop 1
	v_addc_co_u32_e32 v169, vcc, 0, v169, vcc
	global_load_dwordx4 v[168:171], v[168:169], off offset:-4096
	s_waitcnt vmcnt(11)
	ds_write_b128 v132, v[172:175] offset:23040
	v_lshl_add_u64 v[172:173], v[146:147], 0, v[130:131]
	v_add_co_u32_e32 v172, vcc, s41, v172
	s_nop 1
	v_addc_co_u32_e32 v173, vcc, 0, v173, vcc
	global_load_dwordx4 v[172:175], v[172:173], off
	s_waitcnt vmcnt(11)
;     ...
;     GW_LOAD2(kn * 64, kn * bkstep)
;     __builtin_amdgcn_sched_barrier(0);
;     __builtin_amdgcn_s_setprio(1);
; #pragma unroll
;     for (int st = 0; st < 4; ++st) {
;       bf16x8 a0 = *(const bf16x8*)(Ab + st * 32);
;       bf16x8 a1 = *(const bf16x8*)(Ab + 32 * LSTR + st * 32);
;       bf16x8 b0 = *(const bf16x8*)(Bb + st * 32);
;       bf16x8 b1 = *(const bf16x8*)(Bb + 32 * LSTR + st * 32);
;       bf16x8 b2 = *(const bf16x8*)(Bb + 64 * LSTR + st * 32);
;       bf16x8 b3 = *(const bf16x8*)(Bb + 96 * LSTR + st * 32);
;       acc[0][0] = mfma32(a0, b0, acc[0][0]);
;       acc[0][1] = mfma32(a0, b1, acc[0][1]);
;       acc[0][2] = mfma32(a0, b2, acc[0][2]);
;       acc[0][3] = mfma32(a0, b3, acc[0][3]);
;       acc[1][0] = mfma32(a1, b0, acc[1][0]);
;       acc[1][1] = mfma32(a1, b1, acc[1][1]);
;       acc[1][2] = mfma32(a1, b2, acc[1][2]);
;       acc[1][3] = mfma32(a1, b3, acc[1][3]);
;     }
;     __builtin_amdgcn_s_setprio(0);
;     __builtin_amdgcn_sched_barrier(0);
;     __syncthreads();
;     GW_STORE()
;     __syncthreads();
	ds_write_b128 v132, v[176:179] offset:27648
	v_lshl_add_u64 v[176:177], v[146:147], 0, v[130:131]
	v_add_co_u32_e32 v176, vcc, s42, v176
	s_nop 1
	v_addc_co_u32_e32 v177, vcc, 0, v177, vcc
	global_load_dwordx4 v[176:179], v[176:177], off offset:-4096
	s_waitcnt vmcnt(11)
	ds_write_b128 v132, v[180:183] offset:32256
	v_lshl_add_u64 v[180:181], v[146:147], 0, v[130:131]
	v_add_co_u32_e32 v180, vcc, s42, v180
	s_nop 1
	v_addc_co_u32_e32 v181, vcc, 0, v181, vcc
	global_load_dwordx4 v[180:183], v[180:181], off
	s_waitcnt vmcnt(11)
	ds_write_b128 v132, v[184:187] offset:36864
	v_lshl_add_u64 v[184:185], v[146:147], 0, v[130:131]
	v_add_co_u32_e32 v184, vcc, s43, v184
	s_nop 1
	v_addc_co_u32_e32 v185, vcc, 0, v185, vcc
	global_load_dwordx4 v[184:187], v[184:185], off offset:-4096
	s_waitcnt vmcnt(11)
	ds_write_b128 v132, v[188:191] offset:41472
	v_lshl_add_u64 v[188:189], v[146:147], 0, v[130:131]
	v_add_co_u32_e32 v188, vcc, s43, v188
	s_nop 1
	v_addc_co_u32_e32 v189, vcc, 0, v189, vcc
	global_load_dwordx4 v[188:191], v[188:189], off
	s_waitcnt vmcnt(11)
	ds_write_b128 v132, v[192:195] offset:46080
	v_lshl_add_u64 v[192:193], v[146:147], 0, v[130:131]
	v_add_co_u32_e32 v192, vcc, s44, v192
	s_nop 1
	v_addc_co_u32_e32 v193, vcc, 0, v193, vcc
	global_load_dwordx4 v[192:195], v[192:193], off offset:-4096
	s_waitcnt vmcnt(11)
	ds_write_b128 v132, v[196:199] offset:50688
	v_lshl_add_u64 v[196:197], v[146:147], 0, v[130:131]
	v_add_co_u32_e32 v196, vcc, s44, v196
	s_nop 1
	v_addc_co_u32_e32 v197, vcc, 0, v197, vcc
	global_load_dwordx4 v[196:199], v[196:197], off
	s_waitcnt lgkmcnt(0)
	s_barrier
	s_cbranch_scc1 .LBB0_1113
	s_setprio 1
	ds_read_b128 v[200:203], v133 offset:0
	ds_read_b128 v[212:215], v150 offset:18432
	ds_read_b128 v[216:219], v150 offset:23040
	ds_read_b128 v[224:227], v150 offset:27648
	ds_read_b128 v[228:231], v150 offset:32256
	ds_read_b128 v[208:211], v133 offset:4608
	s_waitcnt lgkmcnt(4)
	v_mfma_f32_32x32x16_bf16 v[114:129], v[200:203], v[212:215], v[114:129]
	ds_read_b128 v[204:207], v133 offset:32
	ds_read_b128 v[232:235], v150 offset:18464
	s_waitcnt lgkmcnt(5)
	v_mfma_f32_32x32x16_bf16 v[98:113], v[200:203], v[216:219], v[98:113]
	ds_read_b128 v[236:239], v150 offset:23072
	s_waitcnt lgkmcnt(5)
	v_mfma_f32_32x32x16_bf16 v[82:97], v[200:203], v[224:227], v[82:97]
	ds_read_b128 v[240:243], v150 offset:27680
	s_waitcnt lgkmcnt(5)
	v_mfma_f32_32x32x16_bf16 v[66:81], v[200:203], v[228:231], v[66:81]
	ds_read_b128 v[244:247], v150 offset:32288
	s_waitcnt lgkmcnt(5)
	v_mfma_f32_32x32x16_bf16 v[50:65], v[208:211], v[212:215], v[50:65]
	v_mfma_f32_32x32x16_bf16 v[34:49], v[208:211], v[216:219], v[34:49]
	v_mfma_f32_32x32x16_bf16 v[18:33], v[208:211], v[224:227], v[18:33]
	v_mfma_f32_32x32x16_bf16 v[2:17], v[208:211], v[228:231], v[2:17]
	ds_read_b128 v[208:211], v133 offset:4640
	s_waitcnt lgkmcnt(4)
	v_mfma_f32_32x32x16_bf16 v[114:129], v[204:207], v[232:235], v[114:129]
	ds_read_b128 v[200:203], v133 offset:64
	ds_read_b128 v[212:215], v150 offset:18496
	s_waitcnt lgkmcnt(5)
	v_mfma_f32_32x32x16_bf16 v[98:113], v[204:207], v[236:239], v[98:113]
	ds_read_b128 v[216:219], v150 offset:23104
	s_waitcnt lgkmcnt(5)
	v_mfma_f32_32x32x16_bf16 v[82:97], v[204:207], v[240:243], v[82:97]
	ds_read_b128 v[224:227], v150 offset:27712
	s_waitcnt lgkmcnt(5)
	v_mfma_f32_32x32x16_bf16 v[66:81], v[204:207], v[244:247], v[66:81]
	ds_read_b128 v[228:231], v150 offset:32320
	s_waitcnt lgkmcnt(5)
	v_mfma_f32_32x32x16_bf16 v[50:65], v[208:211], v[232:235], v[50:65]
	v_mfma_f32_32x32x16_bf16 v[34:49], v[208:211], v[236:239], v[34:49]
	v_mfma_f32_32x32x16_bf16 v[18:33], v[208:211], v[240:243], v[18:33]
	v_mfma_f32_32x32x16_bf16 v[2:17], v[208:211], v[244:247], v[2:17]
	ds_read_b128 v[208:211], v133 offset:4672
	s_waitcnt lgkmcnt(4)
	v_mfma_f32_32x32x16_bf16 v[114:129], v[200:203], v[212:215], v[114:129]
	ds_read_b128 v[204:207], v133 offset:96
	ds_read_b128 v[232:235], v150 offset:18528
	s_waitcnt lgkmcnt(5)
	v_mfma_f32_32x32x16_bf16 v[98:113], v[200:203], v[216:219], v[98:113]
	ds_read_b128 v[236:239], v150 offset:23136
	s_waitcnt lgkmcnt(5)
	v_mfma_f32_32x32x16_bf16 v[82:97], v[200:203], v[224:227], v[82:97]
	ds_read_b128 v[240:243], v150 offset:27744
	s_waitcnt lgkmcnt(5)
	v_mfma_f32_32x32x16_bf16 v[66:81], v[200:203], v[228:231], v[66:81]
	ds_read_b128 v[244:247], v150 offset:32352
	s_waitcnt lgkmcnt(5)
	v_mfma_f32_32x32x16_bf16 v[50:65], v[208:211], v[212:215], v[50:65]
	v_mfma_f32_32x32x16_bf16 v[34:49], v[208:211], v[216:219], v[34:49]
	v_mfma_f32_32x32x16_bf16 v[18:33], v[208:211], v[224:227], v[18:33]
	v_mfma_f32_32x32x16_bf16 v[2:17], v[208:211], v[228:231], v[2:17]
	ds_read_b128 v[208:211], v133 offset:4704
	s_waitcnt lgkmcnt(4)
	v_mfma_f32_32x32x16_bf16 v[114:129], v[204:207], v[232:235], v[114:129]
	s_waitcnt lgkmcnt(3)
	v_mfma_f32_32x32x16_bf16 v[98:113], v[204:207], v[236:239], v[98:113]
	s_waitcnt lgkmcnt(2)
	v_mfma_f32_32x32x16_bf16 v[82:97], v[204:207], v[240:243], v[82:97]
	s_waitcnt lgkmcnt(1)
	v_mfma_f32_32x32x16_bf16 v[66:81], v[204:207], v[244:247], v[66:81]
	s_waitcnt lgkmcnt(0)
	v_mfma_f32_32x32x16_bf16 v[50:65], v[208:211], v[232:235], v[50:65]
	v_mfma_f32_32x32x16_bf16 v[34:49], v[208:211], v[236:239], v[34:49]
	v_mfma_f32_32x32x16_bf16 v[18:33], v[208:211], v[240:243], v[18:33]
	v_mfma_f32_32x32x16_bf16 v[2:17], v[208:211], v[244:247], v[2:17]
	s_setprio 0
	v_lshl_add_u64 v[146:147], v[146:147], 0, s[4:5]
	v_lshl_add_u64 v[148:149], v[148:149], 0, s[10:11]
	s_barrier
;     ...
; #pragma unroll
;     for (int st = 0; st < 4; ++st) {
;       bf16x8 a0 = *(const bf16x8*)(Ab + st * 32);
;       bf16x8 a1 = *(const bf16x8*)(Ab + 32 * LSTR + st * 32);
;       bf16x8 b0 = *(const bf16x8*)(Bb + st * 32);
;       bf16x8 b1 = *(const bf16x8*)(Bb + 32 * LSTR + st * 32);
;       bf16x8 b2 = *(const bf16x8*)(Bb + 64 * LSTR + st * 32);
;       bf16x8 b3 = *(const bf16x8*)(Bb + 96 * LSTR + st * 32);
;       acc[0][0] = mfma32(a0, b0, acc[0][0]);
;       acc[0][1] = mfma32(a0, b1, acc[0][1]);
;       acc[0][2] = mfma32(a0, b2, acc[0][2]);
;       acc[0][3] = mfma32(a0, b3, acc[0][3]);
;       acc[1][0] = mfma32(a1, b0, acc[1][0]);
;       acc[1][1] = mfma32(a1, b1, acc[1][1]);
;       acc[1][2] = mfma32(a1, b2, acc[1][2]);
;       acc[1][3] = mfma32(a1, b3, acc[1][3]);
;     }
;     __builtin_amdgcn_s_setprio(0);
;     ...
;     __syncthreads();
;     GW_STORE()
;     __syncthreads();
	s_waitcnt vmcnt(11)
	ds_write_b128 v132, v[152:155]
	s_waitcnt vmcnt(10)
	ds_write_b128 v132, v[156:159] offset:4608
	s_waitcnt vmcnt(9)
	ds_write_b128 v132, v[160:163] offset:9216
	s_waitcnt vmcnt(8)
	ds_write_b128 v132, v[164:167] offset:13824
	s_waitcnt vmcnt(7)
	ds_write_b128 v132, v[168:171] offset:18432
	s_waitcnt vmcnt(6)
	ds_write_b128 v132, v[172:175] offset:23040
	s_waitcnt vmcnt(5)
	ds_write_b128 v132, v[176:179] offset:27648
	s_waitcnt vmcnt(4)
	ds_write_b128 v132, v[180:183] offset:32256
	s_waitcnt vmcnt(3)
	ds_write_b128 v132, v[184:187] offset:36864
	s_waitcnt vmcnt(2)
	ds_write_b128 v132, v[188:191] offset:41472
	s_waitcnt vmcnt(1)
	ds_write_b128 v132, v[192:195] offset:46080
	s_waitcnt vmcnt(0)
	ds_write_b128 v132, v[196:199] offset:50688
	s_waitcnt lgkmcnt(0)
	s_barrier
	v_add_co_u32_e32 v156, vcc, 0x3e0000, v136
	s_nop 0
	s_nop 0
	s_nop 0
	v_addc_co_u32_e32 v157, vcc, 0, v137, vcc
	v_add_co_u32_e32 v160, vcc, 0x3e1000, v136
	s_mov_b32 s18, 0
	s_nop 0
	v_addc_co_u32_e32 v161, vcc, 0, v137, vcc
	v_add_co_u32_e32 v164, vcc, 0x3e2000, v136
	s_nop 0
	v_addc_co_u32_e32 v165, vcc, 0, v137, vcc
	v_add_co_u32_e32 v168, vcc, 0x3e3000, v136
	s_nop 1
	v_addc_co_u32_e32 v169, vcc, 0, v137, vcc
	v_add_co_u32_e32 v172, vcc, 0x3e4000, v136
	s_nop 0
	v_addc_co_u32_e32 v173, vcc, 0, v137, vcc
	v_add_co_u32_e32 v176, vcc, 0x3e5000, v136
	s_nop 1
	v_addc_co_u32_e32 v177, vcc, 0, v137, vcc
	v_add_co_u32_e32 v180, vcc, 0x3e6000, v136
	s_nop 0
	v_addc_co_u32_e32 v181, vcc, 0, v137, vcc
	v_add_co_u32_e32 v136, vcc, 0x3e7000, v136
	s_nop 1
	v_addc_co_u32_e32 v137, vcc, 0, v137, vcc
	s_nop 0
	s_setprio 1
	ds_read_b128 v[188:191], v133 offset:0
	ds_read_b128 v[200:203], v150 offset:18432
	ds_read_b128 v[204:207], v150 offset:23040
	ds_read_b128 v[208:211], v150 offset:27648
	ds_read_b128 v[212:215], v150 offset:32256
	ds_read_b128 v[196:199], v133 offset:4608
	s_waitcnt lgkmcnt(4)
	v_mfma_f32_32x32x16_bf16 v[114:129], v[188:191], v[200:203], v[114:129]
	ds_read_b128 v[192:195], v133 offset:32
	ds_read_b128 v[216:219], v150 offset:18464
	s_waitcnt lgkmcnt(5)
	v_mfma_f32_32x32x16_bf16 v[98:113], v[188:191], v[204:207], v[98:113]
	ds_read_b128 v[224:227], v150 offset:23072
	s_waitcnt lgkmcnt(5)
	v_mfma_f32_32x32x16_bf16 v[82:97], v[188:191], v[208:211], v[82:97]
	ds_read_b128 v[228:231], v150 offset:27680
	s_waitcnt lgkmcnt(5)
	v_mfma_f32_32x32x16_bf16 v[66:81], v[188:191], v[212:215], v[66:81]
	ds_read_b128 v[232:235], v150 offset:32288
	s_waitcnt lgkmcnt(5)
	v_mfma_f32_32x32x16_bf16 v[50:65], v[196:199], v[200:203], v[50:65]
	v_mfma_f32_32x32x16_bf16 v[34:49], v[196:199], v[204:207], v[34:49]
	v_mfma_f32_32x32x16_bf16 v[18:33], v[196:199], v[208:211], v[18:33]
	v_mfma_f32_32x32x16_bf16 v[2:17], v[196:199], v[212:215], v[2:17]
	ds_read_b128 v[196:199], v133 offset:4640
	s_waitcnt lgkmcnt(4)
	v_mfma_f32_32x32x16_bf16 v[114:129], v[192:195], v[216:219], v[114:129]
	ds_read_b128 v[188:191], v133 offset:64
	ds_read_b128 v[200:203], v150 offset:18496
	s_waitcnt lgkmcnt(5)
	v_mfma_f32_32x32x16_bf16 v[98:113], v[192:195], v[224:227], v[98:113]
	ds_read_b128 v[204:207], v150 offset:23104
	s_waitcnt lgkmcnt(5)
	v_mfma_f32_32x32x16_bf16 v[82:97], v[192:195], v[228:231], v[82:97]
	ds_read_b128 v[208:211], v150 offset:27712
	s_waitcnt lgkmcnt(5)
	v_mfma_f32_32x32x16_bf16 v[66:81], v[192:195], v[232:235], v[66:81]
	ds_read_b128 v[212:215], v150 offset:32320
	s_waitcnt lgkmcnt(5)
	v_mfma_f32_32x32x16_bf16 v[50:65], v[196:199], v[216:219], v[50:65]
	v_mfma_f32_32x32x16_bf16 v[34:49], v[196:199], v[224:227], v[34:49]
	v_mfma_f32_32x32x16_bf16 v[18:33], v[196:199], v[228:231], v[18:33]
	v_mfma_f32_32x32x16_bf16 v[2:17], v[196:199], v[232:235], v[2:17]
	ds_read_b128 v[196:199], v133 offset:4672
	s_waitcnt lgkmcnt(4)
	v_mfma_f32_32x32x16_bf16 v[114:129], v[188:191], v[200:203], v[114:129]
	ds_read_b128 v[192:195], v133 offset:96
	ds_read_b128 v[216:219], v150 offset:18528
	s_waitcnt lgkmcnt(5)
	v_mfma_f32_32x32x16_bf16 v[98:113], v[188:191], v[204:207], v[98:113]
	ds_read_b128 v[224:227], v150 offset:23136
	s_waitcnt lgkmcnt(5)
	v_mfma_f32_32x32x16_bf16 v[82:97], v[188:191], v[208:211], v[82:97]
	ds_read_b128 v[228:231], v150 offset:27744
	s_waitcnt lgkmcnt(5)
	v_mfma_f32_32x32x16_bf16 v[66:81], v[188:191], v[212:215], v[66:81]
	ds_read_b128 v[232:235], v150 offset:32352
	s_waitcnt lgkmcnt(5)
	v_mfma_f32_32x32x16_bf16 v[50:65], v[196:199], v[200:203], v[50:65]
	v_mfma_f32_32x32x16_bf16 v[34:49], v[196:199], v[204:207], v[34:49]
	v_mfma_f32_32x32x16_bf16 v[18:33], v[196:199], v[208:211], v[18:33]
	v_mfma_f32_32x32x16_bf16 v[2:17], v[196:199], v[212:215], v[2:17]
	ds_read_b128 v[196:199], v133 offset:4704
	s_waitcnt lgkmcnt(4)
	v_mfma_f32_32x32x16_bf16 v[114:129], v[192:195], v[216:219], v[114:129]
	s_waitcnt lgkmcnt(3)
	v_mfma_f32_32x32x16_bf16 v[98:113], v[192:195], v[224:227], v[98:113]
	s_waitcnt lgkmcnt(2)
	v_mfma_f32_32x32x16_bf16 v[82:97], v[192:195], v[228:231], v[82:97]
	s_waitcnt lgkmcnt(1)
	v_mfma_f32_32x32x16_bf16 v[66:81], v[192:195], v[232:235], v[66:81]
	s_waitcnt lgkmcnt(0)
	v_mfma_f32_32x32x16_bf16 v[50:65], v[196:199], v[216:219], v[50:65]
	v_mfma_f32_32x32x16_bf16 v[34:49], v[196:199], v[224:227], v[34:49]
	v_mfma_f32_32x32x16_bf16 v[18:33], v[196:199], v[228:231], v[18:33]
	v_mfma_f32_32x32x16_bf16 v[2:17], v[196:199], v[232:235], v[2:17]
	s_setprio 0
	v_readlane_b32 s48, v253, 37
	v_readlane_b32 s49, v253, 38
	v_readlane_b32 s50, v253, 39
	v_readlane_b32 s51, v253, 40
	v_readlane_b32 s52, v253, 41
	v_readlane_b32 s53, v253, 42
	v_readlane_b32 s54, v253, 43
	v_readlane_b32 s55, v253, 44
	v_readlane_b32 s56, v253, 45
	v_readlane_b32 s57, v253, 46
	v_readlane_b32 s58, v253, 47
	v_readlane_b32 s59, v253, 48
	v_readlane_b32 s60, v253, 49
	v_readlane_b32 s61, v253, 50
	v_readlane_b32 s62, v253, 51
	v_readlane_b32 s63, v253, 52
	s_mov_b64 s[48:49], s[56:57]
	s_lshl_b32 s19, s14, 8
	s_mov_b64 s[14:15], -1
	s_mov_b64 s[50:51], s[58:59]
	s_mov_b64 s[52:53], s[60:61]
	s_mov_b64 s[54:55], s[62:63]
	s_barrier
	s_waitcnt lgkmcnt(0)
	s_branch .LBB0_1116

;     ...
;   for (int kt = 0; kt < nk; ++kt) {
;     const int kn = (kt + 1 < nk) ? kt + 1 : kt;
;     GW_LOAD2(kn * 64, kn * bkstep)
;     __builtin_amdgcn_sched_barrier(0);
;     __builtin_amdgcn_s_setprio(1);
; #pragma unroll
;     for (int st = 0; st < 4; ++st) {
;       bf16x8 a0 = *(const bf16x8*)(Ab + st * 32);
;       bf16x8 a1 = *(const bf16x8*)(Ab + 32 * LSTR + st * 32);
;       bf16x8 b0 = *(const bf16x8*)(Bb + st * 32);
;       bf16x8 b1 = *(const bf16x8*)(Bb + 32 * LSTR + st * 32);
;       bf16x8 b2 = *(const bf16x8*)(Bb + 64 * LSTR + st * 32);
;       bf16x8 b3 = *(const bf16x8*)(Bb + 96 * LSTR + st * 32);
;       acc[0][0] = mfma32(a0, b0, acc[0][0]);
;       acc[0][1] = mfma32(a0, b1, acc[0][1]);
;       acc[0][2] = mfma32(a0, b2, acc[0][2]);
;       acc[0][3] = mfma32(a0, b3, acc[0][3]);
;       acc[1][0] = mfma32(a1, b0, acc[1][0]);
;       acc[1][1] = mfma32(a1, b1, acc[1][1]);
;       acc[1][2] = mfma32(a1, b2, acc[1][2]);
;       acc[1][3] = mfma32(a1, b3, acc[1][3]);
;     }
;     __builtin_amdgcn_s_setprio(0);
;     __builtin_amdgcn_sched_barrier(0);
;     __syncthreads();
;     GW_STORE()
;     __syncthreads();
.LBB0_1284:
	s_setprio 1
	ds_read_b128 v[204:207], v131 offset:0
	ds_read_b128 v[216:219], v138 offset:18432
	ds_read_b128 v[224:227], v138 offset:23040
	ds_read_b128 v[228:231], v138 offset:27648
	ds_read_b128 v[232:235], v138 offset:32256
	ds_read_b128 v[212:215], v131 offset:4608
	s_waitcnt lgkmcnt(4)
	v_mfma_f32_32x32x16_bf16 v[114:129], v[204:207], v[216:219], v[114:129]
	ds_read_b128 v[208:211], v131 offset:32
	ds_read_b128 v[236:239], v138 offset:18464
	s_waitcnt lgkmcnt(5)
	v_mfma_f32_32x32x16_bf16 v[98:113], v[204:207], v[224:227], v[98:113]
	ds_read_b128 v[240:243], v138 offset:23072
	s_waitcnt lgkmcnt(5)
	v_mfma_f32_32x32x16_bf16 v[82:97], v[204:207], v[228:231], v[82:97]
	ds_read_b128 v[244:247], v138 offset:27680
	s_waitcnt lgkmcnt(5)
	v_mfma_f32_32x32x16_bf16 v[66:81], v[204:207], v[232:235], v[66:81]
	ds_read_b128 v[248:251], v138 offset:32288
	s_waitcnt lgkmcnt(5)
	v_mfma_f32_32x32x16_bf16 v[50:65], v[212:215], v[216:219], v[50:65]
	v_mfma_f32_32x32x16_bf16 v[34:49], v[212:215], v[224:227], v[34:49]
	v_mfma_f32_32x32x16_bf16 v[18:33], v[212:215], v[228:231], v[18:33]
	v_mfma_f32_32x32x16_bf16 v[2:17], v[212:215], v[232:235], v[2:17]
	ds_read_b128 v[212:215], v131 offset:4640
	s_waitcnt lgkmcnt(4)
	v_mfma_f32_32x32x16_bf16 v[114:129], v[208:211], v[236:239], v[114:129]
	ds_read_b128 v[204:207], v131 offset:64
	ds_read_b128 v[216:219], v138 offset:18496
	s_waitcnt lgkmcnt(5)
	v_mfma_f32_32x32x16_bf16 v[98:113], v[208:211], v[240:243], v[98:113]
	ds_read_b128 v[224:227], v138 offset:23104
	s_waitcnt lgkmcnt(5)
	v_mfma_f32_32x32x16_bf16 v[82:97], v[208:211], v[244:247], v[82:97]
	ds_read_b128 v[228:231], v138 offset:27712
	s_waitcnt lgkmcnt(5)
	v_mfma_f32_32x32x16_bf16 v[66:81], v[208:211], v[248:251], v[66:81]
	ds_read_b128 v[232:235], v138 offset:32320
	s_waitcnt lgkmcnt(5)
	v_mfma_f32_32x32x16_bf16 v[50:65], v[212:215], v[236:239], v[50:65]
	v_mfma_f32_32x32x16_bf16 v[34:49], v[212:215], v[240:243], v[34:49]
	v_mfma_f32_32x32x16_bf16 v[18:33], v[212:215], v[244:247], v[18:33]
	v_mfma_f32_32x32x16_bf16 v[2:17], v[212:215], v[248:251], v[2:17]
	ds_read_b128 v[212:215], v131 offset:4672
	s_waitcnt lgkmcnt(4)
	v_mfma_f32_32x32x16_bf16 v[114:129], v[204:207], v[216:219], v[114:129]
	ds_read_b128 v[208:211], v131 offset:96
	ds_read_b128 v[236:239], v138 offset:18528
	s_waitcnt lgkmcnt(5)
	v_mfma_f32_32x32x16_bf16 v[98:113], v[204:207], v[224:227], v[98:113]
	ds_read_b128 v[240:243], v138 offset:23136
	s_waitcnt lgkmcnt(5)
	v_mfma_f32_32x32x16_bf16 v[82:97], v[204:207], v[228:231], v[82:97]
	ds_read_b128 v[244:247], v138 offset:27744
	s_waitcnt lgkmcnt(5)
	v_mfma_f32_32x32x16_bf16 v[66:81], v[204:207], v[232:235], v[66:81]
	ds_read_b128 v[248:251], v138 offset:32352
	s_waitcnt lgkmcnt(5)
	v_mfma_f32_32x32x16_bf16 v[50:65], v[212:215], v[216:219], v[50:65]
	v_mfma_f32_32x32x16_bf16 v[34:49], v[212:215], v[224:227], v[34:49]
	v_mfma_f32_32x32x16_bf16 v[18:33], v[212:215], v[228:231], v[18:33]
	v_mfma_f32_32x32x16_bf16 v[2:17], v[212:215], v[232:235], v[2:17]
	ds_read_b128 v[212:215], v131 offset:4704
	s_waitcnt lgkmcnt(4)
	v_mfma_f32_32x32x16_bf16 v[114:129], v[208:211], v[236:239], v[114:129]
	s_waitcnt lgkmcnt(3)
	v_mfma_f32_32x32x16_bf16 v[98:113], v[208:211], v[240:243], v[98:113]
	s_waitcnt lgkmcnt(2)
	v_mfma_f32_32x32x16_bf16 v[82:97], v[208:211], v[244:247], v[82:97]
	s_waitcnt lgkmcnt(1)
	v_mfma_f32_32x32x16_bf16 v[66:81], v[208:211], v[248:251], v[66:81]
	s_waitcnt lgkmcnt(0)
	v_mfma_f32_32x32x16_bf16 v[50:65], v[212:215], v[236:239], v[50:65]
	v_mfma_f32_32x32x16_bf16 v[34:49], v[212:215], v[240:243], v[34:49]
	v_mfma_f32_32x32x16_bf16 v[18:33], v[212:215], v[244:247], v[18:33]
	v_mfma_f32_32x32x16_bf16 v[2:17], v[212:215], v[248:251], v[2:17]
	s_setprio 0
	s_add_u32 s8, s8, 0x80
	s_addc_u32 s9, s9, 0
	s_cmpk_lg_i32 s8, 0x700
	s_barrier
	s_waitcnt vmcnt(11)
	ds_write_b128 v130, v[154:157]
	v_lshl_add_u64 v[154:155], v[150:151], 0, s[8:9]
	v_add_co_u32_e32 v154, vcc, s43, v154
	s_nop 1
	v_addc_co_u32_e32 v155, vcc, 0, v155, vcc
	global_load_dwordx4 v[154:157], v[154:155], off offset:384
	s_waitcnt vmcnt(11)
	ds_write_b128 v130, v[158:161] offset:4608
	v_lshl_add_u64 v[158:159], v[150:151], 0, s[8:9]
	v_add_co_u32_e32 v158, vcc, s44, v158
	s_nop 1
	v_addc_co_u32_e32 v159, vcc, 0, v159, vcc
	global_load_dwordx4 v[158:161], v[158:159], off offset:384
	s_waitcnt vmcnt(11)
	ds_write_b128 v130, v[162:165] offset:9216
	v_lshl_add_u64 v[162:163], v[150:151], 0, s[8:9]
	v_add_co_u32_e32 v162, vcc, s45, v162
	s_nop 1
	v_addc_co_u32_e32 v163, vcc, 0, v163, vcc
	global_load_dwordx4 v[162:165], v[162:163], off offset:384
	s_waitcnt vmcnt(11)
	ds_write_b128 v130, v[166:169] offset:13824
	v_lshl_add_u64 v[166:167], v[150:151], 0, s[8:9]
	v_add_co_u32_e32 v166, vcc, s46, v166
	s_nop 1
	v_addc_co_u32_e32 v167, vcc, 0, v167, vcc
	global_load_dwordx4 v[166:169], v[166:167], off offset:384
	s_waitcnt vmcnt(11)
	ds_write_b128 v130, v[170:173] offset:18432
	v_lshl_add_u64 v[170:171], v[152:153], 0, s[8:9]
	v_add_co_u32_e32 v170, vcc, s35, v170
	s_nop 1
	v_addc_co_u32_e32 v171, vcc, 0, v171, vcc
	global_load_dwordx4 v[170:173], v[170:171], off offset:128
	s_waitcnt vmcnt(11)
	ds_write_b128 v130, v[174:177] offset:23040
	v_lshl_add_u64 v[174:175], v[152:153], 0, s[8:9]
	v_add_co_u32_e32 v174, vcc, s36, v174
	s_nop 1
	v_addc_co_u32_e32 v175, vcc, 0, v175, vcc
	global_load_dwordx4 v[174:177], v[174:175], off offset:128
	s_waitcnt vmcnt(11)
	ds_write_b128 v130, v[178:181] offset:27648
	v_lshl_add_u64 v[178:179], v[152:153], 0, s[8:9]
	v_add_co_u32_e32 v178, vcc, s37, v178
	s_nop 1
	v_addc_co_u32_e32 v179, vcc, 0, v179, vcc
	global_load_dwordx4 v[178:181], v[178:179], off offset:128
	s_waitcnt vmcnt(11)
	ds_write_b128 v130, v[184:187] offset:32256
	v_lshl_add_u64 v[184:185], v[152:153], 0, s[8:9]
	v_add_co_u32_e32 v184, vcc, s38, v184
	s_nop 1
	v_addc_co_u32_e32 v185, vcc, 0, v185, vcc
	global_load_dwordx4 v[184:187], v[184:185], off offset:128
	s_waitcnt vmcnt(11)
	ds_write_b128 v130, v[188:191] offset:36864
	v_lshl_add_u64 v[188:189], v[152:153], 0, s[8:9]
	v_add_co_u32_e32 v188, vcc, s39, v188
	s_nop 1
	v_addc_co_u32_e32 v189, vcc, 0, v189, vcc
	global_load_dwordx4 v[188:191], v[188:189], off offset:128
	s_waitcnt vmcnt(11)
	ds_write_b128 v130, v[192:195] offset:41472
	v_lshl_add_u64 v[192:193], v[152:153], 0, s[8:9]
	v_add_co_u32_e32 v192, vcc, s40, v192
	s_nop 1
	v_addc_co_u32_e32 v193, vcc, 0, v193, vcc
	global_load_dwordx4 v[192:195], v[192:193], off offset:128
	s_waitcnt vmcnt(11)
	ds_write_b128 v130, v[196:199] offset:46080
	v_lshl_add_u64 v[196:197], v[152:153], 0, s[8:9]
	v_add_co_u32_e32 v196, vcc, s41, v196
	s_nop 1
	v_addc_co_u32_e32 v197, vcc, 0, v197, vcc
	global_load_dwordx4 v[196:199], v[196:197], off offset:128
	s_waitcnt vmcnt(11)
	ds_write_b128 v130, v[200:203] offset:50688
	v_lshl_add_u64 v[200:201], v[152:153], 0, s[8:9]
	v_add_co_u32_e32 v200, vcc, s42, v200
	s_nop 1
	v_addc_co_u32_e32 v201, vcc, 0, v201, vcc
	global_load_dwordx4 v[200:203], v[200:201], off offset:128
	s_waitcnt lgkmcnt(0)
	s_barrier
;     ...
;   for (int kt = 0; kt < nk; ++kt) {
;     const int kn = (kt + 1 < nk) ? kt + 1 : kt;
;     GW_LOAD2(kn * 64, kn * bkstep)
;     __builtin_amdgcn_sched_barrier(0);
;     __builtin_amdgcn_s_setprio(1);
; #pragma unroll
;     for (int st = 0; st < 4; ++st) {
;       bf16x8 a0 = *(const bf16x8*)(Ab + st * 32);
;       bf16x8 a1 = *(const bf16x8*)(Ab + 32 * LSTR + st * 32);
;       bf16x8 b0 = *(const bf16x8*)(Bb + st * 32);
;       bf16x8 b1 = *(const bf16x8*)(Bb + 32 * LSTR + st * 32);
;       bf16x8 b2 = *(const bf16x8*)(Bb + 64 * LSTR + st * 32);
;       bf16x8 b3 = *(const bf16x8*)(Bb + 96 * LSTR + st * 32);
;       acc[0][0] = mfma32(a0, b0, acc[0][0]);
;       acc[0][1] = mfma32(a0, b1, acc[0][1]);
;       acc[0][2] = mfma32(a0, b2, acc[0][2]);
;       acc[0][3] = mfma32(a0, b3, acc[0][3]);
;       acc[1][0] = mfma32(a1, b0, acc[1][0]);
;       acc[1][1] = mfma32(a1, b1, acc[1][1]);
;       acc[1][2] = mfma32(a1, b2, acc[1][2]);
;       acc[1][3] = mfma32(a1, b3, acc[1][3]);
;     }
;     __builtin_amdgcn_s_setprio(0);
;     __builtin_amdgcn_sched_barrier(0);
;     __syncthreads();
;     GW_STORE()
;     __syncthreads();
;   }
	s_cbranch_scc1 .LBB0_1284
	s_setprio 1
	ds_read_b128 v[204:207], v131 offset:0
	ds_read_b128 v[216:219], v138 offset:18432
	ds_read_b128 v[224:227], v138 offset:23040
	ds_read_b128 v[228:231], v138 offset:27648
	ds_read_b128 v[232:235], v138 offset:32256
	ds_read_b128 v[212:215], v131 offset:4608
	s_waitcnt lgkmcnt(4)
	v_mfma_f32_32x32x16_bf16 v[114:129], v[204:207], v[216:219], v[114:129]
	ds_read_b128 v[208:211], v131 offset:32
	ds_read_b128 v[236:239], v138 offset:18464
	s_waitcnt lgkmcnt(5)
	v_mfma_f32_32x32x16_bf16 v[98:113], v[204:207], v[224:227], v[98:113]
	ds_read_b128 v[240:243], v138 offset:23072
	s_waitcnt lgkmcnt(5)
	v_mfma_f32_32x32x16_bf16 v[82:97], v[204:207], v[228:231], v[82:97]
	ds_read_b128 v[244:247], v138 offset:27680
	s_waitcnt lgkmcnt(5)
	v_mfma_f32_32x32x16_bf16 v[66:81], v[204:207], v[232:235], v[66:81]
	ds_read_b128 v[248:251], v138 offset:32288
	s_waitcnt lgkmcnt(5)
	v_mfma_f32_32x32x16_bf16 v[50:65], v[212:215], v[216:219], v[50:65]
	v_mfma_f32_32x32x16_bf16 v[34:49], v[212:215], v[224:227], v[34:49]
	v_mfma_f32_32x32x16_bf16 v[18:33], v[212:215], v[228:231], v[18:33]
	v_mfma_f32_32x32x16_bf16 v[2:17], v[212:215], v[232:235], v[2:17]
	ds_read_b128 v[212:215], v131 offset:4640
	s_waitcnt lgkmcnt(4)
	v_mfma_f32_32x32x16_bf16 v[114:129], v[208:211], v[236:239], v[114:129]
	ds_read_b128 v[204:207], v131 offset:64
	ds_read_b128 v[216:219], v138 offset:18496
	s_waitcnt lgkmcnt(5)
	v_mfma_f32_32x32x16_bf16 v[98:113], v[208:211], v[240:243], v[98:113]
	ds_read_b128 v[224:227], v138 offset:23104
	s_waitcnt lgkmcnt(5)
	v_mfma_f32_32x32x16_bf16 v[82:97], v[208:211], v[244:247], v[82:97]
	ds_read_b128 v[228:231], v138 offset:27712
	s_waitcnt lgkmcnt(5)
	v_mfma_f32_32x32x16_bf16 v[66:81], v[208:211], v[248:251], v[66:81]
	ds_read_b128 v[232:235], v138 offset:32320
	s_waitcnt lgkmcnt(5)
	v_mfma_f32_32x32x16_bf16 v[50:65], v[212:215], v[236:239], v[50:65]
	v_mfma_f32_32x32x16_bf16 v[34:49], v[212:215], v[240:243], v[34:49]
	v_mfma_f32_32x32x16_bf16 v[18:33], v[212:215], v[244:247], v[18:33]
	v_mfma_f32_32x32x16_bf16 v[2:17], v[212:215], v[248:251], v[2:17]
	ds_read_b128 v[212:215], v131 offset:4672
	s_waitcnt lgkmcnt(4)
	v_mfma_f32_32x32x16_bf16 v[114:129], v[204:207], v[216:219], v[114:129]
	ds_read_b128 v[208:211], v131 offset:96
	ds_read_b128 v[236:239], v138 offset:18528
	s_waitcnt lgkmcnt(5)
	v_mfma_f32_32x32x16_bf16 v[98:113], v[204:207], v[224:227], v[98:113]
	ds_read_b128 v[240:243], v138 offset:23136
	s_waitcnt lgkmcnt(5)
	v_mfma_f32_32x32x16_bf16 v[82:97], v[204:207], v[228:231], v[82:97]
	ds_read_b128 v[244:247], v138 offset:27744
	s_waitcnt lgkmcnt(5)
	v_mfma_f32_32x32x16_bf16 v[66:81], v[204:207], v[232:235], v[66:81]
	ds_read_b128 v[248:251], v138 offset:32352
	s_waitcnt lgkmcnt(5)
	v_mfma_f32_32x32x16_bf16 v[50:65], v[212:215], v[216:219], v[50:65]
	v_mfma_f32_32x32x16_bf16 v[34:49], v[212:215], v[224:227], v[34:49]
	v_mfma_f32_32x32x16_bf16 v[18:33], v[212:215], v[228:231], v[18:33]
	v_mfma_f32_32x32x16_bf16 v[2:17], v[212:215], v[232:235], v[2:17]
	ds_read_b128 v[212:215], v131 offset:4704
	s_waitcnt lgkmcnt(4)
	v_mfma_f32_32x32x16_bf16 v[114:129], v[208:211], v[236:239], v[114:129]
	s_waitcnt lgkmcnt(3)
	v_mfma_f32_32x32x16_bf16 v[98:113], v[208:211], v[240:243], v[98:113]
	s_waitcnt lgkmcnt(2)
	v_mfma_f32_32x32x16_bf16 v[82:97], v[208:211], v[244:247], v[82:97]
	s_waitcnt lgkmcnt(1)
	v_mfma_f32_32x32x16_bf16 v[66:81], v[208:211], v[248:251], v[66:81]
	s_waitcnt lgkmcnt(0)
	v_mfma_f32_32x32x16_bf16 v[50:65], v[212:215], v[236:239], v[50:65]
	v_mfma_f32_32x32x16_bf16 v[34:49], v[212:215], v[240:243], v[34:49]
	v_mfma_f32_32x32x16_bf16 v[18:33], v[212:215], v[244:247], v[18:33]
	v_mfma_f32_32x32x16_bf16 v[2:17], v[212:215], v[248:251], v[2:17]
	s_setprio 0
	s_add_u32 s8, s8, 0x80
	s_addc_u32 s9, s9, 0
	s_barrier
	s_waitcnt vmcnt(11)
	ds_write_b128 v130, v[154:157]
	s_waitcnt vmcnt(10)
	ds_write_b128 v130, v[158:161] offset:4608
	s_waitcnt vmcnt(9)
	ds_write_b128 v130, v[162:165] offset:9216
	s_waitcnt vmcnt(8)
	ds_write_b128 v130, v[166:169] offset:13824
	s_waitcnt vmcnt(7)
	ds_write_b128 v130, v[170:173] offset:18432
	s_waitcnt vmcnt(6)
	ds_write_b128 v130, v[174:177] offset:23040
	s_waitcnt vmcnt(5)
	ds_write_b128 v130, v[178:181] offset:27648
	s_waitcnt vmcnt(4)
	ds_write_b128 v130, v[184:187] offset:32256
	s_waitcnt vmcnt(3)
	ds_write_b128 v130, v[188:191] offset:36864
	s_waitcnt vmcnt(2)
	ds_write_b128 v130, v[192:195] offset:41472
	s_waitcnt vmcnt(1)
	ds_write_b128 v130, v[196:199] offset:46080
	s_waitcnt vmcnt(0)
	ds_write_b128 v130, v[200:203] offset:50688
	s_waitcnt lgkmcnt(0)
	s_barrier
;     ...
;   for (int kt = 0; kt < nk; ++kt) {
;     const int kn = (kt + 1 < nk) ? kt + 1 : kt;
;     GW_LOAD2(kn * 64, kn * bkstep)
;     __builtin_amdgcn_sched_barrier(0);
;     __builtin_amdgcn_s_setprio(1);
; #pragma unroll
;     for (int st = 0; st < 4; ++st) {
;       bf16x8 a0 = *(const bf16x8*)(Ab + st * 32);
;       bf16x8 a1 = *(const bf16x8*)(Ab + 32 * LSTR + st * 32);
;       bf16x8 b0 = *(const bf16x8*)(Bb + st * 32);
;       bf16x8 b1 = *(const bf16x8*)(Bb + 32 * LSTR + st * 32);
;       bf16x8 b2 = *(const bf16x8*)(Bb + 64 * LSTR + st * 32);
;       bf16x8 b3 = *(const bf16x8*)(Bb + 96 * LSTR + st * 32);
;       acc[0][0] = mfma32(a0, b0, acc[0][0]);
;       acc[0][1] = mfma32(a0, b1, acc[0][1]);
;       acc[0][2] = mfma32(a0, b2, acc[0][2]);
;       acc[0][3] = mfma32(a0, b3, acc[0][3]);
;       acc[1][0] = mfma32(a1, b0, acc[1][0]);
;       acc[1][1] = mfma32(a1, b1, acc[1][1]);
;       acc[1][2] = mfma32(a1, b2, acc[1][2]);
;       acc[1][3] = mfma32(a1, b3, acc[1][3]);
;     }
;     __builtin_amdgcn_s_setprio(0);
;     __builtin_amdgcn_sched_barrier(0);
;     __syncthreads();
;     GW_STORE()
;     __syncthreads();
;   }
; __device__ __forceinline__ void inproj_tile(const Params& P, int l, int mt, int ntw, char* smem) {
;     ...
;   const int row0 = mt * 128;
;   const bool isctx = row0 >= NLAT;
;   const int b = isctx ? ((row0 - NLAT) >> 8) : (row0 >> 12);
;   const int pos0 = isctx ? ((row0 - NLAT) & 255) : (row0 & 4095);
;   const int tk0 = isctx ? (SEQ + pos0) : pos0;
	s_nop 0
	s_nop 0
	v_add_co_u32_e32 v132, vcc, 0x10000, v142
	s_mov_b32 s58, 0
	s_nop 0
	v_addc_co_u32_e32 v133, vcc, 0, v143, vcc
	v_add_co_u32_e32 v132, vcc, 0x20000, v142
	s_nop 1
	v_addc_co_u32_e32 v133, vcc, 0, v143, vcc
	v_add_co_u32_e32 v148, vcc, 0x30000, v142
	s_nop 1
	v_addc_co_u32_e32 v149, vcc, 0, v143, vcc
	v_add_co_u32_e32 v132, vcc, 0x40000, v142
	s_nop 1
	v_addc_co_u32_e32 v133, vcc, 0, v143, vcc
	v_add_co_u32_e32 v148, vcc, 0x50000, v142
	s_nop 1
	v_addc_co_u32_e32 v149, vcc, 0, v143, vcc
	v_add_co_u32_e32 v132, vcc, 0x60000, v142
	s_nop 1
	v_addc_co_u32_e32 v133, vcc, 0, v143, vcc
	v_add_co_u32_e32 v142, vcc, 0x70000, v142
	s_nop 1
	v_addc_co_u32_e32 v143, vcc, 0, v143, vcc
	s_setprio 1
	ds_read_b128 v[196:199], v131 offset:0
	ds_read_b128 v[208:211], v138 offset:18432
	ds_read_b128 v[212:215], v138 offset:23040
	ds_read_b128 v[216:219], v138 offset:27648
	ds_read_b128 v[224:227], v138 offset:32256
	ds_read_b128 v[204:207], v131 offset:4608
	s_waitcnt lgkmcnt(4)
	v_mfma_f32_32x32x16_bf16 v[114:129], v[196:199], v[208:211], v[114:129]
	ds_read_b128 v[200:203], v131 offset:32
	ds_read_b128 v[228:231], v138 offset:18464
	s_waitcnt lgkmcnt(5)
	v_mfma_f32_32x32x16_bf16 v[98:113], v[196:199], v[212:215], v[98:113]
	ds_read_b128 v[232:235], v138 offset:23072
	s_waitcnt lgkmcnt(5)
	v_mfma_f32_32x32x16_bf16 v[82:97], v[196:199], v[216:219], v[82:97]
	ds_read_b128 v[236:239], v138 offset:27680
	s_waitcnt lgkmcnt(5)
	v_mfma_f32_32x32x16_bf16 v[66:81], v[196:199], v[224:227], v[66:81]
	ds_read_b128 v[240:243], v138 offset:32288
	s_waitcnt lgkmcnt(5)
	v_mfma_f32_32x32x16_bf16 v[50:65], v[204:207], v[208:211], v[50:65]
	v_mfma_f32_32x32x16_bf16 v[34:49], v[204:207], v[212:215], v[34:49]
	v_mfma_f32_32x32x16_bf16 v[18:33], v[204:207], v[216:219], v[18:33]
	v_mfma_f32_32x32x16_bf16 v[2:17], v[204:207], v[224:227], v[2:17]
	ds_read_b128 v[204:207], v131 offset:4640
	s_waitcnt lgkmcnt(4)
	v_mfma_f32_32x32x16_bf16 v[114:129], v[200:203], v[228:231], v[114:129]
	ds_read_b128 v[196:199], v131 offset:64
	ds_read_b128 v[208:211], v138 offset:18496
	s_waitcnt lgkmcnt(5)
	v_mfma_f32_32x32x16_bf16 v[98:113], v[200:203], v[232:235], v[98:113]
	ds_read_b128 v[212:215], v138 offset:23104
	s_waitcnt lgkmcnt(5)
	v_mfma_f32_32x32x16_bf16 v[82:97], v[200:203], v[236:239], v[82:97]
	ds_read_b128 v[216:219], v138 offset:27712
	s_waitcnt lgkmcnt(5)
	v_mfma_f32_32x32x16_bf16 v[66:81], v[200:203], v[240:243], v[66:81]
	ds_read_b128 v[224:227], v138 offset:32320
	s_waitcnt lgkmcnt(5)
	v_mfma_f32_32x32x16_bf16 v[50:65], v[204:207], v[228:231], v[50:65]
	v_mfma_f32_32x32x16_bf16 v[34:49], v[204:207], v[232:235], v[34:49]
	v_mfma_f32_32x32x16_bf16 v[18:33], v[204:207], v[236:239], v[18:33]
	v_mfma_f32_32x32x16_bf16 v[2:17], v[204:207], v[240:243], v[2:17]
	ds_read_b128 v[204:207], v131 offset:4672
	s_waitcnt lgkmcnt(4)
	v_mfma_f32_32x32x16_bf16 v[114:129], v[196:199], v[208:211], v[114:129]
	ds_read_b128 v[200:203], v131 offset:96
	ds_read_b128 v[228:231], v138 offset:18528
	s_waitcnt lgkmcnt(5)
	v_mfma_f32_32x32x16_bf16 v[98:113], v[196:199], v[212:215], v[98:113]
	ds_read_b128 v[232:235], v138 offset:23136
	s_waitcnt lgkmcnt(5)
	v_mfma_f32_32x32x16_bf16 v[82:97], v[196:199], v[216:219], v[82:97]
	ds_read_b128 v[236:239], v138 offset:27744
	s_waitcnt lgkmcnt(5)
	v_mfma_f32_32x32x16_bf16 v[66:81], v[196:199], v[224:227], v[66:81]
	ds_read_b128 v[240:243], v138 offset:32352
	s_waitcnt lgkmcnt(5)
	v_mfma_f32_32x32x16_bf16 v[50:65], v[204:207], v[208:211], v[50:65]
	v_mfma_f32_32x32x16_bf16 v[34:49], v[204:207], v[212:215], v[34:49]
	v_mfma_f32_32x32x16_bf16 v[18:33], v[204:207], v[216:219], v[18:33]
	v_mfma_f32_32x32x16_bf16 v[2:17], v[204:207], v[224:227], v[2:17]
	ds_read_b128 v[204:207], v131 offset:4704
	s_waitcnt lgkmcnt(4)
	v_mfma_f32_32x32x16_bf16 v[114:129], v[200:203], v[228:231], v[114:129]
	s_waitcnt lgkmcnt(3)
	v_mfma_f32_32x32x16_bf16 v[98:113], v[200:203], v[232:235], v[98:113]
	s_waitcnt lgkmcnt(2)
	v_mfma_f32_32x32x16_bf16 v[82:97], v[200:203], v[236:239], v[82:97]
	s_waitcnt lgkmcnt(1)
	v_mfma_f32_32x32x16_bf16 v[66:81], v[200:203], v[240:243], v[66:81]
	s_waitcnt lgkmcnt(0)
	v_mfma_f32_32x32x16_bf16 v[50:65], v[204:207], v[228:231], v[50:65]
	v_mfma_f32_32x32x16_bf16 v[34:49], v[204:207], v[232:235], v[34:49]
	v_mfma_f32_32x32x16_bf16 v[18:33], v[204:207], v[236:239], v[18:33]
	v_mfma_f32_32x32x16_bf16 v[2:17], v[204:207], v[240:243], v[2:17]
	s_setprio 0
	s_lshl_b32 s18, s10, 7
	s_cmpk_lt_i32 s10, 0x100
	s_cselect_b64 s[8:9], -1, 0
	s_add_i32 s6, s18, 0xffff8000
	s_and_b32 s57, s18, 0x80
	s_barrier
; __device__ __forceinline__ void inproj_tile(const Params& P, int l, int mt, int ntw, char* smem) {
;     ...
;   float* cs = (float*)smem;
;   const int row0 = mt * 128;
;   const bool isctx = row0 >= NLAT;
;   const int b = isctx ? ((row0 - NLAT) >> 8) : (row0 >> 12);
;   const int pos0 = isctx ? ((row0 - NLAT) & 255) : (row0 & 4095);
;   const int tk0 = isctx ? (SEQ + pos0) : pos0;
;   int tid_ = threadIdx.x;
;   asm volatile("" : "+v"(tid_));
;   const int lane = tid_ & 63, wave = tid_ >> 6;
;   const int r = 32 * wave + (lane & 31), half = lane >> 5;
;   const size_t grow = (size_t)row0 + r;
;   const float* crow = cs + r * CSTR + half * 64;
; #pragma unroll 1
;   for (int hsel = 0; hsel < 2; ++hsel) {
;     const int nt = ntw * 2 + hsel;
;     wide_acc_to_lds(acc, cs, hsel);
;     if (nt < 4) {
;       const int part = nt >> 1, cb = (nt & 1) * 128;
;       if (!isctx) {
;         u16* base = WSP(u16, OFF_FTT) + (size_t)b * 256 * 8192 + part * 4096 + pos0;
;         epi_transposed(cs, [&](int ch) { return base + (size_t)(cb + ch) * 8192; });
;       } else {
;         u16* base = WSP(u16, OFF_FTTC) + (size_t)b * 256 * 512 + part * 256 + pos0;
;         epi_transposed(cs, [&](int ch) { return base + (size_t)(cb + ch) * 512; });
;       }
;     } else if (nt < 7 || (nt >= 10 && nt < 13)) {
;       const bool isq = nt < 7;
;       const int head = (isq ? (nt - 4) : (nt - 10)) * 2 + half;
;       const float* g = (isq ? P.na_qn_g : P.na_kn_g) + l * 64;
;       float ss = 0.f;
; #pragma unroll
;       for (int q = 0; q < 16; ++q) {
;         float4 a = *(const float4*)(crow + q * 4);
;         ss += a.x * a.x + a.y * a.y + a.z * a.z + a.w * a.w;
;       }
;       const float rinv = rsqrtf(ss * (1.f / 64.f) + EPS) * (isq ? (0.125f * LOG2E) : 1.f);
;       u16* dst = WSP(u16, isq ? OFF_QN : OFF_KN) + grow * 384 + head * 64;
; #pragma unroll 1
;       for (int q = 0; q < 8; ++q) {
;         float4 a = *(const float4*)(crow + q * 8), c = *(const float4*)(crow + q * 8 + 4);
;         float4 ga = *(const float4*)(g + q * 8), gc = *(const float4*)(g + q * 8 + 4);
;         *(uint4*)(dst + q * 8) = pack8(a.x * rinv * ga.x, a.y * rinv * ga.y, a.z * rinv * ga.z, a.w * rinv * ga.w,
;                                        c.x * rinv * gc.x, c.y * rinv * gc.y, c.z * rinv * gc.z, c.w * rinv * gc.w);
;       }
;     } else if ((nt >= 7 && nt < 10) || (nt >= 16 && nt < 19)) {
	s_lshr_b32 s6, s6, 8
	s_ashr_i32 s12, s10, 5
	s_and_b32 s59, s18, 0xf80
	s_or_b32 s11, s57, 0x1000
	v_mov_b32_e32 v154, v134
	s_waitcnt lgkmcnt(0)
	s_cmpk_gt_i32 s10, 0xff
	s_cselect_b32 s60, s11, s59
	v_ashrrev_i32_e32 v155, 1, v154
	v_bfi_b32 v130, s47, v155, v154
	s_movk_i32 s11, 0x210
	v_lshlrev_b32_e32 v133, 1, v154
	s_cselect_b32 s13, s57, s59
	v_mul_lo_u32 v132, v130, s11
	v_and_b32_e32 v184, 64, v133
	s_cselect_b32 s10, s6, s12
	v_lshl_add_u32 v185, v184, 2, v132
	s_lshl_b32 s33, s16, 1
	v_add_u32_e32 v132, s13, v155
	s_ashr_i32 s13, s12, 31
	s_lshl_b32 s16, s16, 12
	s_ashr_i32 s19, s18, 31
	s_lshl_b64 s[20:21], s[12:13], 22
	s_ashr_i32 s17, s16, 31
	s_lshl_b64 s[22:23], s[6:7], 18
	s_mul_i32 s11, s10, 6
	s_cmp_gt_u32 s33, 9
	s_mul_i32 s61, s10, 0x330000
	s_mul_hi_i32 s62, s11, 0x88000
	s_cselect_b64 s[10:11], -1, 0
	s_cmp_gt_u32 s33, 21
	s_cselect_b64 s[12:13], -1, 0
	s_cmp_lt_u32 s33, 16
	v_ashrrev_i32_e32 v132, 2, v132
	s_cselect_b64 s[24:25], -1, 0
	v_ashrrev_i32_e32 v131, 31, v130
	v_and_b32_e32 v142, -16, v132
	v_lshlrev_b32_e32 v132, 4, v130
	s_and_b64 s[24:25], s[24:25], exec
	v_and_b32_e32 v138, 0x3f0, v132
	s_cselect_b32 s6, s49, 0x343b1100
	v_lshl_add_u64 v[130:131], s[18:19], 0, v[130:131]
	v_mov_b64_e32 v[132:133], s[90:91]
	s_cselect_b32 s56, s48, 0x1ffffed
	v_mad_u64_u32 v[146:147], s[18:19], v130, s50, v[132:133]
	s_add_u32 s6, s90, s6
	s_addc_u32 s18, s91, 0
	s_add_u32 s6, s6, s61
	s_addc_u32 s19, s18, s62
	s_lshl_b32 s18, s60, 1
	s_add_u32 s18, s6, s18
	s_addc_u32 s19, s19, 0
	v_mov_b32_e32 v141, v139
	s_add_u32 s6, s28, s20
	v_lshl_add_u64 v[148:149], s[18:19], 0, v[140:141]
	s_addc_u32 s18, s29, s21
	s_lshl_b64 s[16:17], s[16:17], 1
	s_add_u32 s6, s6, s16
	s_addc_u32 s17, s18, s17
	s_lshl_b32 s16, s59, 1
	s_add_u32 s16, s6, s16
	s_addc_u32 s17, s17, 0
	s_add_u32 s6, s30, s22
	v_lshl_add_u64 v[150:151], s[16:17], 0, v[140:141]
	s_addc_u32 s18, s31, s23
	s_lshl_b64 s[16:17], s[14:15], 1
	s_add_u32 s6, s6, s16
	s_addc_u32 s15, s18, s17
	s_lshl_b32 s16, s57, 1
	s_add_u32 s16, s6, s16
	v_and_b32_e32 v156, 31, v154
	v_mov_b64_e32 v[144:145], v[138:139]
	s_addc_u32 s17, s15, 0
	v_lshrrev_b32_e32 v132, 5, v155
	v_bfe_u32 v138, v154, 5, 1
	v_lshl_add_u64 v[152:153], s[16:17], 0, v[140:141]
	v_mul_lo_u32 v132, v132, s51
	v_mul_u32_u24_e32 v133, 0x210, v156
	v_lshlrev_b32_e32 v141, 8, v138
	v_add3_u32 v141, v132, v133, v141
	v_mad_u64_u32 v[132:133], s[16:17], v130, s52, 0
	v_mad_i32_i24 v147, v131, s50, v147
	v_mad_i32_i24 v131, v131, s52, v133
	v_lshl_or_b32 v130, v138, 7, v132
	v_ashrrev_i32_e32 v143, 31, v142
	v_lshl_add_u64 v[154:155], s[4:5], 0, v[130:131]
	s_add_i32 s57, s14, 0xfffff500
	s_mov_b64 s[14:15], -1
	s_branch .LBB0_1287

;     ...
;   for (int kt = 0; kt < nk; ++kt) {
;     const int kn = (kt + 1 < nk) ? kt + 1 : kt;
;     GW_LOAD2(kn * 64, kn * bkstep)
;     __builtin_amdgcn_sched_barrier(0);
;     __builtin_amdgcn_s_setprio(1);
; #pragma unroll
;     for (int st = 0; st < 4; ++st) {
;       bf16x8 a0 = *(const bf16x8*)(Ab + st * 32);
;       bf16x8 a1 = *(const bf16x8*)(Ab + 32 * LSTR + st * 32);
;       bf16x8 b0 = *(const bf16x8*)(Bb + st * 32);
;       bf16x8 b1 = *(const bf16x8*)(Bb + 32 * LSTR + st * 32);
;       bf16x8 b2 = *(const bf16x8*)(Bb + 64 * LSTR + st * 32);
;       bf16x8 b3 = *(const bf16x8*)(Bb + 96 * LSTR + st * 32);
;       acc[0][0] = mfma32(a0, b0, acc[0][0]);
;       acc[0][1] = mfma32(a0, b1, acc[0][1]);
;       acc[0][2] = mfma32(a0, b2, acc[0][2]);
;       acc[0][3] = mfma32(a0, b3, acc[0][3]);
;       acc[1][0] = mfma32(a1, b0, acc[1][0]);
;       acc[1][1] = mfma32(a1, b1, acc[1][1]);
;       acc[1][2] = mfma32(a1, b2, acc[1][2]);
;       acc[1][3] = mfma32(a1, b3, acc[1][3]);
;     }
;     __builtin_amdgcn_s_setprio(0);
;     __builtin_amdgcn_sched_barrier(0);
;     __syncthreads();
;     GW_STORE()
;     __syncthreads();
;   }
.LBB0_1715:
	s_setprio 1
	ds_read_b128 v[200:203], v130 offset:0
	ds_read_b128 v[212:215], v133 offset:18432
	ds_read_b128 v[216:219], v133 offset:23040
	ds_read_b128 v[224:227], v133 offset:27648
	ds_read_b128 v[228:231], v133 offset:32256
	ds_read_b128 v[208:211], v130 offset:4608
	s_waitcnt lgkmcnt(4)
	v_mfma_f32_32x32x16_bf16 v[114:129], v[200:203], v[212:215], v[114:129]
	ds_read_b128 v[204:207], v130 offset:32
	ds_read_b128 v[232:235], v133 offset:18464
	s_waitcnt lgkmcnt(5)
	v_mfma_f32_32x32x16_bf16 v[98:113], v[200:203], v[216:219], v[98:113]
	ds_read_b128 v[236:239], v133 offset:23072
	s_waitcnt lgkmcnt(5)
	v_mfma_f32_32x32x16_bf16 v[82:97], v[200:203], v[224:227], v[82:97]
	ds_read_b128 v[240:243], v133 offset:27680
	s_waitcnt lgkmcnt(5)
	v_mfma_f32_32x32x16_bf16 v[66:81], v[200:203], v[228:231], v[66:81]
	ds_read_b128 v[244:247], v133 offset:32288
	s_waitcnt lgkmcnt(5)
	v_mfma_f32_32x32x16_bf16 v[50:65], v[208:211], v[212:215], v[50:65]
	v_mfma_f32_32x32x16_bf16 v[34:49], v[208:211], v[216:219], v[34:49]
	v_mfma_f32_32x32x16_bf16 v[18:33], v[208:211], v[224:227], v[18:33]
	v_mfma_f32_32x32x16_bf16 v[2:17], v[208:211], v[228:231], v[2:17]
	ds_read_b128 v[208:211], v130 offset:4640
	s_waitcnt lgkmcnt(4)
	v_mfma_f32_32x32x16_bf16 v[114:129], v[204:207], v[232:235], v[114:129]
	ds_read_b128 v[200:203], v130 offset:64
	ds_read_b128 v[212:215], v133 offset:18496
	s_waitcnt lgkmcnt(5)
	v_mfma_f32_32x32x16_bf16 v[98:113], v[204:207], v[236:239], v[98:113]
	ds_read_b128 v[216:219], v133 offset:23104
	s_waitcnt lgkmcnt(5)
	v_mfma_f32_32x32x16_bf16 v[82:97], v[204:207], v[240:243], v[82:97]
	ds_read_b128 v[224:227], v133 offset:27712
	s_waitcnt lgkmcnt(5)
	v_mfma_f32_32x32x16_bf16 v[66:81], v[204:207], v[244:247], v[66:81]
	ds_read_b128 v[228:231], v133 offset:32320
	s_waitcnt lgkmcnt(5)
	v_mfma_f32_32x32x16_bf16 v[50:65], v[208:211], v[232:235], v[50:65]
	v_mfma_f32_32x32x16_bf16 v[34:49], v[208:211], v[236:239], v[34:49]
	v_mfma_f32_32x32x16_bf16 v[18:33], v[208:211], v[240:243], v[18:33]
	v_mfma_f32_32x32x16_bf16 v[2:17], v[208:211], v[244:247], v[2:17]
	ds_read_b128 v[208:211], v130 offset:4672
	s_waitcnt lgkmcnt(4)
	v_mfma_f32_32x32x16_bf16 v[114:129], v[200:203], v[212:215], v[114:129]
	ds_read_b128 v[204:207], v130 offset:96
	ds_read_b128 v[232:235], v133 offset:18528
	s_waitcnt lgkmcnt(5)
	v_mfma_f32_32x32x16_bf16 v[98:113], v[200:203], v[216:219], v[98:113]
	ds_read_b128 v[236:239], v133 offset:23136
	s_waitcnt lgkmcnt(5)
	v_mfma_f32_32x32x16_bf16 v[82:97], v[200:203], v[224:227], v[82:97]
	ds_read_b128 v[240:243], v133 offset:27744
	s_waitcnt lgkmcnt(5)
	v_mfma_f32_32x32x16_bf16 v[66:81], v[200:203], v[228:231], v[66:81]
	ds_read_b128 v[244:247], v133 offset:32352
	s_waitcnt lgkmcnt(5)
	v_mfma_f32_32x32x16_bf16 v[50:65], v[208:211], v[212:215], v[50:65]
	v_mfma_f32_32x32x16_bf16 v[34:49], v[208:211], v[216:219], v[34:49]
	v_mfma_f32_32x32x16_bf16 v[18:33], v[208:211], v[224:227], v[18:33]
	v_mfma_f32_32x32x16_bf16 v[2:17], v[208:211], v[228:231], v[2:17]
	ds_read_b128 v[208:211], v130 offset:4704
	s_waitcnt lgkmcnt(4)
	v_mfma_f32_32x32x16_bf16 v[114:129], v[204:207], v[232:235], v[114:129]
	s_waitcnt lgkmcnt(3)
	v_mfma_f32_32x32x16_bf16 v[98:113], v[204:207], v[236:239], v[98:113]
	s_waitcnt lgkmcnt(2)
	v_mfma_f32_32x32x16_bf16 v[82:97], v[204:207], v[240:243], v[82:97]
	s_waitcnt lgkmcnt(1)
	v_mfma_f32_32x32x16_bf16 v[66:81], v[204:207], v[244:247], v[66:81]
	s_waitcnt lgkmcnt(0)
	v_mfma_f32_32x32x16_bf16 v[50:65], v[208:211], v[232:235], v[50:65]
	v_mfma_f32_32x32x16_bf16 v[34:49], v[208:211], v[236:239], v[34:49]
	v_mfma_f32_32x32x16_bf16 v[18:33], v[208:211], v[240:243], v[18:33]
	v_mfma_f32_32x32x16_bf16 v[2:17], v[208:211], v[244:247], v[2:17]
	s_setprio 0
	s_add_u32 s14, s14, 0x80
	s_addc_u32 s15, s15, 0
	s_cmpk_lg_i32 s14, 0x700
	s_barrier
	s_waitcnt vmcnt(11)
	ds_write_b128 v132, v[152:155]
	v_lshl_add_u64 v[152:153], v[148:149], 0, s[14:15]
	v_add_co_u32_e32 v152, vcc, s37, v152
	s_nop 1
	v_addc_co_u32_e32 v153, vcc, 0, v153, vcc
	global_load_dwordx4 v[152:155], v[152:153], off offset:384
	s_waitcnt vmcnt(11)
	ds_write_b128 v132, v[156:159] offset:4608
	v_lshl_add_u64 v[156:157], v[148:149], 0, s[14:15]
	v_add_co_u32_e32 v156, vcc, s38, v156
	s_nop 1
	v_addc_co_u32_e32 v157, vcc, 0, v157, vcc
	global_load_dwordx4 v[156:159], v[156:157], off offset:384
	s_waitcnt vmcnt(11)
	ds_write_b128 v132, v[160:163] offset:9216
	v_lshl_add_u64 v[160:161], v[148:149], 0, s[14:15]
	v_add_co_u32_e32 v160, vcc, s39, v160
	s_nop 1
	v_addc_co_u32_e32 v161, vcc, 0, v161, vcc
	global_load_dwordx4 v[160:163], v[160:161], off offset:384
	s_waitcnt vmcnt(11)
	ds_write_b128 v132, v[164:167] offset:13824
	v_lshl_add_u64 v[164:165], v[148:149], 0, s[14:15]
	v_add_co_u32_e32 v164, vcc, s40, v164
	s_nop 1
	v_addc_co_u32_e32 v165, vcc, 0, v165, vcc
	global_load_dwordx4 v[164:167], v[164:165], off offset:384
	s_waitcnt vmcnt(11)
	ds_write_b128 v132, v[168:171] offset:18432
	v_lshl_add_u64 v[168:169], v[150:151], 0, s[14:15]
	v_add_co_u32_e32 v168, vcc, s41, v168
	s_nop 1
	v_addc_co_u32_e32 v169, vcc, 0, v169, vcc
	global_load_dwordx4 v[168:171], v[168:169], off offset:128
	s_waitcnt vmcnt(11)
	ds_write_b128 v132, v[172:175] offset:23040
	v_lshl_add_u64 v[172:173], v[150:151], 0, s[14:15]
	v_add_co_u32_e32 v172, vcc, s42, v172
	s_nop 1
	v_addc_co_u32_e32 v173, vcc, 0, v173, vcc
	global_load_dwordx4 v[172:175], v[172:173], off offset:128
	s_waitcnt vmcnt(11)
	ds_write_b128 v132, v[176:179] offset:27648
	v_lshl_add_u64 v[176:177], v[150:151], 0, s[14:15]
	v_add_co_u32_e32 v176, vcc, s43, v176
	s_nop 1
	v_addc_co_u32_e32 v177, vcc, 0, v177, vcc
	global_load_dwordx4 v[176:179], v[176:177], off offset:128
	s_waitcnt vmcnt(11)
;     ...
;   for (int kt = 0; kt < nk; ++kt) {
;     const int kn = (kt + 1 < nk) ? kt + 1 : kt;
;     GW_LOAD2(kn * 64, kn * bkstep)
;     __builtin_amdgcn_sched_barrier(0);
;     __builtin_amdgcn_s_setprio(1);
; #pragma unroll
;     for (int st = 0; st < 4; ++st) {
;       bf16x8 a0 = *(const bf16x8*)(Ab + st * 32);
;       bf16x8 a1 = *(const bf16x8*)(Ab + 32 * LSTR + st * 32);
;       bf16x8 b0 = *(const bf16x8*)(Bb + st * 32);
;       bf16x8 b1 = *(const bf16x8*)(Bb + 32 * LSTR + st * 32);
;       bf16x8 b2 = *(const bf16x8*)(Bb + 64 * LSTR + st * 32);
;       bf16x8 b3 = *(const bf16x8*)(Bb + 96 * LSTR + st * 32);
;       acc[0][0] = mfma32(a0, b0, acc[0][0]);
;       acc[0][1] = mfma32(a0, b1, acc[0][1]);
;       acc[0][2] = mfma32(a0, b2, acc[0][2]);
;       acc[0][3] = mfma32(a0, b3, acc[0][3]);
;       acc[1][0] = mfma32(a1, b0, acc[1][0]);
;       acc[1][1] = mfma32(a1, b1, acc[1][1]);
;       acc[1][2] = mfma32(a1, b2, acc[1][2]);
;       acc[1][3] = mfma32(a1, b3, acc[1][3]);
;     }
;     __builtin_amdgcn_s_setprio(0);
;     __builtin_amdgcn_sched_barrier(0);
;     __syncthreads();
;     GW_STORE()
;     __syncthreads();
;   }
	ds_write_b128 v132, v[180:183] offset:32256
	v_lshl_add_u64 v[180:181], v[150:151], 0, s[14:15]
	v_add_co_u32_e32 v180, vcc, s44, v180
	s_nop 1
	v_addc_co_u32_e32 v181, vcc, 0, v181, vcc
	global_load_dwordx4 v[180:183], v[180:181], off offset:128
	s_waitcnt vmcnt(11)
	ds_write_b128 v132, v[184:187] offset:36864
	v_lshl_add_u64 v[184:185], v[150:151], 0, s[14:15]
	v_add_co_u32_e32 v184, vcc, s45, v184
	s_nop 1
	v_addc_co_u32_e32 v185, vcc, 0, v185, vcc
	global_load_dwordx4 v[184:187], v[184:185], off offset:128
	s_waitcnt vmcnt(11)
	ds_write_b128 v132, v[188:191] offset:41472
	v_lshl_add_u64 v[188:189], v[150:151], 0, s[14:15]
	v_add_co_u32_e32 v188, vcc, s46, v188
	s_nop 1
	v_addc_co_u32_e32 v189, vcc, 0, v189, vcc
	global_load_dwordx4 v[188:191], v[188:189], off offset:128
	s_waitcnt vmcnt(11)
	ds_write_b128 v132, v[192:195] offset:46080
	v_lshl_add_u64 v[192:193], v[150:151], 0, s[14:15]
	v_add_co_u32_e32 v192, vcc, s47, v192
	s_nop 1
	v_addc_co_u32_e32 v193, vcc, 0, v193, vcc
	global_load_dwordx4 v[192:195], v[192:193], off offset:128
	s_waitcnt vmcnt(11)
	ds_write_b128 v132, v[196:199] offset:50688
	v_lshl_add_u64 v[196:197], v[150:151], 0, s[14:15]
	v_add_co_u32_e32 v196, vcc, s48, v196
	s_nop 1
	v_addc_co_u32_e32 v197, vcc, 0, v197, vcc
	global_load_dwordx4 v[196:199], v[196:197], off offset:128
	s_waitcnt lgkmcnt(0)
	s_barrier
	s_cbranch_scc1 .LBB0_1715
	s_setprio 1
	ds_read_b128 v[200:203], v130 offset:0
	ds_read_b128 v[212:215], v133 offset:18432
	ds_read_b128 v[216:219], v133 offset:23040
	ds_read_b128 v[224:227], v133 offset:27648
	ds_read_b128 v[228:231], v133 offset:32256
	ds_read_b128 v[208:211], v130 offset:4608
	s_waitcnt lgkmcnt(4)
	v_mfma_f32_32x32x16_bf16 v[114:129], v[200:203], v[212:215], v[114:129]
	ds_read_b128 v[204:207], v130 offset:32
	ds_read_b128 v[232:235], v133 offset:18464
	s_waitcnt lgkmcnt(5)
	v_mfma_f32_32x32x16_bf16 v[98:113], v[200:203], v[216:219], v[98:113]
	ds_read_b128 v[236:239], v133 offset:23072
	s_waitcnt lgkmcnt(5)
	v_mfma_f32_32x32x16_bf16 v[82:97], v[200:203], v[224:227], v[82:97]
	ds_read_b128 v[240:243], v133 offset:27680
	s_waitcnt lgkmcnt(5)
	v_mfma_f32_32x32x16_bf16 v[66:81], v[200:203], v[228:231], v[66:81]
	ds_read_b128 v[244:247], v133 offset:32288
	s_waitcnt lgkmcnt(5)
	v_mfma_f32_32x32x16_bf16 v[50:65], v[208:211], v[212:215], v[50:65]
	v_mfma_f32_32x32x16_bf16 v[34:49], v[208:211], v[216:219], v[34:49]
	v_mfma_f32_32x32x16_bf16 v[18:33], v[208:211], v[224:227], v[18:33]
	v_mfma_f32_32x32x16_bf16 v[2:17], v[208:211], v[228:231], v[2:17]
	ds_read_b128 v[208:211], v130 offset:4640
	s_waitcnt lgkmcnt(4)
	v_mfma_f32_32x32x16_bf16 v[114:129], v[204:207], v[232:235], v[114:129]
	ds_read_b128 v[200:203], v130 offset:64
	ds_read_b128 v[212:215], v133 offset:18496
	s_waitcnt lgkmcnt(5)
	v_mfma_f32_32x32x16_bf16 v[98:113], v[204:207], v[236:239], v[98:113]
	ds_read_b128 v[216:219], v133 offset:23104
	s_waitcnt lgkmcnt(5)
	v_mfma_f32_32x32x16_bf16 v[82:97], v[204:207], v[240:243], v[82:97]
	ds_read_b128 v[224:227], v133 offset:27712
	s_waitcnt lgkmcnt(5)
	v_mfma_f32_32x32x16_bf16 v[66:81], v[204:207], v[244:247], v[66:81]
	ds_read_b128 v[228:231], v133 offset:32320
	s_waitcnt lgkmcnt(5)
	v_mfma_f32_32x32x16_bf16 v[50:65], v[208:211], v[232:235], v[50:65]
	v_mfma_f32_32x32x16_bf16 v[34:49], v[208:211], v[236:239], v[34:49]
	v_mfma_f32_32x32x16_bf16 v[18:33], v[208:211], v[240:243], v[18:33]
	v_mfma_f32_32x32x16_bf16 v[2:17], v[208:211], v[244:247], v[2:17]
	ds_read_b128 v[208:211], v130 offset:4672
	s_waitcnt lgkmcnt(4)
	v_mfma_f32_32x32x16_bf16 v[114:129], v[200:203], v[212:215], v[114:129]
	ds_read_b128 v[204:207], v130 offset:96
	ds_read_b128 v[232:235], v133 offset:18528
	s_waitcnt lgkmcnt(5)
	v_mfma_f32_32x32x16_bf16 v[98:113], v[200:203], v[216:219], v[98:113]
	ds_read_b128 v[236:239], v133 offset:23136
	s_waitcnt lgkmcnt(5)
	v_mfma_f32_32x32x16_bf16 v[82:97], v[200:203], v[224:227], v[82:97]
	ds_read_b128 v[240:243], v133 offset:27744
	s_waitcnt lgkmcnt(5)
	v_mfma_f32_32x32x16_bf16 v[66:81], v[200:203], v[228:231], v[66:81]
	ds_read_b128 v[244:247], v133 offset:32352
	s_waitcnt lgkmcnt(5)
	v_mfma_f32_32x32x16_bf16 v[50:65], v[208:211], v[212:215], v[50:65]
	v_mfma_f32_32x32x16_bf16 v[34:49], v[208:211], v[216:219], v[34:49]
	v_mfma_f32_32x32x16_bf16 v[18:33], v[208:211], v[224:227], v[18:33]
	v_mfma_f32_32x32x16_bf16 v[2:17], v[208:211], v[228:231], v[2:17]
	ds_read_b128 v[208:211], v130 offset:4704
	s_waitcnt lgkmcnt(4)
	v_mfma_f32_32x32x16_bf16 v[114:129], v[204:207], v[232:235], v[114:129]
	s_waitcnt lgkmcnt(3)
	v_mfma_f32_32x32x16_bf16 v[98:113], v[204:207], v[236:239], v[98:113]
	s_waitcnt lgkmcnt(2)
	v_mfma_f32_32x32x16_bf16 v[82:97], v[204:207], v[240:243], v[82:97]
	s_waitcnt lgkmcnt(1)
	v_mfma_f32_32x32x16_bf16 v[66:81], v[204:207], v[244:247], v[66:81]
	s_waitcnt lgkmcnt(0)
	v_mfma_f32_32x32x16_bf16 v[50:65], v[208:211], v[232:235], v[50:65]
	v_mfma_f32_32x32x16_bf16 v[34:49], v[208:211], v[236:239], v[34:49]
	v_mfma_f32_32x32x16_bf16 v[18:33], v[208:211], v[240:243], v[18:33]
	v_mfma_f32_32x32x16_bf16 v[2:17], v[208:211], v[244:247], v[2:17]
	s_setprio 0
	s_add_u32 s14, s14, 0x80
	s_addc_u32 s15, s15, 0
	s_barrier
;     ...
;   for (int kt = 0; kt < nk; ++kt) {
;     const int kn = (kt + 1 < nk) ? kt + 1 : kt;
;     GW_LOAD2(kn * 64, kn * bkstep)
;     __builtin_amdgcn_sched_barrier(0);
;     __builtin_amdgcn_s_setprio(1);
; #pragma unroll
;     for (int st = 0; st < 4; ++st) {
;       bf16x8 a0 = *(const bf16x8*)(Ab + st * 32);
;       bf16x8 a1 = *(const bf16x8*)(Ab + 32 * LSTR + st * 32);
;       bf16x8 b0 = *(const bf16x8*)(Bb + st * 32);
;       bf16x8 b1 = *(const bf16x8*)(Bb + 32 * LSTR + st * 32);
;       bf16x8 b2 = *(const bf16x8*)(Bb + 64 * LSTR + st * 32);
;       bf16x8 b3 = *(const bf16x8*)(Bb + 96 * LSTR + st * 32);
;       acc[0][0] = mfma32(a0, b0, acc[0][0]);
;       acc[0][1] = mfma32(a0, b1, acc[0][1]);
;       acc[0][2] = mfma32(a0, b2, acc[0][2]);
;       acc[0][3] = mfma32(a0, b3, acc[0][3]);
;       acc[1][0] = mfma32(a1, b0, acc[1][0]);
;       acc[1][1] = mfma32(a1, b1, acc[1][1]);
;       acc[1][2] = mfma32(a1, b2, acc[1][2]);
;       acc[1][3] = mfma32(a1, b3, acc[1][3]);
;     }
;     __builtin_amdgcn_s_setprio(0);
;     __builtin_amdgcn_sched_barrier(0);
;     __syncthreads();
;     GW_STORE()
;     __syncthreads();
;   }
	s_waitcnt vmcnt(11)
	ds_write_b128 v132, v[152:155]
	s_waitcnt vmcnt(10)
	ds_write_b128 v132, v[156:159] offset:4608
	s_waitcnt vmcnt(9)
	ds_write_b128 v132, v[160:163] offset:9216
	s_waitcnt vmcnt(8)
	ds_write_b128 v132, v[164:167] offset:13824
	s_waitcnt vmcnt(7)
	ds_write_b128 v132, v[168:171] offset:18432
	s_waitcnt vmcnt(6)
	ds_write_b128 v132, v[172:175] offset:23040
	s_waitcnt vmcnt(5)
	ds_write_b128 v132, v[176:179] offset:27648
	s_waitcnt vmcnt(4)
	ds_write_b128 v132, v[180:183] offset:32256
	s_waitcnt vmcnt(3)
	ds_write_b128 v132, v[184:187] offset:36864
	s_waitcnt vmcnt(2)
	ds_write_b128 v132, v[188:191] offset:41472
	s_waitcnt vmcnt(1)
	ds_write_b128 v132, v[192:195] offset:46080
	s_waitcnt vmcnt(0)
	ds_write_b128 v132, v[196:199] offset:50688
	s_waitcnt lgkmcnt(0)
	s_barrier
	v_add_co_u32_e32 v160, vcc, 0x10000, v138
	s_nop 0
	s_nop 0
	s_nop 0
	v_addc_co_u32_e32 v161, vcc, 0, v139, vcc
	v_add_co_u32_e32 v164, vcc, 0x20000, v138
	s_nop 0
	v_addc_co_u32_e32 v165, vcc, 0, v139, vcc
	v_add_co_u32_e32 v168, vcc, 0x30000, v138
	s_lshl_b64 s[12:13], s[12:13], 7
	s_nop 0
	v_addc_co_u32_e32 v169, vcc, 0, v139, vcc
	v_add_co_u32_e32 v172, vcc, 0x40000, v138
	s_nop 0
	v_addc_co_u32_e32 v173, vcc, 0, v139, vcc
	v_add_co_u32_e32 v176, vcc, 0x50000, v138
	s_mov_b32 s53, 0
	s_nop 0
	v_addc_co_u32_e32 v177, vcc, 0, v139, vcc
	v_add_co_u32_e32 v180, vcc, 0x60000, v138
	s_nop 0
	v_addc_co_u32_e32 v181, vcc, 0, v139, vcc
	v_add_co_u32_e32 v138, vcc, 0x70000, v138
	s_nop 1
	v_addc_co_u32_e32 v139, vcc, 0, v139, vcc
	s_nop 0
	s_setprio 1
	ds_read_b128 v[188:191], v130 offset:0
	ds_read_b128 v[200:203], v133 offset:18432
	ds_read_b128 v[204:207], v133 offset:23040
	ds_read_b128 v[208:211], v133 offset:27648
	ds_read_b128 v[212:215], v133 offset:32256
	ds_read_b128 v[196:199], v130 offset:4608
	s_waitcnt lgkmcnt(4)
	v_mfma_f32_32x32x16_bf16 v[114:129], v[188:191], v[200:203], v[114:129]
	ds_read_b128 v[192:195], v130 offset:32
	ds_read_b128 v[216:219], v133 offset:18464
	s_waitcnt lgkmcnt(5)
	v_mfma_f32_32x32x16_bf16 v[98:113], v[188:191], v[204:207], v[98:113]
	ds_read_b128 v[224:227], v133 offset:23072
	s_waitcnt lgkmcnt(5)
	v_mfma_f32_32x32x16_bf16 v[82:97], v[188:191], v[208:211], v[82:97]
	ds_read_b128 v[228:231], v133 offset:27680
	s_waitcnt lgkmcnt(5)
	v_mfma_f32_32x32x16_bf16 v[66:81], v[188:191], v[212:215], v[66:81]
	ds_read_b128 v[232:235], v133 offset:32288
	s_waitcnt lgkmcnt(5)
	v_mfma_f32_32x32x16_bf16 v[50:65], v[196:199], v[200:203], v[50:65]
	v_mfma_f32_32x32x16_bf16 v[34:49], v[196:199], v[204:207], v[34:49]
	v_mfma_f32_32x32x16_bf16 v[18:33], v[196:199], v[208:211], v[18:33]
	v_mfma_f32_32x32x16_bf16 v[2:17], v[196:199], v[212:215], v[2:17]
	ds_read_b128 v[196:199], v130 offset:4640
	s_waitcnt lgkmcnt(4)
	v_mfma_f32_32x32x16_bf16 v[114:129], v[192:195], v[216:219], v[114:129]
	ds_read_b128 v[188:191], v130 offset:64
	ds_read_b128 v[200:203], v133 offset:18496
	s_waitcnt lgkmcnt(5)
	v_mfma_f32_32x32x16_bf16 v[98:113], v[192:195], v[224:227], v[98:113]
	ds_read_b128 v[204:207], v133 offset:23104
	s_waitcnt lgkmcnt(5)
	v_mfma_f32_32x32x16_bf16 v[82:97], v[192:195], v[228:231], v[82:97]
	ds_read_b128 v[208:211], v133 offset:27712
	s_waitcnt lgkmcnt(5)
	v_mfma_f32_32x32x16_bf16 v[66:81], v[192:195], v[232:235], v[66:81]
	ds_read_b128 v[212:215], v133 offset:32320
	s_waitcnt lgkmcnt(5)
	v_mfma_f32_32x32x16_bf16 v[50:65], v[196:199], v[216:219], v[50:65]
	v_mfma_f32_32x32x16_bf16 v[34:49], v[196:199], v[224:227], v[34:49]
	v_mfma_f32_32x32x16_bf16 v[18:33], v[196:199], v[228:231], v[18:33]
	v_mfma_f32_32x32x16_bf16 v[2:17], v[196:199], v[232:235], v[2:17]
	ds_read_b128 v[196:199], v130 offset:4672
	s_waitcnt lgkmcnt(4)
	v_mfma_f32_32x32x16_bf16 v[114:129], v[188:191], v[200:203], v[114:129]
	ds_read_b128 v[192:195], v130 offset:96
	ds_read_b128 v[216:219], v133 offset:18528
	s_waitcnt lgkmcnt(5)
	v_mfma_f32_32x32x16_bf16 v[98:113], v[188:191], v[204:207], v[98:113]
	ds_read_b128 v[224:227], v133 offset:23136
	s_waitcnt lgkmcnt(5)
	v_mfma_f32_32x32x16_bf16 v[82:97], v[188:191], v[208:211], v[82:97]
	ds_read_b128 v[228:231], v133 offset:27744
	s_waitcnt lgkmcnt(5)
	v_mfma_f32_32x32x16_bf16 v[66:81], v[188:191], v[212:215], v[66:81]
	ds_read_b128 v[232:235], v133 offset:32352
	s_waitcnt lgkmcnt(5)
	v_mfma_f32_32x32x16_bf16 v[50:65], v[196:199], v[200:203], v[50:65]
	v_mfma_f32_32x32x16_bf16 v[34:49], v[196:199], v[204:207], v[34:49]
	v_mfma_f32_32x32x16_bf16 v[18:33], v[196:199], v[208:211], v[18:33]
	v_mfma_f32_32x32x16_bf16 v[2:17], v[196:199], v[212:215], v[2:17]
	ds_read_b128 v[196:199], v130 offset:4704
	s_waitcnt lgkmcnt(4)
	v_mfma_f32_32x32x16_bf16 v[114:129], v[192:195], v[216:219], v[114:129]
	s_waitcnt lgkmcnt(3)
	v_mfma_f32_32x32x16_bf16 v[98:113], v[192:195], v[224:227], v[98:113]
	s_waitcnt lgkmcnt(2)
	v_mfma_f32_32x32x16_bf16 v[82:97], v[192:195], v[228:231], v[82:97]
	s_waitcnt lgkmcnt(1)
	v_mfma_f32_32x32x16_bf16 v[66:81], v[192:195], v[232:235], v[66:81]
	s_waitcnt lgkmcnt(0)
	v_mfma_f32_32x32x16_bf16 v[50:65], v[196:199], v[216:219], v[50:65]
	v_mfma_f32_32x32x16_bf16 v[34:49], v[196:199], v[224:227], v[34:49]
	v_mfma_f32_32x32x16_bf16 v[18:33], v[196:199], v[228:231], v[18:33]
	v_mfma_f32_32x32x16_bf16 v[2:17], v[196:199], v[232:235], v[2:17]
	s_setprio 0
	s_mov_b64 s[16:17], -1
	s_barrier
	s_waitcnt lgkmcnt(0)

;     ...
;   for (int kt = 0; kt < nk; ++kt) {
;     const int kn = (kt + 1 < nk) ? kt + 1 : kt;
;     GW_LOAD2(kn * 64, kn * bkstep)
;     __builtin_amdgcn_sched_barrier(0);
;     __builtin_amdgcn_s_setprio(1);
; #pragma unroll
;     for (int st = 0; st < 4; ++st) {
;       bf16x8 a0 = *(const bf16x8*)(Ab + st * 32);
;       bf16x8 a1 = *(const bf16x8*)(Ab + 32 * LSTR + st * 32);
;       bf16x8 b0 = *(const bf16x8*)(Bb + st * 32);
;       bf16x8 b1 = *(const bf16x8*)(Bb + 32 * LSTR + st * 32);
;       bf16x8 b2 = *(const bf16x8*)(Bb + 64 * LSTR + st * 32);
;       bf16x8 b3 = *(const bf16x8*)(Bb + 96 * LSTR + st * 32);
;       acc[0][0] = mfma32(a0, b0, acc[0][0]);
;       acc[0][1] = mfma32(a0, b1, acc[0][1]);
;       acc[0][2] = mfma32(a0, b2, acc[0][2]);
;       acc[0][3] = mfma32(a0, b3, acc[0][3]);
;       acc[1][0] = mfma32(a1, b0, acc[1][0]);
;       acc[1][1] = mfma32(a1, b1, acc[1][1]);
;       acc[1][2] = mfma32(a1, b2, acc[1][2]);
;       acc[1][3] = mfma32(a1, b3, acc[1][3]);
;     }
;     __builtin_amdgcn_s_setprio(0);
;     __builtin_amdgcn_sched_barrier(0);
;     __syncthreads();
;     GW_STORE()
;     __syncthreads();
;   }
; __device__ __forceinline__ void expert1_tile(const Params& P, int e, int mt, int ntw, char* smem) {
;     ...
;   const int* ridx = WSP(int, OFF_ROWIDX) + e * EROWS + mt * 128;
;   const u16* H = WSP(u16, OFF_H);
;   const u16* Bt = WSP(u16, OFF_WGU) + (size_t)e * 4096 * DM + (size_t)ntw * 256 * 64;
;   gemm_wide([&](int rr) { return H + (size_t)ridx[rr] * DM; }, Bt, 64, DM, smem, acc, 4096 * 64);
.LBB0_2065:
	s_setprio 1
	ds_read_b128 v[206:209], v133 offset:0
	ds_read_b128 v[218:221], v137 offset:18432
	ds_read_b128 v[224:227], v137 offset:23040
	ds_read_b128 v[228:231], v137 offset:27648
	ds_read_b128 v[232:235], v137 offset:32256
	ds_read_b128 v[214:217], v133 offset:4608
	s_waitcnt lgkmcnt(4)
	v_mfma_f32_32x32x16_bf16 v[114:129], v[206:209], v[218:221], v[114:129]
	ds_read_b128 v[210:213], v133 offset:32
	ds_read_b128 v[236:239], v137 offset:18464
	s_waitcnt lgkmcnt(5)
	v_mfma_f32_32x32x16_bf16 v[98:113], v[206:209], v[224:227], v[98:113]
	ds_read_b128 v[240:243], v137 offset:23072
	s_waitcnt lgkmcnt(5)
	v_mfma_f32_32x32x16_bf16 v[82:97], v[206:209], v[228:231], v[82:97]
	ds_read_b128 v[244:247], v137 offset:27680
	s_waitcnt lgkmcnt(5)
	v_mfma_f32_32x32x16_bf16 v[66:81], v[206:209], v[232:235], v[66:81]
	ds_read_b128 v[248:251], v137 offset:32288
	s_waitcnt lgkmcnt(5)
	v_mfma_f32_32x32x16_bf16 v[50:65], v[214:217], v[218:221], v[50:65]
	v_mfma_f32_32x32x16_bf16 v[34:49], v[214:217], v[224:227], v[34:49]
	v_mfma_f32_32x32x16_bf16 v[18:33], v[214:217], v[228:231], v[18:33]
	v_mfma_f32_32x32x16_bf16 v[2:17], v[214:217], v[232:235], v[2:17]
	ds_read_b128 v[214:217], v133 offset:4640
	s_waitcnt lgkmcnt(4)
	v_mfma_f32_32x32x16_bf16 v[114:129], v[210:213], v[236:239], v[114:129]
	ds_read_b128 v[206:209], v133 offset:64
	ds_read_b128 v[218:221], v137 offset:18496
	s_waitcnt lgkmcnt(5)
	v_mfma_f32_32x32x16_bf16 v[98:113], v[210:213], v[240:243], v[98:113]
	ds_read_b128 v[224:227], v137 offset:23104
	s_waitcnt lgkmcnt(5)
	v_mfma_f32_32x32x16_bf16 v[82:97], v[210:213], v[244:247], v[82:97]
	ds_read_b128 v[228:231], v137 offset:27712
	s_waitcnt lgkmcnt(5)
	v_mfma_f32_32x32x16_bf16 v[66:81], v[210:213], v[248:251], v[66:81]
	ds_read_b128 v[232:235], v137 offset:32320
	s_waitcnt lgkmcnt(5)
	v_mfma_f32_32x32x16_bf16 v[50:65], v[214:217], v[236:239], v[50:65]
	v_mfma_f32_32x32x16_bf16 v[34:49], v[214:217], v[240:243], v[34:49]
	v_mfma_f32_32x32x16_bf16 v[18:33], v[214:217], v[244:247], v[18:33]
	v_mfma_f32_32x32x16_bf16 v[2:17], v[214:217], v[248:251], v[2:17]
	ds_read_b128 v[214:217], v133 offset:4672
	s_waitcnt lgkmcnt(4)
	v_mfma_f32_32x32x16_bf16 v[114:129], v[206:209], v[218:221], v[114:129]
	ds_read_b128 v[210:213], v133 offset:96
	ds_read_b128 v[236:239], v137 offset:18528
	s_waitcnt lgkmcnt(5)
	v_mfma_f32_32x32x16_bf16 v[98:113], v[206:209], v[224:227], v[98:113]
	ds_read_b128 v[240:243], v137 offset:23136
	s_waitcnt lgkmcnt(5)
	v_mfma_f32_32x32x16_bf16 v[82:97], v[206:209], v[228:231], v[82:97]
	ds_read_b128 v[244:247], v137 offset:27744
	s_waitcnt lgkmcnt(5)
	v_mfma_f32_32x32x16_bf16 v[66:81], v[206:209], v[232:235], v[66:81]
	ds_read_b128 v[248:251], v137 offset:32352
	s_waitcnt lgkmcnt(5)
	v_mfma_f32_32x32x16_bf16 v[50:65], v[214:217], v[218:221], v[50:65]
	v_mfma_f32_32x32x16_bf16 v[34:49], v[214:217], v[224:227], v[34:49]
	v_mfma_f32_32x32x16_bf16 v[18:33], v[214:217], v[228:231], v[18:33]
	v_mfma_f32_32x32x16_bf16 v[2:17], v[214:217], v[232:235], v[2:17]
	ds_read_b128 v[214:217], v133 offset:4704
	s_waitcnt lgkmcnt(4)
	v_mfma_f32_32x32x16_bf16 v[114:129], v[210:213], v[236:239], v[114:129]
	s_waitcnt lgkmcnt(3)
	v_mfma_f32_32x32x16_bf16 v[98:113], v[210:213], v[240:243], v[98:113]
	s_waitcnt lgkmcnt(2)
	v_mfma_f32_32x32x16_bf16 v[82:97], v[210:213], v[244:247], v[82:97]
	s_waitcnt lgkmcnt(1)
	v_mfma_f32_32x32x16_bf16 v[66:81], v[210:213], v[248:251], v[66:81]
	s_waitcnt lgkmcnt(0)
	v_mfma_f32_32x32x16_bf16 v[50:65], v[214:217], v[236:239], v[50:65]
	v_mfma_f32_32x32x16_bf16 v[34:49], v[214:217], v[240:243], v[34:49]
	v_mfma_f32_32x32x16_bf16 v[18:33], v[214:217], v[244:247], v[18:33]
	v_mfma_f32_32x32x16_bf16 v[2:17], v[214:217], v[248:251], v[2:17]
	s_setprio 0
	s_add_i32 s41, s41, -1
	v_lshl_add_u64 v[148:149], v[148:149], 0, s[8:9]
	v_lshl_add_u64 v[150:151], v[150:151], 0, s[10:11]
	v_lshl_add_u64 v[152:153], v[152:153], 0, s[10:11]
	v_lshl_add_u64 v[154:155], v[154:155], 0, s[10:11]
	s_cmp_lg_u32 s41, 0
	v_lshl_add_u64 v[156:157], v[156:157], 0, s[10:11]
	s_barrier
	s_waitcnt vmcnt(11)
	ds_write_b128 v132, v[158:161]
	v_lshl_add_u64 v[158:159], v[150:151], 0, v[130:131]
	global_load_dwordx4 v[158:161], v[158:159], off
	s_waitcnt vmcnt(11)
	ds_write_b128 v132, v[162:165] offset:4608
	v_lshl_add_u64 v[162:163], v[152:153], 0, v[130:131]
	global_load_dwordx4 v[162:165], v[162:163], off
	s_waitcnt vmcnt(11)
	ds_write_b128 v132, v[166:169] offset:9216
	v_lshl_add_u64 v[166:167], v[154:155], 0, v[130:131]
	global_load_dwordx4 v[166:169], v[166:167], off
	s_waitcnt vmcnt(11)
	ds_write_b128 v132, v[170:173] offset:13824
	v_lshl_add_u64 v[170:171], v[156:157], 0, v[130:131]
	global_load_dwordx4 v[170:173], v[170:171], off
	s_waitcnt vmcnt(11)
	ds_write_b128 v132, v[174:177] offset:18432
	v_lshl_add_u64 v[174:175], v[148:149], 0, v[130:131]
	v_add_co_u32_e32 v174, vcc, s35, v174
	s_nop 1
	v_addc_co_u32_e32 v175, vcc, 0, v175, vcc
	global_load_dwordx4 v[174:177], v[174:175], off offset:-4096
	s_waitcnt vmcnt(11)
	ds_write_b128 v132, v[178:181] offset:23040
	v_lshl_add_u64 v[178:179], v[148:149], 0, v[130:131]
	v_add_co_u32_e32 v178, vcc, s35, v178
	s_nop 1
	v_addc_co_u32_e32 v179, vcc, 0, v179, vcc
	global_load_dwordx4 v[178:181], v[178:179], off
	s_waitcnt vmcnt(11)
	ds_write_b128 v132, v[182:185] offset:27648
	v_lshl_add_u64 v[182:183], v[148:149], 0, v[130:131]
	v_add_co_u32_e32 v182, vcc, s36, v182
	s_nop 1
	v_addc_co_u32_e32 v183, vcc, 0, v183, vcc
	global_load_dwordx4 v[182:185], v[182:183], off offset:-4096
	s_waitcnt vmcnt(11)
	ds_write_b128 v132, v[186:189] offset:32256
	v_lshl_add_u64 v[186:187], v[148:149], 0, v[130:131]
	v_add_co_u32_e32 v186, vcc, s36, v186
	s_nop 1
	v_addc_co_u32_e32 v187, vcc, 0, v187, vcc
	global_load_dwordx4 v[186:189], v[186:187], off
	s_waitcnt vmcnt(11)
	ds_write_b128 v132, v[190:193] offset:36864
	v_lshl_add_u64 v[190:191], v[148:149], 0, v[130:131]
	v_add_co_u32_e32 v190, vcc, s37, v190
	s_nop 1
	v_addc_co_u32_e32 v191, vcc, 0, v191, vcc
	global_load_dwordx4 v[190:193], v[190:191], off offset:-4096
	s_waitcnt vmcnt(11)
	ds_write_b128 v132, v[194:197] offset:41472
	v_lshl_add_u64 v[194:195], v[148:149], 0, v[130:131]
	v_add_co_u32_e32 v194, vcc, s37, v194
	s_nop 1
	v_addc_co_u32_e32 v195, vcc, 0, v195, vcc
	global_load_dwordx4 v[194:197], v[194:195], off
	s_waitcnt vmcnt(11)
	ds_write_b128 v132, v[198:201] offset:46080
	v_lshl_add_u64 v[198:199], v[148:149], 0, v[130:131]
	v_add_co_u32_e32 v198, vcc, s38, v198
	s_nop 1
	v_addc_co_u32_e32 v199, vcc, 0, v199, vcc
	global_load_dwordx4 v[198:201], v[198:199], off offset:-4096
	s_waitcnt vmcnt(11)
	ds_write_b128 v132, v[202:205] offset:50688
	v_lshl_add_u64 v[202:203], v[148:149], 0, v[130:131]
	v_add_co_u32_e32 v202, vcc, s38, v202
	s_nop 1
	v_addc_co_u32_e32 v203, vcc, 0, v203, vcc
	global_load_dwordx4 v[202:205], v[202:203], off
	s_waitcnt lgkmcnt(0)
	s_barrier
;     ...
;   for (int kt = 0; kt < nk; ++kt) {
;     const int kn = (kt + 1 < nk) ? kt + 1 : kt;
;     GW_LOAD2(kn * 64, kn * bkstep)
;     __builtin_amdgcn_sched_barrier(0);
;     __builtin_amdgcn_s_setprio(1);
; #pragma unroll
;     for (int st = 0; st < 4; ++st) {
;       bf16x8 a0 = *(const bf16x8*)(Ab + st * 32);
;       bf16x8 a1 = *(const bf16x8*)(Ab + 32 * LSTR + st * 32);
;       bf16x8 b0 = *(const bf16x8*)(Bb + st * 32);
;       bf16x8 b1 = *(const bf16x8*)(Bb + 32 * LSTR + st * 32);
;       bf16x8 b2 = *(const bf16x8*)(Bb + 64 * LSTR + st * 32);
;       bf16x8 b3 = *(const bf16x8*)(Bb + 96 * LSTR + st * 32);
;       acc[0][0] = mfma32(a0, b0, acc[0][0]);
;       acc[0][1] = mfma32(a0, b1, acc[0][1]);
;       acc[0][2] = mfma32(a0, b2, acc[0][2]);
;       acc[0][3] = mfma32(a0, b3, acc[0][3]);
;       acc[1][0] = mfma32(a1, b0, acc[1][0]);
;       acc[1][1] = mfma32(a1, b1, acc[1][1]);
;       acc[1][2] = mfma32(a1, b2, acc[1][2]);
;       acc[1][3] = mfma32(a1, b3, acc[1][3]);
;     }
;     __builtin_amdgcn_s_setprio(0);
;     __builtin_amdgcn_sched_barrier(0);
;     __syncthreads();
;     GW_STORE()
;     __syncthreads();
;   }
	s_cbranch_scc1 .LBB0_2065
	s_setprio 1
	ds_read_b128 v[206:209], v133 offset:0
	ds_read_b128 v[218:221], v137 offset:18432
	ds_read_b128 v[224:227], v137 offset:23040
	ds_read_b128 v[228:231], v137 offset:27648
	ds_read_b128 v[232:235], v137 offset:32256
	ds_read_b128 v[214:217], v133 offset:4608
	s_waitcnt lgkmcnt(4)
	v_mfma_f32_32x32x16_bf16 v[114:129], v[206:209], v[218:221], v[114:129]
	ds_read_b128 v[210:213], v133 offset:32
	ds_read_b128 v[236:239], v137 offset:18464
	s_waitcnt lgkmcnt(5)
	v_mfma_f32_32x32x16_bf16 v[98:113], v[206:209], v[224:227], v[98:113]
	ds_read_b128 v[240:243], v137 offset:23072
	s_waitcnt lgkmcnt(5)
	v_mfma_f32_32x32x16_bf16 v[82:97], v[206:209], v[228:231], v[82:97]
	ds_read_b128 v[244:247], v137 offset:27680
	s_waitcnt lgkmcnt(5)
	v_mfma_f32_32x32x16_bf16 v[66:81], v[206:209], v[232:235], v[66:81]
	ds_read_b128 v[248:251], v137 offset:32288
	s_waitcnt lgkmcnt(5)
	v_mfma_f32_32x32x16_bf16 v[50:65], v[214:217], v[218:221], v[50:65]
	v_mfma_f32_32x32x16_bf16 v[34:49], v[214:217], v[224:227], v[34:49]
	v_mfma_f32_32x32x16_bf16 v[18:33], v[214:217], v[228:231], v[18:33]
	v_mfma_f32_32x32x16_bf16 v[2:17], v[214:217], v[232:235], v[2:17]
	ds_read_b128 v[214:217], v133 offset:4640
	s_waitcnt lgkmcnt(4)
	v_mfma_f32_32x32x16_bf16 v[114:129], v[210:213], v[236:239], v[114:129]
	ds_read_b128 v[206:209], v133 offset:64
	ds_read_b128 v[218:221], v137 offset:18496
	s_waitcnt lgkmcnt(5)
	v_mfma_f32_32x32x16_bf16 v[98:113], v[210:213], v[240:243], v[98:113]
	ds_read_b128 v[224:227], v137 offset:23104
	s_waitcnt lgkmcnt(5)
	v_mfma_f32_32x32x16_bf16 v[82:97], v[210:213], v[244:247], v[82:97]
	ds_read_b128 v[228:231], v137 offset:27712
	s_waitcnt lgkmcnt(5)
	v_mfma_f32_32x32x16_bf16 v[66:81], v[210:213], v[248:251], v[66:81]
	ds_read_b128 v[232:235], v137 offset:32320
	s_waitcnt lgkmcnt(5)
	v_mfma_f32_32x32x16_bf16 v[50:65], v[214:217], v[236:239], v[50:65]
	v_mfma_f32_32x32x16_bf16 v[34:49], v[214:217], v[240:243], v[34:49]
	v_mfma_f32_32x32x16_bf16 v[18:33], v[214:217], v[244:247], v[18:33]
	v_mfma_f32_32x32x16_bf16 v[2:17], v[214:217], v[248:251], v[2:17]
	ds_read_b128 v[214:217], v133 offset:4672
	s_waitcnt lgkmcnt(4)
	v_mfma_f32_32x32x16_bf16 v[114:129], v[206:209], v[218:221], v[114:129]
	ds_read_b128 v[210:213], v133 offset:96
	ds_read_b128 v[236:239], v137 offset:18528
	s_waitcnt lgkmcnt(5)
	v_mfma_f32_32x32x16_bf16 v[98:113], v[206:209], v[224:227], v[98:113]
	ds_read_b128 v[240:243], v137 offset:23136
	s_waitcnt lgkmcnt(5)
	v_mfma_f32_32x32x16_bf16 v[82:97], v[206:209], v[228:231], v[82:97]
	ds_read_b128 v[244:247], v137 offset:27744
	s_waitcnt lgkmcnt(5)
	v_mfma_f32_32x32x16_bf16 v[66:81], v[206:209], v[232:235], v[66:81]
	ds_read_b128 v[248:251], v137 offset:32352
	s_waitcnt lgkmcnt(5)
	v_mfma_f32_32x32x16_bf16 v[50:65], v[214:217], v[218:221], v[50:65]
	v_mfma_f32_32x32x16_bf16 v[34:49], v[214:217], v[224:227], v[34:49]
	v_mfma_f32_32x32x16_bf16 v[18:33], v[214:217], v[228:231], v[18:33]
	v_mfma_f32_32x32x16_bf16 v[2:17], v[214:217], v[232:235], v[2:17]
	ds_read_b128 v[214:217], v133 offset:4704
	s_waitcnt lgkmcnt(4)
	v_mfma_f32_32x32x16_bf16 v[114:129], v[210:213], v[236:239], v[114:129]
	s_waitcnt lgkmcnt(3)
	v_mfma_f32_32x32x16_bf16 v[98:113], v[210:213], v[240:243], v[98:113]
	s_waitcnt lgkmcnt(2)
	v_mfma_f32_32x32x16_bf16 v[82:97], v[210:213], v[244:247], v[82:97]
	s_waitcnt lgkmcnt(1)
	v_mfma_f32_32x32x16_bf16 v[66:81], v[210:213], v[248:251], v[66:81]
	s_waitcnt lgkmcnt(0)
	v_mfma_f32_32x32x16_bf16 v[50:65], v[214:217], v[236:239], v[50:65]
	v_mfma_f32_32x32x16_bf16 v[34:49], v[214:217], v[240:243], v[34:49]
	v_mfma_f32_32x32x16_bf16 v[18:33], v[214:217], v[244:247], v[18:33]
	v_mfma_f32_32x32x16_bf16 v[2:17], v[214:217], v[248:251], v[2:17]
	s_setprio 0
	v_lshl_add_u64 v[148:149], v[148:149], 0, s[8:9]
	v_lshl_add_u64 v[150:151], v[150:151], 0, s[10:11]
	v_lshl_add_u64 v[152:153], v[152:153], 0, s[10:11]
	v_lshl_add_u64 v[154:155], v[154:155], 0, s[10:11]
	v_lshl_add_u64 v[156:157], v[156:157], 0, s[10:11]
	s_barrier
	s_waitcnt vmcnt(11)
	ds_write_b128 v132, v[158:161]
	s_waitcnt vmcnt(10)
	ds_write_b128 v132, v[162:165] offset:4608
	s_waitcnt vmcnt(9)
	ds_write_b128 v132, v[166:169] offset:9216
	s_waitcnt vmcnt(8)
	ds_write_b128 v132, v[170:173] offset:13824
	s_waitcnt vmcnt(7)
	ds_write_b128 v132, v[174:177] offset:18432
	s_waitcnt vmcnt(6)
	ds_write_b128 v132, v[178:181] offset:23040
	s_waitcnt vmcnt(5)
	ds_write_b128 v132, v[182:185] offset:27648
	s_waitcnt vmcnt(4)
	ds_write_b128 v132, v[186:189] offset:32256
	s_waitcnt vmcnt(3)
	ds_write_b128 v132, v[190:193] offset:36864
	s_waitcnt vmcnt(2)
	ds_write_b128 v132, v[194:197] offset:41472
	s_waitcnt vmcnt(1)
	ds_write_b128 v132, v[198:201] offset:46080
	s_waitcnt vmcnt(0)
	ds_write_b128 v132, v[202:205] offset:50688
	s_waitcnt lgkmcnt(0)
	s_barrier
;     ...
;   for (int kt = 0; kt < nk; ++kt) {
;     const int kn = (kt + 1 < nk) ? kt + 1 : kt;
;     GW_LOAD2(kn * 64, kn * bkstep)
;     __builtin_amdgcn_sched_barrier(0);
;     __builtin_amdgcn_s_setprio(1);
; #pragma unroll
;     for (int st = 0; st < 4; ++st) {
;       bf16x8 a0 = *(const bf16x8*)(Ab + st * 32);
;       bf16x8 a1 = *(const bf16x8*)(Ab + 32 * LSTR + st * 32);
;       bf16x8 b0 = *(const bf16x8*)(Bb + st * 32);
;       bf16x8 b1 = *(const bf16x8*)(Bb + 32 * LSTR + st * 32);
;       bf16x8 b2 = *(const bf16x8*)(Bb + 64 * LSTR + st * 32);
;       bf16x8 b3 = *(const bf16x8*)(Bb + 96 * LSTR + st * 32);
;       acc[0][0] = mfma32(a0, b0, acc[0][0]);
;       acc[0][1] = mfma32(a0, b1, acc[0][1]);
;       acc[0][2] = mfma32(a0, b2, acc[0][2]);
;       acc[0][3] = mfma32(a0, b3, acc[0][3]);
;       acc[1][0] = mfma32(a1, b0, acc[1][0]);
;       acc[1][1] = mfma32(a1, b1, acc[1][1]);
;       acc[1][2] = mfma32(a1, b2, acc[1][2]);
;       acc[1][3] = mfma32(a1, b3, acc[1][3]);
;     }
;     __builtin_amdgcn_s_setprio(0);
;     __builtin_amdgcn_sched_barrier(0);
;     __syncthreads();
;     GW_STORE()
;     __syncthreads();
;   }
; __device__ __forceinline__ void expert1_tile(const Params& P, int e, int mt, int ntw, char* smem) {
;     ...
;   float* cs = (float*)smem;
;   int tid_ = threadIdx.x;
;   asm volatile("" : "+v"(tid_));
;   const int lane = tid_ & 63, wave = tid_ >> 6;
;   const int r = 32 * wave + (lane & 31), part = lane >> 5;
; #pragma unroll 1
;   for (int h = 0; h < 2; ++h) {
;     wide_acc_to_lds(acc, cs, h);
;     u16* dst = WSP(u16, OFF_HID) + ((size_t)e * EROWS + mt * 128 + r) * 2048 + (ntw * 2 + h) * 64 + part * 32;
	v_add_co_u32_e32 v156, vcc, 0x780000, v138
	s_nop 0
	s_nop 0
	s_nop 0
	v_addc_co_u32_e32 v157, vcc, 0, v139, vcc
	v_add_co_u32_e32 v160, vcc, 0x781000, v138
	s_mov_b32 s18, 0
	s_nop 0
	v_addc_co_u32_e32 v161, vcc, 0, v139, vcc
	v_add_co_u32_e32 v164, vcc, 0x782000, v138
	s_nop 0
	v_addc_co_u32_e32 v165, vcc, 0, v139, vcc
	v_add_co_u32_e32 v168, vcc, 0x783000, v138
	s_nop 1
	v_addc_co_u32_e32 v169, vcc, 0, v139, vcc
	v_add_co_u32_e32 v172, vcc, 0x784000, v138
	s_nop 0
	v_addc_co_u32_e32 v173, vcc, 0, v139, vcc
	v_add_co_u32_e32 v176, vcc, 0x785000, v138
	s_nop 1
	v_addc_co_u32_e32 v177, vcc, 0, v139, vcc
	v_add_co_u32_e32 v180, vcc, 0x786000, v138
	s_nop 0
	v_addc_co_u32_e32 v181, vcc, 0, v139, vcc
	v_add_co_u32_e32 v138, vcc, 0x787000, v138
	s_nop 1
	v_addc_co_u32_e32 v139, vcc, 0, v139, vcc
	s_nop 0
	s_setprio 1
	ds_read_b128 v[188:191], v133 offset:0
	ds_read_b128 v[200:203], v137 offset:18432
	ds_read_b128 v[204:207], v137 offset:23040
	ds_read_b128 v[208:211], v137 offset:27648
	ds_read_b128 v[212:215], v137 offset:32256
	ds_read_b128 v[196:199], v133 offset:4608
	s_waitcnt lgkmcnt(4)
	v_mfma_f32_32x32x16_bf16 v[114:129], v[188:191], v[200:203], v[114:129]
	ds_read_b128 v[192:195], v133 offset:32
	ds_read_b128 v[216:219], v137 offset:18464
	s_waitcnt lgkmcnt(5)
	v_mfma_f32_32x32x16_bf16 v[98:113], v[188:191], v[204:207], v[98:113]
	ds_read_b128 v[224:227], v137 offset:23072
	s_waitcnt lgkmcnt(5)
	v_mfma_f32_32x32x16_bf16 v[82:97], v[188:191], v[208:211], v[82:97]
	ds_read_b128 v[228:231], v137 offset:27680
	s_waitcnt lgkmcnt(5)
	v_mfma_f32_32x32x16_bf16 v[66:81], v[188:191], v[212:215], v[66:81]
	ds_read_b128 v[232:235], v137 offset:32288
	s_waitcnt lgkmcnt(5)
	v_mfma_f32_32x32x16_bf16 v[50:65], v[196:199], v[200:203], v[50:65]
	v_mfma_f32_32x32x16_bf16 v[34:49], v[196:199], v[204:207], v[34:49]
	v_mfma_f32_32x32x16_bf16 v[18:33], v[196:199], v[208:211], v[18:33]
	v_mfma_f32_32x32x16_bf16 v[2:17], v[196:199], v[212:215], v[2:17]
	ds_read_b128 v[196:199], v133 offset:4640
	s_waitcnt lgkmcnt(4)
	v_mfma_f32_32x32x16_bf16 v[114:129], v[192:195], v[216:219], v[114:129]
	ds_read_b128 v[188:191], v133 offset:64
	ds_read_b128 v[200:203], v137 offset:18496
	s_waitcnt lgkmcnt(5)
	v_mfma_f32_32x32x16_bf16 v[98:113], v[192:195], v[224:227], v[98:113]
	ds_read_b128 v[204:207], v137 offset:23104
	s_waitcnt lgkmcnt(5)
	v_mfma_f32_32x32x16_bf16 v[82:97], v[192:195], v[228:231], v[82:97]
	ds_read_b128 v[208:211], v137 offset:27712
	s_waitcnt lgkmcnt(5)
	v_mfma_f32_32x32x16_bf16 v[66:81], v[192:195], v[232:235], v[66:81]
	ds_read_b128 v[212:215], v137 offset:32320
	s_waitcnt lgkmcnt(5)
	v_mfma_f32_32x32x16_bf16 v[50:65], v[196:199], v[216:219], v[50:65]
	v_mfma_f32_32x32x16_bf16 v[34:49], v[196:199], v[224:227], v[34:49]
	v_mfma_f32_32x32x16_bf16 v[18:33], v[196:199], v[228:231], v[18:33]
	v_mfma_f32_32x32x16_bf16 v[2:17], v[196:199], v[232:235], v[2:17]
	ds_read_b128 v[196:199], v133 offset:4672
	s_waitcnt lgkmcnt(4)
	v_mfma_f32_32x32x16_bf16 v[114:129], v[188:191], v[200:203], v[114:129]
	ds_read_b128 v[192:195], v133 offset:96
	ds_read_b128 v[216:219], v137 offset:18528
	s_waitcnt lgkmcnt(5)
	v_mfma_f32_32x32x16_bf16 v[98:113], v[188:191], v[204:207], v[98:113]
	ds_read_b128 v[224:227], v137 offset:23136
	s_waitcnt lgkmcnt(5)
	v_mfma_f32_32x32x16_bf16 v[82:97], v[188:191], v[208:211], v[82:97]
	ds_read_b128 v[228:231], v137 offset:27744
	s_waitcnt lgkmcnt(5)
	v_mfma_f32_32x32x16_bf16 v[66:81], v[188:191], v[212:215], v[66:81]
	ds_read_b128 v[232:235], v137 offset:32352
	s_waitcnt lgkmcnt(5)
	v_mfma_f32_32x32x16_bf16 v[50:65], v[196:199], v[200:203], v[50:65]
	v_mfma_f32_32x32x16_bf16 v[34:49], v[196:199], v[204:207], v[34:49]
	v_mfma_f32_32x32x16_bf16 v[18:33], v[196:199], v[208:211], v[18:33]
	v_mfma_f32_32x32x16_bf16 v[2:17], v[196:199], v[212:215], v[2:17]
	ds_read_b128 v[196:199], v133 offset:4704
	s_waitcnt lgkmcnt(4)
	v_mfma_f32_32x32x16_bf16 v[114:129], v[192:195], v[216:219], v[114:129]
	s_waitcnt lgkmcnt(3)
	v_mfma_f32_32x32x16_bf16 v[98:113], v[192:195], v[224:227], v[98:113]
	s_waitcnt lgkmcnt(2)
	v_mfma_f32_32x32x16_bf16 v[82:97], v[192:195], v[228:231], v[82:97]
	s_waitcnt lgkmcnt(1)
	v_mfma_f32_32x32x16_bf16 v[66:81], v[192:195], v[232:235], v[66:81]
	s_waitcnt lgkmcnt(0)
	v_mfma_f32_32x32x16_bf16 v[50:65], v[196:199], v[216:219], v[50:65]
	v_mfma_f32_32x32x16_bf16 v[34:49], v[196:199], v[224:227], v[34:49]
	v_mfma_f32_32x32x16_bf16 v[18:33], v[196:199], v[228:231], v[18:33]
	v_mfma_f32_32x32x16_bf16 v[2:17], v[196:199], v[232:235], v[2:17]
	s_setprio 0
	v_mov_b32_e32 v130, v134
	s_barrier
	s_waitcnt lgkmcnt(0)
	s_mul_hi_i32 s13, s14, 0x1100
	v_ashrrev_i32_e32 v132, 1, v130
	s_mulk_i32 s14, 0x1100
	v_bfi_b32 v132, s39, v132, v130
	s_add_u32 s14, s14, s16
	s_addc_u32 s15, s13, s17
	v_ashrrev_i32_e32 v133, 31, v132
	v_lshl_add_u64 v[138:139], s[14:15], 0, v[132:133]
	v_and_b32_e32 v130, 32, v130
	v_lshlrev_b64 v[138:139], 12, v[138:139]
	v_mul_lo_u32 v132, v132, s22
	v_lshl_add_u32 v137, v130, 2, v132
	v_lshl_add_u64 v[132:133], s[4:5], 0, v[138:139]
	v_lshlrev_b32_e32 v130, 1, v130
	s_lshl_b32 s16, s12, 7
	v_lshl_add_u64 v[132:133], v[132:133], 0, v[130:131]
	s_mov_b64 s[12:13], -1
	s_branch .LBB0_2068

;     ...
;   for (int kt = 0; kt < nk; ++kt) {
;     const int kn = (kt + 1 < nk) ? kt + 1 : kt;
;     GW_LOAD2(kn * 64, kn * bkstep)
;     __builtin_amdgcn_sched_barrier(0);
;     __builtin_amdgcn_s_setprio(1);
; #pragma unroll
;     for (int st = 0; st < 4; ++st) {
;       bf16x8 a0 = *(const bf16x8*)(Ab + st * 32);
;       bf16x8 a1 = *(const bf16x8*)(Ab + 32 * LSTR + st * 32);
;       bf16x8 b0 = *(const bf16x8*)(Bb + st * 32);
;       bf16x8 b1 = *(const bf16x8*)(Bb + 32 * LSTR + st * 32);
;       bf16x8 b2 = *(const bf16x8*)(Bb + 64 * LSTR + st * 32);
;       bf16x8 b3 = *(const bf16x8*)(Bb + 96 * LSTR + st * 32);
;       acc[0][0] = mfma32(a0, b0, acc[0][0]);
;       acc[0][1] = mfma32(a0, b1, acc[0][1]);
;       acc[0][2] = mfma32(a0, b2, acc[0][2]);
;       acc[0][3] = mfma32(a0, b3, acc[0][3]);
;       acc[1][0] = mfma32(a1, b0, acc[1][0]);
;       acc[1][1] = mfma32(a1, b1, acc[1][1]);
;       acc[1][2] = mfma32(a1, b2, acc[1][2]);
;       acc[1][3] = mfma32(a1, b3, acc[1][3]);
;     }
;     __builtin_amdgcn_s_setprio(0);
;     __builtin_amdgcn_sched_barrier(0);
;     __syncthreads();
;     GW_STORE()
;     __syncthreads();
;   }
; __device__ __forceinline__ void expert2_tile(const Params& P, int e, int mt, int ntw, char* smem) {
;     ...
;   const u16* A = WSP(u16, OFF_HID) + ((size_t)e * EROWS + mt * 128) * 2048;
;   const u16* Bt = WSP(u16, OFF_WDN) + (size_t)e * DM * 2048 + (size_t)ntw * 256 * 64;
;   gemm_wide([&](int rr) { return A + (size_t)rr * 2048; }, Bt, 64, 2048, smem, acc, 1024 * 64);
.LBB0_2143:
	s_setprio 1
	ds_read_b128 v[200:203], v133 offset:0
	ds_read_b128 v[212:215], v137 offset:18432
	ds_read_b128 v[216:219], v137 offset:23040
	ds_read_b128 v[224:227], v137 offset:27648
	ds_read_b128 v[228:231], v137 offset:32256
	ds_read_b128 v[208:211], v133 offset:4608
	s_waitcnt lgkmcnt(4)
	v_mfma_f32_32x32x16_bf16 v[114:129], v[200:203], v[212:215], v[114:129]
	ds_read_b128 v[204:207], v133 offset:32
	ds_read_b128 v[232:235], v137 offset:18464
	s_waitcnt lgkmcnt(5)
	v_mfma_f32_32x32x16_bf16 v[98:113], v[200:203], v[216:219], v[98:113]
	ds_read_b128 v[236:239], v137 offset:23072
	s_waitcnt lgkmcnt(5)
	v_mfma_f32_32x32x16_bf16 v[82:97], v[200:203], v[224:227], v[82:97]
	ds_read_b128 v[240:243], v137 offset:27680
	s_waitcnt lgkmcnt(5)
	v_mfma_f32_32x32x16_bf16 v[66:81], v[200:203], v[228:231], v[66:81]
	ds_read_b128 v[244:247], v137 offset:32288
	s_waitcnt lgkmcnt(5)
	v_mfma_f32_32x32x16_bf16 v[50:65], v[208:211], v[212:215], v[50:65]
	v_mfma_f32_32x32x16_bf16 v[34:49], v[208:211], v[216:219], v[34:49]
	v_mfma_f32_32x32x16_bf16 v[18:33], v[208:211], v[224:227], v[18:33]
	v_mfma_f32_32x32x16_bf16 v[2:17], v[208:211], v[228:231], v[2:17]
	ds_read_b128 v[208:211], v133 offset:4640
	s_waitcnt lgkmcnt(4)
	v_mfma_f32_32x32x16_bf16 v[114:129], v[204:207], v[232:235], v[114:129]
	ds_read_b128 v[200:203], v133 offset:64
	ds_read_b128 v[212:215], v137 offset:18496
	s_waitcnt lgkmcnt(5)
	v_mfma_f32_32x32x16_bf16 v[98:113], v[204:207], v[236:239], v[98:113]
	ds_read_b128 v[216:219], v137 offset:23104
	s_waitcnt lgkmcnt(5)
	v_mfma_f32_32x32x16_bf16 v[82:97], v[204:207], v[240:243], v[82:97]
	ds_read_b128 v[224:227], v137 offset:27712
	s_waitcnt lgkmcnt(5)
	v_mfma_f32_32x32x16_bf16 v[66:81], v[204:207], v[244:247], v[66:81]
	ds_read_b128 v[228:231], v137 offset:32320
	s_waitcnt lgkmcnt(5)
	v_mfma_f32_32x32x16_bf16 v[50:65], v[208:211], v[232:235], v[50:65]
	v_mfma_f32_32x32x16_bf16 v[34:49], v[208:211], v[236:239], v[34:49]
	v_mfma_f32_32x32x16_bf16 v[18:33], v[208:211], v[240:243], v[18:33]
	v_mfma_f32_32x32x16_bf16 v[2:17], v[208:211], v[244:247], v[2:17]
	ds_read_b128 v[208:211], v133 offset:4672
	s_waitcnt lgkmcnt(4)
	v_mfma_f32_32x32x16_bf16 v[114:129], v[200:203], v[212:215], v[114:129]
	ds_read_b128 v[204:207], v133 offset:96
	ds_read_b128 v[232:235], v137 offset:18528
	s_waitcnt lgkmcnt(5)
	v_mfma_f32_32x32x16_bf16 v[98:113], v[200:203], v[216:219], v[98:113]
	ds_read_b128 v[236:239], v137 offset:23136
	s_waitcnt lgkmcnt(5)
	v_mfma_f32_32x32x16_bf16 v[82:97], v[200:203], v[224:227], v[82:97]
	ds_read_b128 v[240:243], v137 offset:27744
	s_waitcnt lgkmcnt(5)
	v_mfma_f32_32x32x16_bf16 v[66:81], v[200:203], v[228:231], v[66:81]
	ds_read_b128 v[244:247], v137 offset:32352
	s_waitcnt lgkmcnt(5)
	v_mfma_f32_32x32x16_bf16 v[50:65], v[208:211], v[212:215], v[50:65]
	v_mfma_f32_32x32x16_bf16 v[34:49], v[208:211], v[216:219], v[34:49]
	v_mfma_f32_32x32x16_bf16 v[18:33], v[208:211], v[224:227], v[18:33]
	v_mfma_f32_32x32x16_bf16 v[2:17], v[208:211], v[228:231], v[2:17]
	ds_read_b128 v[208:211], v133 offset:4704
	s_waitcnt lgkmcnt(4)
	v_mfma_f32_32x32x16_bf16 v[114:129], v[204:207], v[232:235], v[114:129]
	s_waitcnt lgkmcnt(3)
	v_mfma_f32_32x32x16_bf16 v[98:113], v[204:207], v[236:239], v[98:113]
	s_waitcnt lgkmcnt(2)
	v_mfma_f32_32x32x16_bf16 v[82:97], v[204:207], v[240:243], v[82:97]
	s_waitcnt lgkmcnt(1)
	v_mfma_f32_32x32x16_bf16 v[66:81], v[204:207], v[244:247], v[66:81]
	s_waitcnt lgkmcnt(0)
	v_mfma_f32_32x32x16_bf16 v[50:65], v[208:211], v[232:235], v[50:65]
	v_mfma_f32_32x32x16_bf16 v[34:49], v[208:211], v[236:239], v[34:49]
	v_mfma_f32_32x32x16_bf16 v[18:33], v[208:211], v[240:243], v[18:33]
	v_mfma_f32_32x32x16_bf16 v[2:17], v[208:211], v[244:247], v[2:17]
	s_setprio 0
	s_add_i32 s15, s15, -1
	v_lshl_add_u64 v[148:149], v[148:149], 0, s[4:5]
	s_cmp_lg_u32 s15, 0
	v_lshl_add_u64 v[150:151], v[150:151], 0, s[10:11]
	s_barrier
	s_waitcnt vmcnt(11)
	ds_write_b128 v132, v[152:155]
	v_lshl_add_u64 v[152:153], v[150:151], 0, v[130:131]
	v_add_co_u32_e32 v152, vcc, s37, v152
	s_nop 1
	v_addc_co_u32_e32 v153, vcc, 0, v153, vcc
	global_load_dwordx4 v[152:155], v[152:153], off offset:384
	s_waitcnt vmcnt(11)
	ds_write_b128 v132, v[156:159] offset:4608
	v_lshl_add_u64 v[156:157], v[150:151], 0, v[130:131]
	v_add_co_u32_e32 v156, vcc, s38, v156
	s_nop 1
	v_addc_co_u32_e32 v157, vcc, 0, v157, vcc
	global_load_dwordx4 v[156:159], v[156:157], off offset:384
	s_waitcnt vmcnt(11)
	ds_write_b128 v132, v[160:163] offset:9216
	v_lshl_add_u64 v[160:161], v[150:151], 0, v[130:131]
	v_add_co_u32_e32 v160, vcc, s39, v160
	s_nop 1
	v_addc_co_u32_e32 v161, vcc, 0, v161, vcc
	global_load_dwordx4 v[160:163], v[160:161], off offset:384
	s_waitcnt vmcnt(11)
	ds_write_b128 v132, v[164:167] offset:13824
	v_lshl_add_u64 v[164:165], v[150:151], 0, v[130:131]
	v_add_co_u32_e32 v164, vcc, s40, v164
	s_nop 1
	v_addc_co_u32_e32 v165, vcc, 0, v165, vcc
	global_load_dwordx4 v[164:167], v[164:165], off offset:384
	s_waitcnt vmcnt(11)
	ds_write_b128 v132, v[168:171] offset:18432
	v_lshl_add_u64 v[168:169], v[148:149], 0, v[130:131]
	v_add_co_u32_e32 v168, vcc, s41, v168
	s_nop 1
	v_addc_co_u32_e32 v169, vcc, 0, v169, vcc
	global_load_dwordx4 v[168:171], v[168:169], off offset:-4096
	s_waitcnt vmcnt(11)
	ds_write_b128 v132, v[172:175] offset:23040
	v_lshl_add_u64 v[172:173], v[148:149], 0, v[130:131]
	v_add_co_u32_e32 v172, vcc, s41, v172
	s_nop 1
	v_addc_co_u32_e32 v173, vcc, 0, v173, vcc
	global_load_dwordx4 v[172:175], v[172:173], off
	s_waitcnt vmcnt(11)
;     ...
;   for (int kt = 0; kt < nk; ++kt) {
;     const int kn = (kt + 1 < nk) ? kt + 1 : kt;
;     GW_LOAD2(kn * 64, kn * bkstep)
;     __builtin_amdgcn_sched_barrier(0);
;     __builtin_amdgcn_s_setprio(1);
; #pragma unroll
;     for (int st = 0; st < 4; ++st) {
;       bf16x8 a0 = *(const bf16x8*)(Ab + st * 32);
;       bf16x8 a1 = *(const bf16x8*)(Ab + 32 * LSTR + st * 32);
;       bf16x8 b0 = *(const bf16x8*)(Bb + st * 32);
;       bf16x8 b1 = *(const bf16x8*)(Bb + 32 * LSTR + st * 32);
;       bf16x8 b2 = *(const bf16x8*)(Bb + 64 * LSTR + st * 32);
;       bf16x8 b3 = *(const bf16x8*)(Bb + 96 * LSTR + st * 32);
;       acc[0][0] = mfma32(a0, b0, acc[0][0]);
;       acc[0][1] = mfma32(a0, b1, acc[0][1]);
;       acc[0][2] = mfma32(a0, b2, acc[0][2]);
;       acc[0][3] = mfma32(a0, b3, acc[0][3]);
;       acc[1][0] = mfma32(a1, b0, acc[1][0]);
;       acc[1][1] = mfma32(a1, b1, acc[1][1]);
;       acc[1][2] = mfma32(a1, b2, acc[1][2]);
;       acc[1][3] = mfma32(a1, b3, acc[1][3]);
;     }
;     __builtin_amdgcn_s_setprio(0);
;     __builtin_amdgcn_sched_barrier(0);
;     __syncthreads();
;     GW_STORE()
;     __syncthreads();
;   }
	ds_write_b128 v132, v[176:179] offset:27648
	v_lshl_add_u64 v[176:177], v[148:149], 0, v[130:131]
	v_add_co_u32_e32 v176, vcc, s42, v176
	s_nop 1
	v_addc_co_u32_e32 v177, vcc, 0, v177, vcc
	global_load_dwordx4 v[176:179], v[176:177], off offset:-4096
	s_waitcnt vmcnt(11)
	ds_write_b128 v132, v[180:183] offset:32256
	v_lshl_add_u64 v[180:181], v[148:149], 0, v[130:131]
	v_add_co_u32_e32 v180, vcc, s42, v180
	s_nop 1
	v_addc_co_u32_e32 v181, vcc, 0, v181, vcc
	global_load_dwordx4 v[180:183], v[180:181], off
	s_waitcnt vmcnt(11)
	ds_write_b128 v132, v[184:187] offset:36864
	v_lshl_add_u64 v[184:185], v[148:149], 0, v[130:131]
	v_add_co_u32_e32 v184, vcc, s43, v184
	s_nop 1
	v_addc_co_u32_e32 v185, vcc, 0, v185, vcc
	global_load_dwordx4 v[184:187], v[184:185], off offset:-4096
	s_waitcnt vmcnt(11)
	ds_write_b128 v132, v[188:191] offset:41472
	v_lshl_add_u64 v[188:189], v[148:149], 0, v[130:131]
	v_add_co_u32_e32 v188, vcc, s43, v188
	s_nop 1
	v_addc_co_u32_e32 v189, vcc, 0, v189, vcc
	global_load_dwordx4 v[188:191], v[188:189], off
	s_waitcnt vmcnt(11)
	ds_write_b128 v132, v[192:195] offset:46080
	v_lshl_add_u64 v[192:193], v[148:149], 0, v[130:131]
	v_add_co_u32_e32 v192, vcc, s44, v192
	s_nop 1
	v_addc_co_u32_e32 v193, vcc, 0, v193, vcc
	global_load_dwordx4 v[192:195], v[192:193], off offset:-4096
	s_waitcnt vmcnt(11)
	ds_write_b128 v132, v[196:199] offset:50688
	v_lshl_add_u64 v[196:197], v[148:149], 0, v[130:131]
	v_add_co_u32_e32 v196, vcc, s44, v196
	s_nop 1
	v_addc_co_u32_e32 v197, vcc, 0, v197, vcc
	global_load_dwordx4 v[196:199], v[196:197], off
	s_waitcnt lgkmcnt(0)
	s_barrier
	s_cbranch_scc1 .LBB0_2143
	s_setprio 1
	ds_read_b128 v[200:203], v133 offset:0
	ds_read_b128 v[212:215], v137 offset:18432
	ds_read_b128 v[216:219], v137 offset:23040
	ds_read_b128 v[224:227], v137 offset:27648
	ds_read_b128 v[228:231], v137 offset:32256
	ds_read_b128 v[208:211], v133 offset:4608
	s_waitcnt lgkmcnt(4)
	v_mfma_f32_32x32x16_bf16 v[114:129], v[200:203], v[212:215], v[114:129]
	ds_read_b128 v[204:207], v133 offset:32
	ds_read_b128 v[232:235], v137 offset:18464
	s_waitcnt lgkmcnt(5)
	v_mfma_f32_32x32x16_bf16 v[98:113], v[200:203], v[216:219], v[98:113]
	ds_read_b128 v[236:239], v137 offset:23072
	s_waitcnt lgkmcnt(5)
	v_mfma_f32_32x32x16_bf16 v[82:97], v[200:203], v[224:227], v[82:97]
	ds_read_b128 v[240:243], v137 offset:27680
	s_waitcnt lgkmcnt(5)
	v_mfma_f32_32x32x16_bf16 v[66:81], v[200:203], v[228:231], v[66:81]
	ds_read_b128 v[244:247], v137 offset:32288
	s_waitcnt lgkmcnt(5)
	v_mfma_f32_32x32x16_bf16 v[50:65], v[208:211], v[212:215], v[50:65]
	v_mfma_f32_32x32x16_bf16 v[34:49], v[208:211], v[216:219], v[34:49]
	v_mfma_f32_32x32x16_bf16 v[18:33], v[208:211], v[224:227], v[18:33]
	v_mfma_f32_32x32x16_bf16 v[2:17], v[208:211], v[228:231], v[2:17]
	ds_read_b128 v[208:211], v133 offset:4640
	s_waitcnt lgkmcnt(4)
	v_mfma_f32_32x32x16_bf16 v[114:129], v[204:207], v[232:235], v[114:129]
	ds_read_b128 v[200:203], v133 offset:64
	ds_read_b128 v[212:215], v137 offset:18496
	s_waitcnt lgkmcnt(5)
	v_mfma_f32_32x32x16_bf16 v[98:113], v[204:207], v[236:239], v[98:113]
	ds_read_b128 v[216:219], v137 offset:23104
	s_waitcnt lgkmcnt(5)
	v_mfma_f32_32x32x16_bf16 v[82:97], v[204:207], v[240:243], v[82:97]
	ds_read_b128 v[224:227], v137 offset:27712
	s_waitcnt lgkmcnt(5)
	v_mfma_f32_32x32x16_bf16 v[66:81], v[204:207], v[244:247], v[66:81]
	ds_read_b128 v[228:231], v137 offset:32320
	s_waitcnt lgkmcnt(5)
	v_mfma_f32_32x32x16_bf16 v[50:65], v[208:211], v[232:235], v[50:65]
	v_mfma_f32_32x32x16_bf16 v[34:49], v[208:211], v[236:239], v[34:49]
	v_mfma_f32_32x32x16_bf16 v[18:33], v[208:211], v[240:243], v[18:33]
	v_mfma_f32_32x32x16_bf16 v[2:17], v[208:211], v[244:247], v[2:17]
	ds_read_b128 v[208:211], v133 offset:4672
	s_waitcnt lgkmcnt(4)
	v_mfma_f32_32x32x16_bf16 v[114:129], v[200:203], v[212:215], v[114:129]
	ds_read_b128 v[204:207], v133 offset:96
	ds_read_b128 v[232:235], v137 offset:18528
	s_waitcnt lgkmcnt(5)
	v_mfma_f32_32x32x16_bf16 v[98:113], v[200:203], v[216:219], v[98:113]
	ds_read_b128 v[236:239], v137 offset:23136
	s_waitcnt lgkmcnt(5)
	v_mfma_f32_32x32x16_bf16 v[82:97], v[200:203], v[224:227], v[82:97]
	ds_read_b128 v[240:243], v137 offset:27744
	s_waitcnt lgkmcnt(5)
	v_mfma_f32_32x32x16_bf16 v[66:81], v[200:203], v[228:231], v[66:81]
	ds_read_b128 v[244:247], v137 offset:32352
	s_waitcnt lgkmcnt(5)
	v_mfma_f32_32x32x16_bf16 v[50:65], v[208:211], v[212:215], v[50:65]
	v_mfma_f32_32x32x16_bf16 v[34:49], v[208:211], v[216:219], v[34:49]
	v_mfma_f32_32x32x16_bf16 v[18:33], v[208:211], v[224:227], v[18:33]
	v_mfma_f32_32x32x16_bf16 v[2:17], v[208:211], v[228:231], v[2:17]
	ds_read_b128 v[208:211], v133 offset:4704
	s_waitcnt lgkmcnt(4)
	v_mfma_f32_32x32x16_bf16 v[114:129], v[204:207], v[232:235], v[114:129]
	s_waitcnt lgkmcnt(3)
	v_mfma_f32_32x32x16_bf16 v[98:113], v[204:207], v[236:239], v[98:113]
	s_waitcnt lgkmcnt(2)
	v_mfma_f32_32x32x16_bf16 v[82:97], v[204:207], v[240:243], v[82:97]
	s_waitcnt lgkmcnt(1)
	v_mfma_f32_32x32x16_bf16 v[66:81], v[204:207], v[244:247], v[66:81]
	s_waitcnt lgkmcnt(0)
	v_mfma_f32_32x32x16_bf16 v[50:65], v[208:211], v[232:235], v[50:65]
	v_mfma_f32_32x32x16_bf16 v[34:49], v[208:211], v[236:239], v[34:49]
	v_mfma_f32_32x32x16_bf16 v[18:33], v[208:211], v[240:243], v[18:33]
	v_mfma_f32_32x32x16_bf16 v[2:17], v[208:211], v[244:247], v[2:17]
	s_setprio 0
	v_lshl_add_u64 v[148:149], v[148:149], 0, s[4:5]
	v_lshl_add_u64 v[150:151], v[150:151], 0, s[10:11]
	s_barrier
;     ...
;   for (int kt = 0; kt < nk; ++kt) {
;     const int kn = (kt + 1 < nk) ? kt + 1 : kt;
;     GW_LOAD2(kn * 64, kn * bkstep)
;     __builtin_amdgcn_sched_barrier(0);
;     __builtin_amdgcn_s_setprio(1);
; #pragma unroll
;     for (int st = 0; st < 4; ++st) {
;       bf16x8 a0 = *(const bf16x8*)(Ab + st * 32);
;       bf16x8 a1 = *(const bf16x8*)(Ab + 32 * LSTR + st * 32);
;       bf16x8 b0 = *(const bf16x8*)(Bb + st * 32);
;       bf16x8 b1 = *(const bf16x8*)(Bb + 32 * LSTR + st * 32);
;       bf16x8 b2 = *(const bf16x8*)(Bb + 64 * LSTR + st * 32);
;       bf16x8 b3 = *(const bf16x8*)(Bb + 96 * LSTR + st * 32);
;       acc[0][0] = mfma32(a0, b0, acc[0][0]);
;       acc[0][1] = mfma32(a0, b1, acc[0][1]);
;       acc[0][2] = mfma32(a0, b2, acc[0][2]);
;       acc[0][3] = mfma32(a0, b3, acc[0][3]);
;       acc[1][0] = mfma32(a1, b0, acc[1][0]);
;       acc[1][1] = mfma32(a1, b1, acc[1][1]);
;       acc[1][2] = mfma32(a1, b2, acc[1][2]);
;       acc[1][3] = mfma32(a1, b3, acc[1][3]);
;     }
;     __builtin_amdgcn_s_setprio(0);
;     __builtin_amdgcn_sched_barrier(0);
;     __syncthreads();
;     GW_STORE()
;     __syncthreads();
;   }
; __device__ __forceinline__ void expert2_tile(const Params& P, int e, int mt, int ntw, char* smem) {
;     ...
;   float* cs = (float*)smem;
; #pragma unroll 1
;   for (int h = 0; h < 2; ++h) {
;     wide_acc_to_lds(acc, cs, h);
;     epi_plain(cs, WSP(u16, OFF_YE), DM, (size_t)e * EROWS + mt * 128, ntw * 256 + h * 128);
	s_waitcnt vmcnt(11)
	ds_write_b128 v132, v[152:155]
	s_waitcnt vmcnt(10)
	ds_write_b128 v132, v[156:159] offset:4608
	s_waitcnt vmcnt(9)
	ds_write_b128 v132, v[160:163] offset:9216
	s_waitcnt vmcnt(8)
	ds_write_b128 v132, v[164:167] offset:13824
	s_waitcnt vmcnt(7)
	ds_write_b128 v132, v[168:171] offset:18432
	s_waitcnt vmcnt(6)
	ds_write_b128 v132, v[172:175] offset:23040
	s_waitcnt vmcnt(5)
	ds_write_b128 v132, v[176:179] offset:27648
	s_waitcnt vmcnt(4)
	ds_write_b128 v132, v[180:183] offset:32256
	s_waitcnt vmcnt(3)
	ds_write_b128 v132, v[184:187] offset:36864
	s_waitcnt vmcnt(2)
	ds_write_b128 v132, v[188:191] offset:41472
	s_waitcnt vmcnt(1)
	ds_write_b128 v132, v[192:195] offset:46080
	s_waitcnt vmcnt(0)
	ds_write_b128 v132, v[196:199] offset:50688
	s_waitcnt lgkmcnt(0)
	s_barrier
	v_add_co_u32_e32 v156, vcc, 0x3e0000, v138
	s_nop 0
	s_nop 0
	s_nop 0
	v_addc_co_u32_e32 v157, vcc, 0, v139, vcc
	v_add_co_u32_e32 v160, vcc, 0x3e1000, v138
	s_mov_b32 s18, 0
	s_nop 0
	v_addc_co_u32_e32 v161, vcc, 0, v139, vcc
	v_add_co_u32_e32 v164, vcc, 0x3e2000, v138
	s_nop 0
	v_addc_co_u32_e32 v165, vcc, 0, v139, vcc
	v_add_co_u32_e32 v168, vcc, 0x3e3000, v138
	s_nop 1
	v_addc_co_u32_e32 v169, vcc, 0, v139, vcc
	v_add_co_u32_e32 v172, vcc, 0x3e4000, v138
	s_nop 0
	v_addc_co_u32_e32 v173, vcc, 0, v139, vcc
	v_add_co_u32_e32 v176, vcc, 0x3e5000, v138
	s_nop 1
	v_addc_co_u32_e32 v177, vcc, 0, v139, vcc
	v_add_co_u32_e32 v180, vcc, 0x3e6000, v138
	s_nop 0
	v_addc_co_u32_e32 v181, vcc, 0, v139, vcc
	v_add_co_u32_e32 v138, vcc, 0x3e7000, v138
	s_nop 1
	v_addc_co_u32_e32 v139, vcc, 0, v139, vcc
	s_nop 0
	s_setprio 1
	ds_read_b128 v[188:191], v133 offset:0
	ds_read_b128 v[200:203], v137 offset:18432
	ds_read_b128 v[204:207], v137 offset:23040
	ds_read_b128 v[208:211], v137 offset:27648
	ds_read_b128 v[212:215], v137 offset:32256
	ds_read_b128 v[196:199], v133 offset:4608
	s_waitcnt lgkmcnt(4)
	v_mfma_f32_32x32x16_bf16 v[114:129], v[188:191], v[200:203], v[114:129]
	ds_read_b128 v[192:195], v133 offset:32
	ds_read_b128 v[216:219], v137 offset:18464
	s_waitcnt lgkmcnt(5)
	v_mfma_f32_32x32x16_bf16 v[98:113], v[188:191], v[204:207], v[98:113]
	ds_read_b128 v[224:227], v137 offset:23072
	s_waitcnt lgkmcnt(5)
	v_mfma_f32_32x32x16_bf16 v[82:97], v[188:191], v[208:211], v[82:97]
	ds_read_b128 v[228:231], v137 offset:27680
	s_waitcnt lgkmcnt(5)
	v_mfma_f32_32x32x16_bf16 v[66:81], v[188:191], v[212:215], v[66:81]
	ds_read_b128 v[232:235], v137 offset:32288
	s_waitcnt lgkmcnt(5)
	v_mfma_f32_32x32x16_bf16 v[50:65], v[196:199], v[200:203], v[50:65]
	v_mfma_f32_32x32x16_bf16 v[34:49], v[196:199], v[204:207], v[34:49]
	v_mfma_f32_32x32x16_bf16 v[18:33], v[196:199], v[208:211], v[18:33]
	v_mfma_f32_32x32x16_bf16 v[2:17], v[196:199], v[212:215], v[2:17]
	ds_read_b128 v[196:199], v133 offset:4640
	s_waitcnt lgkmcnt(4)
	v_mfma_f32_32x32x16_bf16 v[114:129], v[192:195], v[216:219], v[114:129]
	ds_read_b128 v[188:191], v133 offset:64
	ds_read_b128 v[200:203], v137 offset:18496
	s_waitcnt lgkmcnt(5)
	v_mfma_f32_32x32x16_bf16 v[98:113], v[192:195], v[224:227], v[98:113]
	ds_read_b128 v[204:207], v137 offset:23104
	s_waitcnt lgkmcnt(5)
	v_mfma_f32_32x32x16_bf16 v[82:97], v[192:195], v[228:231], v[82:97]
	ds_read_b128 v[208:211], v137 offset:27712
	s_waitcnt lgkmcnt(5)
	v_mfma_f32_32x32x16_bf16 v[66:81], v[192:195], v[232:235], v[66:81]
	ds_read_b128 v[212:215], v137 offset:32320
	s_waitcnt lgkmcnt(5)
	v_mfma_f32_32x32x16_bf16 v[50:65], v[196:199], v[216:219], v[50:65]
	v_mfma_f32_32x32x16_bf16 v[34:49], v[196:199], v[224:227], v[34:49]
	v_mfma_f32_32x32x16_bf16 v[18:33], v[196:199], v[228:231], v[18:33]
	v_mfma_f32_32x32x16_bf16 v[2:17], v[196:199], v[232:235], v[2:17]
	ds_read_b128 v[196:199], v133 offset:4672
	s_waitcnt lgkmcnt(4)
	v_mfma_f32_32x32x16_bf16 v[114:129], v[188:191], v[200:203], v[114:129]
	ds_read_b128 v[192:195], v133 offset:96
	ds_read_b128 v[216:219], v137 offset:18528
	s_waitcnt lgkmcnt(5)
	v_mfma_f32_32x32x16_bf16 v[98:113], v[188:191], v[204:207], v[98:113]
	ds_read_b128 v[224:227], v137 offset:23136
	s_waitcnt lgkmcnt(5)
	v_mfma_f32_32x32x16_bf16 v[82:97], v[188:191], v[208:211], v[82:97]
	ds_read_b128 v[228:231], v137 offset:27744
	s_waitcnt lgkmcnt(5)
	v_mfma_f32_32x32x16_bf16 v[66:81], v[188:191], v[212:215], v[66:81]
	ds_read_b128 v[232:235], v137 offset:32352
	s_waitcnt lgkmcnt(5)
	v_mfma_f32_32x32x16_bf16 v[50:65], v[196:199], v[200:203], v[50:65]
	v_mfma_f32_32x32x16_bf16 v[34:49], v[196:199], v[204:207], v[34:49]
	v_mfma_f32_32x32x16_bf16 v[18:33], v[196:199], v[208:211], v[18:33]
	v_mfma_f32_32x32x16_bf16 v[2:17], v[196:199], v[212:215], v[2:17]
	ds_read_b128 v[196:199], v133 offset:4704
	s_waitcnt lgkmcnt(4)
	v_mfma_f32_32x32x16_bf16 v[114:129], v[192:195], v[216:219], v[114:129]
	s_waitcnt lgkmcnt(3)
	v_mfma_f32_32x32x16_bf16 v[98:113], v[192:195], v[224:227], v[98:113]
	s_waitcnt lgkmcnt(2)
	v_mfma_f32_32x32x16_bf16 v[82:97], v[192:195], v[228:231], v[82:97]
	s_waitcnt lgkmcnt(1)
	v_mfma_f32_32x32x16_bf16 v[66:81], v[192:195], v[232:235], v[66:81]
	s_waitcnt lgkmcnt(0)
	v_mfma_f32_32x32x16_bf16 v[50:65], v[196:199], v[216:219], v[50:65]
	v_mfma_f32_32x32x16_bf16 v[34:49], v[196:199], v[224:227], v[34:49]
	v_mfma_f32_32x32x16_bf16 v[18:33], v[196:199], v[228:231], v[18:33]
	v_mfma_f32_32x32x16_bf16 v[2:17], v[196:199], v[232:235], v[2:17]
	s_setprio 0
	s_lshl_b32 s19, s14, 8
	s_mov_b64 s[14:15], -1
	s_barrier
	s_waitcnt lgkmcnt(0)
	s_branch .LBB0_2146
